# 1/sqrtf expansions in P1/P3/P4 epilogues and P3 K-split rescale replaced by v_rsq_f32 (f32, 1ulp), plus previous ssq-load batching
# baseline (speedup 1.0000x reference)
; __device__ __forceinline__ float ss_get(const ss_t* p) { const ss_t v = *p; return (float)(unsigned)(v >> 32) + (float)(unsigned)v * 2.3283064365386963e-10f; }
; __device__ __forceinline__ unsigned pkbf(float lo, float hi) { typedef float f2_t __attribute__((ext_vector_type(2))); typedef __bf16 b2_t __attribute__((ext_vector_type(2))); f2_t v = {lo, hi}; b2_t b = __builtin_convertvector(v, b2_t); return __builtin_bit_cast(unsigned, b); }
; __device__ __forceinline__ f32x2 gelu_pk(f32x2 v) {
;     const f32x2 av = __builtin_elementwise_abs(v), d = av * 0.2316418882f + 1.0f;
;     f32x2 t; t.x = __builtin_amdgcn_rcpf(d.x); t.y = __builtin_amdgcn_rcpf(d.y);
;     f32x2 q = t * 0.5307027145f + (-0.7265760135f); q = q * t + 0.7107068705f; q = q * t + (-0.142248368f); q = q * t + 0.127414796f; q = q * t;
;     const f32x2 s = (v * v) * (-0.72134752044f);
;     f32x2 e; e.x = __builtin_amdgcn_exp2f(s.x); e.y = __builtin_amdgcn_exp2f(s.y);
;     const f32x2 m = v * (q * e), r = v - m;
;     f32x2 o; o.x = v.x < 0.f ? m.x : r.x; o.y = v.y < 0.f ? m.y : r.y; return o;
;     __device__ __forceinline__ void operator()(const f32x4 (&acc)[2][2][4][2], const Unit& u, int wr, int wc, int fr, int fq) const {
;     ...
;             for (int m = 0; m < 4; ++m) { const int row = row0 + ai * HALF + m * 16; bf16_t* rowp = O + (size_t)row * ldc + col0;
;                 const float rs = 1.0f / sqrtf(ss_get(ssq + row) * (1.0f / 2048.f) + 1e-6f);
; #pragma unroll
;                 for (int bj = 0; bj < 2; ++bj) { f32x4 v0 = acc[ai][bj][m][0] * rs, v1 = acc[ai][bj][m][1] * rs;
;                     if (act) { f32x2 a = gelu_pk((f32x2){v0[0], v0[1]}), b = gelu_pk((f32x2){v0[2], v0[3]}), c = gelu_pk((f32x2){v1[0], v1[1]}), d = gelu_pk((f32x2){v1[2], v1[3]});
;                         v0 = (f32x4){a.x, a.y, b.x, b.y}; v1 = (f32x4){c.x, c.y, d.x, d.y}; }
;                     u32x4 w; w.x = pkbf(v0[0], v0[1]); w.y = pkbf(v0[2], v0[3]); w.z = pkbf(v1[0], v1[1]); w.w = pkbf(v1[2], v1[3]);
.LBB0_177:
	v_mov_b32_e32 v142, v152
	s_cmp_lt_i32 s53, 8
	v_ashrrev_i32_e32 v143, 31, v142
	v_lshl_add_u64 v[144:145], v[142:143], 3, s[4:5]
	global_load_dwordx2 v[146:147], v[144:145], off
	global_load_dwordx2 v[172:173], v[144:145], off offset:128
	global_load_dwordx2 v[174:175], v[144:145], off offset:256
	global_load_dwordx2 v[176:177], v[144:145], off offset:384
	global_load_dwordx2 v[178:179], v[144:145], off offset:1024
	global_load_dwordx2 v[180:181], v[144:145], off offset:1152
	global_load_dwordx2 v[182:183], v[144:145], off offset:1280
	global_load_dwordx2 v[184:185], v[144:145], off offset:1408
	s_flbit_i32_b32 s2, 0
	v_mov_b32_e32 v149, v2
	s_cselect_b64 s[40:41], -1, 0
	s_min_u32 s15, s2, 32
	s_sub_i32 s52, 32, s15
	s_cmp_gt_i32 s53, 7
	s_waitcnt vmcnt(0)
	v_mov_b32_e32 v148, v147
	v_lshlrev_b64 v[148:149], s15, v[148:149]
	v_min_u32_e32 v143, 1, v148
	v_or_b32_e32 v143, v149, v143
	v_cvt_f32_u32_e32 v143, v143
	v_cvt_f32_u32_e32 v146, v146
	v_ldexp_f32 v143, v143, s52
	v_fmac_f32_e32 v143, 0x2f800000, v146
	v_fmamk_f32 v143, v143, 0x3a000000, v205
	v_rsq_f32_e32 v146, v143
	s_nop 0
	s_nop 1
	s_nop 0
	s_nop 1
	s_nop 1
	s_nop 1
	v_pk_mul_f32 v[130:131], v[130:131], v[146:147] op_sel_hi:[1,0]
	v_pk_mul_f32 v[128:129], v[128:129], v[146:147] op_sel_hi:[1,0]
	v_pk_mul_f32 v[148:149], v[126:127], v[146:147] op_sel_hi:[1,0]
	v_pk_mul_f32 v[150:151], v[124:125], v[146:147] op_sel_hi:[1,0]
	s_cbranch_scc1 .LBB0_179
	v_and_b32_e32 v125, 0x7fffffff, v129
	v_and_b32_e32 v124, 0x7fffffff, v128
	v_pk_fma_f32 v[124:125], v[124:125], s[90:91], 1.0 op_sel_hi:[1,0,0]
	s_mov_b32 s2, 0xbf3a00e3
	v_rcp_f32_e32 v126, v124
	v_rcp_f32_e32 v127, v125
	v_mov_b64_e32 v[124:125], s[2:3]
	v_pk_mul_f32 v[158:159], v[128:129], v[128:129]
	s_mov_b32 s2, 0xbf38aa3b
	v_pk_fma_f32 v[156:157], v[126:127], s[92:93], v[124:125] op_sel_hi:[1,0,0]
	v_pk_mul_f32 v[158:159], v[158:159], s[2:3] op_sel_hi:[1,0]
	v_pk_fma_f32 v[156:157], v[126:127], v[156:157], s[94:95] op_sel_hi:[1,1,0]
	v_exp_f32_e32 v158, v158
	v_exp_f32_e32 v159, v159
	v_pk_fma_f32 v[156:157], v[126:127], v[156:157], s[96:97] op_sel_hi:[1,1,0]
	v_cmp_gt_f32_e32 vcc, 0, v128
	v_pk_fma_f32 v[156:157], v[126:127], v[156:157], s[30:31] op_sel_hi:[1,1,0]
	s_nop 0
	v_pk_mul_f32 v[126:127], v[126:127], v[156:157]
	v_pk_mul_f32 v[156:157], v[130:131], v[130:131]
	v_pk_mul_f32 v[126:127], v[158:159], v[126:127]
	v_pk_mul_f32 v[156:157], v[156:157], s[2:3] op_sel_hi:[1,0]
	v_pk_mul_f32 v[158:159], v[128:129], v[126:127]
	v_pk_fma_f32 v[126:127], v[128:129], v[126:127], v[128:129] neg_lo:[1,0,0] neg_hi:[1,0,0]
	v_exp_f32_e32 v156, v156
	v_cndmask_b32_e32 v128, v126, v158, vcc
	v_cmp_gt_f32_e32 vcc, 0, v129
	v_and_b32_e32 v126, 0x7fffffff, v130
	v_exp_f32_e32 v157, v157
	v_cndmask_b32_e32 v129, v127, v159, vcc
	v_and_b32_e32 v127, 0x7fffffff, v131
	v_pk_fma_f32 v[126:127], v[126:127], s[90:91], 1.0 op_sel_hi:[1,0,0]
	v_cmp_gt_f32_e32 vcc, 0, v130
	v_rcp_f32_e32 v126, v126
	v_rcp_f32_e32 v127, v127
	s_nop 0
	v_pk_fma_f32 v[158:159], v[126:127], s[92:93], v[124:125] op_sel_hi:[1,0,0]
	s_nop 0
	v_pk_fma_f32 v[158:159], v[126:127], v[158:159], s[94:95] op_sel_hi:[1,1,0]
	s_nop 0
	v_pk_fma_f32 v[158:159], v[126:127], v[158:159], s[96:97] op_sel_hi:[1,1,0]
	s_nop 0
	v_pk_fma_f32 v[158:159], v[126:127], v[158:159], s[30:31] op_sel_hi:[1,1,0]
	s_nop 0
	v_pk_mul_f32 v[126:127], v[126:127], v[158:159]
	v_pk_mul_f32 v[158:159], v[150:151], v[150:151]
	v_pk_mul_f32 v[126:127], v[156:157], v[126:127]
	v_pk_mul_f32 v[158:159], v[158:159], s[2:3] op_sel_hi:[1,0]
	v_pk_mul_f32 v[156:157], v[130:131], v[126:127]
	v_pk_fma_f32 v[126:127], v[130:131], v[126:127], v[130:131] neg_lo:[1,0,0] neg_hi:[1,0,0]
	v_exp_f32_e32 v158, v158
	v_cndmask_b32_e32 v130, v126, v156, vcc
	v_cmp_gt_f32_e32 vcc, 0, v131
	v_and_b32_e32 v126, 0x7fffffff, v150
	v_exp_f32_e32 v159, v159
	v_cndmask_b32_e32 v131, v127, v157, vcc
	v_and_b32_e32 v127, 0x7fffffff, v151
	v_pk_fma_f32 v[126:127], v[126:127], s[90:91], 1.0 op_sel_hi:[1,0,0]
	v_cmp_gt_f32_e32 vcc, 0, v150
	v_rcp_f32_e32 v126, v126
	v_rcp_f32_e32 v127, v127
	s_nop 0
	v_pk_fma_f32 v[156:157], v[126:127], s[92:93], v[124:125] op_sel_hi:[1,0,0]
	s_nop 0
	v_pk_fma_f32 v[156:157], v[126:127], v[156:157], s[94:95] op_sel_hi:[1,1,0]
	s_nop 0
	v_pk_fma_f32 v[156:157], v[126:127], v[156:157], s[96:97] op_sel_hi:[1,1,0]
	s_nop 0
	v_pk_fma_f32 v[156:157], v[126:127], v[156:157], s[30:31] op_sel_hi:[1,1,0]
	s_nop 0
	v_pk_mul_f32 v[126:127], v[126:127], v[156:157]
	v_pk_mul_f32 v[156:157], v[148:149], v[148:149]
	v_pk_mul_f32 v[126:127], v[158:159], v[126:127]
	s_nop 0
	v_pk_mul_f32 v[158:159], v[150:151], v[126:127]
	v_pk_fma_f32 v[126:127], v[150:151], v[126:127], v[150:151] neg_lo:[1,0,0] neg_hi:[1,0,0]
	s_nop 0
	v_cndmask_b32_e32 v150, v126, v158, vcc
	v_cmp_gt_f32_e32 vcc, 0, v151
	v_and_b32_e32 v126, 0x7fffffff, v148
	s_nop 0
	v_cndmask_b32_e32 v151, v127, v159, vcc
	v_and_b32_e32 v127, 0x7fffffff, v149
	v_pk_fma_f32 v[126:127], v[126:127], s[90:91], 1.0 op_sel_hi:[1,0,0]
	v_cmp_gt_f32_e32 vcc, 0, v148
	v_rcp_f32_e32 v126, v126
	v_rcp_f32_e32 v127, v127
	s_nop 0
	v_pk_fma_f32 v[124:125], v[126:127], s[92:93], v[124:125] op_sel_hi:[1,0,0]
	s_nop 0
	v_pk_fma_f32 v[124:125], v[126:127], v[124:125], s[94:95] op_sel_hi:[1,1,0]
	s_nop 0
	v_pk_fma_f32 v[124:125], v[126:127], v[124:125], s[96:97] op_sel_hi:[1,1,0]
	s_nop 0
	v_pk_fma_f32 v[124:125], v[126:127], v[124:125], s[30:31] op_sel_hi:[1,1,0]
	s_nop 0
	v_pk_mul_f32 v[124:125], v[126:127], v[124:125]
	v_pk_mul_f32 v[126:127], v[156:157], s[2:3] op_sel_hi:[1,0]
	s_nop 0
	v_exp_f32_e32 v126, v126
	v_exp_f32_e32 v127, v127
	s_nop 0
	v_pk_mul_f32 v[124:125], v[126:127], v[124:125]
	s_nop 0
	v_pk_mul_f32 v[126:127], v[148:149], v[124:125]
	v_pk_fma_f32 v[124:125], v[148:149], v[124:125], v[148:149] neg_lo:[1,0,0] neg_hi:[1,0,0]
	s_nop 0
	v_cndmask_b32_e32 v148, v124, v126, vcc
	v_cmp_gt_f32_e32 vcc, 0, v149
	s_nop 1
	v_cndmask_b32_e32 v149, v125, v127, vcc

; __device__ __forceinline__ float ss_get(const ss_t* p) { const ss_t v = *p; return (float)(unsigned)(v >> 32) + (float)(unsigned)v * 2.3283064365386963e-10f; }
; __device__ __forceinline__ unsigned pkbf(float lo, float hi) { typedef float f2_t __attribute__((ext_vector_type(2))); typedef __bf16 b2_t __attribute__((ext_vector_type(2))); f2_t v = {lo, hi}; b2_t b = __builtin_convertvector(v, b2_t); return __builtin_bit_cast(unsigned, b); }
; __device__ __forceinline__ f32x2 gelu_pk(f32x2 v) {
;     const f32x2 av = __builtin_elementwise_abs(v), d = av * 0.2316418882f + 1.0f;
;     f32x2 t; t.x = __builtin_amdgcn_rcpf(d.x); t.y = __builtin_amdgcn_rcpf(d.y);
;     f32x2 q = t * 0.5307027145f + (-0.7265760135f); q = q * t + 0.7107068705f; q = q * t + (-0.142248368f); q = q * t + 0.127414796f; q = q * t;
;     const f32x2 s = (v * v) * (-0.72134752044f);
;     f32x2 e; e.x = __builtin_amdgcn_exp2f(s.x); e.y = __builtin_amdgcn_exp2f(s.y);
;     const f32x2 m = v * (q * e), r = v - m;
;     f32x2 o; o.x = v.x < 0.f ? m.x : r.x; o.y = v.y < 0.f ? m.y : r.y; return o;
;     __device__ __forceinline__ void operator()(const f32x4 (&acc)[2][2][4][2], const Unit& u, int wr, int wc, int fr, int fq) const {
;     ...
;             for (int m = 0; m < 4; ++m) { const int row = row0 + ai * HALF + m * 16; bf16_t* rowp = O + (size_t)row * ldc + col0;
;                 const float rs = 1.0f / sqrtf(ss_get(ssq + row) * (1.0f / 2048.f) + 1e-6f);
; #pragma unroll
;                 for (int bj = 0; bj < 2; ++bj) { f32x4 v0 = acc[ai][bj][m][0] * rs, v1 = acc[ai][bj][m][1] * rs;
;                     if (act) { f32x2 a = gelu_pk((f32x2){v0[0], v0[1]}), b = gelu_pk((f32x2){v0[2], v0[3]}), c = gelu_pk((f32x2){v1[0], v1[1]}), d = gelu_pk((f32x2){v1[2], v1[3]});
;                         v0 = (f32x4){a.x, a.y, b.x, b.y}; v1 = (f32x4){c.x, c.y, d.x, d.y}; }
;                     u32x4 w; w.x = pkbf(v0[0], v0[1]); w.y = pkbf(v0[2], v0[3]); w.z = pkbf(v1[0], v1[1]); w.w = pkbf(v1[2], v1[3]);
.LBB0_181:
	v_cvt_pk_bf16_f32 v120, v120, v121
	v_cvt_pk_bf16_f32 v121, v122, v123
	v_cvt_pk_bf16_f32 v122, v116, v117
	v_cvt_pk_bf16_f32 v123, v118, v119
	global_store_dwordx4 v[126:127], v[120:123], off offset:256
	s_nop 1
	v_mov_b32_e32 v116, v172
	v_mov_b32_e32 v117, v173
	v_mov_b32_e32 v119, v2
	v_mov_b32_e32 v118, v117
	v_lshlrev_b64 v[118:119], s15, v[118:119]
	v_min_u32_e32 v117, 1, v118
	v_or_b32_e32 v117, v119, v117
	v_cvt_f32_u32_e32 v117, v117
	v_cvt_f32_u32_e32 v116, v116
	v_ldexp_f32 v117, v117, s52
	v_fmac_f32_e32 v117, 0x2f800000, v116
	v_fmamk_f32 v116, v117, 0x3a000000, v205
	v_rsq_f32_e32 v116, v116
	s_nop 0
	s_nop 1
	s_nop 0
	s_nop 1
	s_nop 1
	s_nop 1
	s_and_b64 vcc, exec, s[36:37]
	v_pk_mul_f32 v[114:115], v[114:115], v[116:117] op_sel_hi:[1,0]
	v_pk_mul_f32 v[118:119], v[112:113], v[116:117] op_sel_hi:[1,0]
	v_pk_mul_f32 v[110:111], v[110:111], v[116:117] op_sel_hi:[1,0]
	v_pk_mul_f32 v[112:113], v[108:109], v[116:117] op_sel_hi:[1,0]
	s_cbranch_vccnz .LBB0_183
	v_and_b32_e32 v109, 0x7fffffff, v119
	v_and_b32_e32 v108, 0x7fffffff, v118
	v_pk_fma_f32 v[108:109], v[108:109], s[90:91], 1.0 op_sel_hi:[1,0,0]
	s_mov_b32 s2, 0xbf3a00e3
	v_rcp_f32_e32 v120, v108
	v_rcp_f32_e32 v121, v109
	v_mov_b64_e32 v[108:109], s[2:3]
	v_pk_mul_f32 v[126:127], v[118:119], v[118:119]
	s_mov_b32 s2, 0xbf38aa3b
	v_pk_fma_f32 v[122:123], v[120:121], s[92:93], v[108:109] op_sel_hi:[1,0,0]
	v_pk_mul_f32 v[126:127], v[126:127], s[2:3] op_sel_hi:[1,0]
	v_pk_fma_f32 v[122:123], v[120:121], v[122:123], s[94:95] op_sel_hi:[1,1,0]
	v_exp_f32_e32 v126, v126
	v_exp_f32_e32 v127, v127
	v_pk_fma_f32 v[122:123], v[120:121], v[122:123], s[96:97] op_sel_hi:[1,1,0]
	v_cmp_gt_f32_e32 vcc, 0, v118
	v_pk_fma_f32 v[122:123], v[120:121], v[122:123], s[30:31] op_sel_hi:[1,1,0]
	s_nop 0
	v_pk_mul_f32 v[120:121], v[120:121], v[122:123]
	v_pk_mul_f32 v[122:123], v[114:115], v[114:115]
	v_pk_mul_f32 v[120:121], v[126:127], v[120:121]
	v_pk_mul_f32 v[122:123], v[122:123], s[2:3] op_sel_hi:[1,0]
	v_pk_mul_f32 v[126:127], v[118:119], v[120:121]
	v_pk_fma_f32 v[120:121], v[118:119], v[120:121], v[118:119] neg_lo:[1,0,0] neg_hi:[1,0,0]
	v_exp_f32_e32 v122, v122
	v_cndmask_b32_e32 v118, v120, v126, vcc
	v_cmp_gt_f32_e32 vcc, 0, v119
	v_and_b32_e32 v120, 0x7fffffff, v114
	v_exp_f32_e32 v123, v123
	v_cndmask_b32_e32 v119, v121, v127, vcc
	v_and_b32_e32 v121, 0x7fffffff, v115
	v_pk_fma_f32 v[120:121], v[120:121], s[90:91], 1.0 op_sel_hi:[1,0,0]
	v_cmp_gt_f32_e32 vcc, 0, v114
	v_rcp_f32_e32 v120, v120
	v_rcp_f32_e32 v121, v121
	s_nop 0
	v_pk_fma_f32 v[126:127], v[120:121], s[92:93], v[108:109] op_sel_hi:[1,0,0]
	s_nop 0
	v_pk_fma_f32 v[126:127], v[120:121], v[126:127], s[94:95] op_sel_hi:[1,1,0]
	s_nop 0
	v_pk_fma_f32 v[126:127], v[120:121], v[126:127], s[96:97] op_sel_hi:[1,1,0]
	s_nop 0
	v_pk_fma_f32 v[126:127], v[120:121], v[126:127], s[30:31] op_sel_hi:[1,1,0]
	s_nop 0
	v_pk_mul_f32 v[120:121], v[120:121], v[126:127]
	v_pk_mul_f32 v[126:127], v[112:113], v[112:113]
	v_pk_mul_f32 v[120:121], v[122:123], v[120:121]
	v_pk_mul_f32 v[126:127], v[126:127], s[2:3] op_sel_hi:[1,0]
	v_pk_mul_f32 v[122:123], v[114:115], v[120:121]
	v_pk_fma_f32 v[120:121], v[114:115], v[120:121], v[114:115] neg_lo:[1,0,0] neg_hi:[1,0,0]
	v_exp_f32_e32 v126, v126
	v_cndmask_b32_e32 v114, v120, v122, vcc
	v_cmp_gt_f32_e32 vcc, 0, v115
	v_and_b32_e32 v120, 0x7fffffff, v112
	v_exp_f32_e32 v127, v127
	v_cndmask_b32_e32 v115, v121, v123, vcc
	v_and_b32_e32 v121, 0x7fffffff, v113
	v_pk_fma_f32 v[120:121], v[120:121], s[90:91], 1.0 op_sel_hi:[1,0,0]
	v_cmp_gt_f32_e32 vcc, 0, v112
	v_rcp_f32_e32 v120, v120
	v_rcp_f32_e32 v121, v121
	s_nop 0
	v_pk_fma_f32 v[122:123], v[120:121], s[92:93], v[108:109] op_sel_hi:[1,0,0]
	s_nop 0
	v_pk_fma_f32 v[122:123], v[120:121], v[122:123], s[94:95] op_sel_hi:[1,1,0]
	s_nop 0
	v_pk_fma_f32 v[122:123], v[120:121], v[122:123], s[96:97] op_sel_hi:[1,1,0]
	s_nop 0
	v_pk_fma_f32 v[122:123], v[120:121], v[122:123], s[30:31] op_sel_hi:[1,1,0]
	s_nop 0
	v_pk_mul_f32 v[120:121], v[120:121], v[122:123]
	v_pk_mul_f32 v[122:123], v[110:111], v[110:111]
	v_pk_mul_f32 v[120:121], v[126:127], v[120:121]
	s_nop 0
	v_pk_mul_f32 v[126:127], v[112:113], v[120:121]
	v_pk_fma_f32 v[120:121], v[112:113], v[120:121], v[112:113] neg_lo:[1,0,0] neg_hi:[1,0,0]
	s_nop 0
	v_cndmask_b32_e32 v112, v120, v126, vcc
	v_cmp_gt_f32_e32 vcc, 0, v113
	v_and_b32_e32 v120, 0x7fffffff, v110
	s_nop 0
	v_cndmask_b32_e32 v113, v121, v127, vcc
	v_and_b32_e32 v121, 0x7fffffff, v111
	v_pk_fma_f32 v[120:121], v[120:121], s[90:91], 1.0 op_sel_hi:[1,0,0]
	v_cmp_gt_f32_e32 vcc, 0, v110
	v_rcp_f32_e32 v120, v120
	v_rcp_f32_e32 v121, v121
	s_nop 0
	v_pk_fma_f32 v[108:109], v[120:121], s[92:93], v[108:109] op_sel_hi:[1,0,0]
	s_nop 0
	v_pk_fma_f32 v[108:109], v[120:121], v[108:109], s[94:95] op_sel_hi:[1,1,0]
	s_nop 0
	v_pk_fma_f32 v[108:109], v[120:121], v[108:109], s[96:97] op_sel_hi:[1,1,0]
	s_nop 0
	v_pk_fma_f32 v[108:109], v[120:121], v[108:109], s[30:31] op_sel_hi:[1,1,0]
	s_nop 0
	v_pk_mul_f32 v[108:109], v[120:121], v[108:109]
	v_pk_mul_f32 v[120:121], v[122:123], s[2:3] op_sel_hi:[1,0]
	s_nop 0
	v_exp_f32_e32 v120, v120
	v_exp_f32_e32 v121, v121
	s_nop 0
	v_pk_mul_f32 v[108:109], v[120:121], v[108:109]
	s_nop 0
	v_pk_mul_f32 v[120:121], v[110:111], v[108:109]
	v_pk_fma_f32 v[108:109], v[110:111], v[108:109], v[110:111] neg_lo:[1,0,0] neg_hi:[1,0,0]
	s_nop 0
	v_cndmask_b32_e32 v110, v108, v120, vcc
	v_cmp_gt_f32_e32 vcc, 0, v111
	s_nop 1
	v_cndmask_b32_e32 v111, v109, v121, vcc

; __device__ __forceinline__ float ss_get(const ss_t* p) { const ss_t v = *p; return (float)(unsigned)(v >> 32) + (float)(unsigned)v * 2.3283064365386963e-10f; }
; __device__ __forceinline__ unsigned pkbf(float lo, float hi) { typedef float f2_t __attribute__((ext_vector_type(2))); typedef __bf16 b2_t __attribute__((ext_vector_type(2))); f2_t v = {lo, hi}; b2_t b = __builtin_convertvector(v, b2_t); return __builtin_bit_cast(unsigned, b); }
; __device__ __forceinline__ f32x2 gelu_pk(f32x2 v) {
;     const f32x2 av = __builtin_elementwise_abs(v), d = av * 0.2316418882f + 1.0f;
;     f32x2 t; t.x = __builtin_amdgcn_rcpf(d.x); t.y = __builtin_amdgcn_rcpf(d.y);
;     f32x2 q = t * 0.5307027145f + (-0.7265760135f); q = q * t + 0.7107068705f; q = q * t + (-0.142248368f); q = q * t + 0.127414796f; q = q * t;
;     const f32x2 s = (v * v) * (-0.72134752044f);
;     f32x2 e; e.x = __builtin_amdgcn_exp2f(s.x); e.y = __builtin_amdgcn_exp2f(s.y);
;     const f32x2 m = v * (q * e), r = v - m;
;     f32x2 o; o.x = v.x < 0.f ? m.x : r.x; o.y = v.y < 0.f ? m.y : r.y; return o;
;     __device__ __forceinline__ void operator()(const f32x4 (&acc)[2][2][4][2], const Unit& u, int wr, int wc, int fr, int fq) const {
;     ...
;             for (int m = 0; m < 4; ++m) { const int row = row0 + ai * HALF + m * 16; bf16_t* rowp = O + (size_t)row * ldc + col0;
;                 const float rs = 1.0f / sqrtf(ss_get(ssq + row) * (1.0f / 2048.f) + 1e-6f);
; #pragma unroll
;                 for (int bj = 0; bj < 2; ++bj) { f32x4 v0 = acc[ai][bj][m][0] * rs, v1 = acc[ai][bj][m][1] * rs;
;                     if (act) { f32x2 a = gelu_pk((f32x2){v0[0], v0[1]}), b = gelu_pk((f32x2){v0[2], v0[3]}), c = gelu_pk((f32x2){v1[0], v1[1]}), d = gelu_pk((f32x2){v1[2], v1[3]});
;                         v0 = (f32x4){a.x, a.y, b.x, b.y}; v1 = (f32x4){c.x, c.y, d.x, d.y}; }
;                     u32x4 w; w.x = pkbf(v0[0], v0[1]); w.y = pkbf(v0[2], v0[3]); w.z = pkbf(v1[0], v1[1]); w.w = pkbf(v1[2], v1[3]);
.LBB0_185:
	v_cvt_pk_bf16_f32 v104, v104, v105
	v_cvt_pk_bf16_f32 v105, v106, v107
	v_cvt_pk_bf16_f32 v106, v100, v101
	v_cvt_pk_bf16_f32 v107, v102, v103
	global_store_dwordx4 v[108:109], v[104:107], off offset:256
	s_nop 1
	v_mov_b32_e32 v100, v174
	v_mov_b32_e32 v101, v175
	v_mov_b32_e32 v103, v2
	v_mov_b32_e32 v102, v101
	v_lshlrev_b64 v[102:103], s15, v[102:103]
	v_min_u32_e32 v101, 1, v102
	v_or_b32_e32 v101, v103, v101
	v_cvt_f32_u32_e32 v101, v101
	v_cvt_f32_u32_e32 v100, v100
	v_ldexp_f32 v101, v101, s52
	v_fmac_f32_e32 v101, 0x2f800000, v100
	v_fmamk_f32 v100, v101, 0x3a000000, v205
	v_rsq_f32_e32 v100, v100
	s_nop 0
	s_nop 1
	s_nop 0
	s_nop 1
	s_nop 1
	s_nop 1
	s_and_b64 vcc, exec, s[36:37]
	v_pk_mul_f32 v[98:99], v[98:99], v[100:101] op_sel_hi:[1,0]
	v_pk_mul_f32 v[102:103], v[96:97], v[100:101] op_sel_hi:[1,0]
	v_pk_mul_f32 v[94:95], v[94:95], v[100:101] op_sel_hi:[1,0]
	v_pk_mul_f32 v[96:97], v[92:93], v[100:101] op_sel_hi:[1,0]
	s_cbranch_vccnz .LBB0_187
	v_and_b32_e32 v93, 0x7fffffff, v103
	v_and_b32_e32 v92, 0x7fffffff, v102
	v_pk_fma_f32 v[92:93], v[92:93], s[90:91], 1.0 op_sel_hi:[1,0,0]
	s_mov_b32 s2, 0xbf3a00e3
	v_rcp_f32_e32 v104, v92
	v_rcp_f32_e32 v105, v93
	v_mov_b64_e32 v[92:93], s[2:3]
	v_pk_mul_f32 v[108:109], v[102:103], v[102:103]
	s_mov_b32 s2, 0xbf38aa3b
	v_pk_fma_f32 v[106:107], v[104:105], s[92:93], v[92:93] op_sel_hi:[1,0,0]
	v_pk_mul_f32 v[108:109], v[108:109], s[2:3] op_sel_hi:[1,0]
	v_pk_fma_f32 v[106:107], v[104:105], v[106:107], s[94:95] op_sel_hi:[1,1,0]
	v_exp_f32_e32 v108, v108
	v_exp_f32_e32 v109, v109
	v_pk_fma_f32 v[106:107], v[104:105], v[106:107], s[96:97] op_sel_hi:[1,1,0]
	v_cmp_gt_f32_e32 vcc, 0, v102
	v_pk_fma_f32 v[106:107], v[104:105], v[106:107], s[30:31] op_sel_hi:[1,1,0]
	s_nop 0
	v_pk_mul_f32 v[104:105], v[104:105], v[106:107]
	v_pk_mul_f32 v[106:107], v[98:99], v[98:99]
	v_pk_mul_f32 v[104:105], v[108:109], v[104:105]
	v_pk_mul_f32 v[106:107], v[106:107], s[2:3] op_sel_hi:[1,0]
	v_pk_mul_f32 v[108:109], v[102:103], v[104:105]
	v_pk_fma_f32 v[104:105], v[102:103], v[104:105], v[102:103] neg_lo:[1,0,0] neg_hi:[1,0,0]
	v_exp_f32_e32 v106, v106
	v_cndmask_b32_e32 v102, v104, v108, vcc
	v_cmp_gt_f32_e32 vcc, 0, v103
	v_and_b32_e32 v104, 0x7fffffff, v98
	v_exp_f32_e32 v107, v107
	v_cndmask_b32_e32 v103, v105, v109, vcc
	v_and_b32_e32 v105, 0x7fffffff, v99
	v_pk_fma_f32 v[104:105], v[104:105], s[90:91], 1.0 op_sel_hi:[1,0,0]
	v_cmp_gt_f32_e32 vcc, 0, v98
	v_rcp_f32_e32 v104, v104
	v_rcp_f32_e32 v105, v105
	s_nop 0
	v_pk_fma_f32 v[108:109], v[104:105], s[92:93], v[92:93] op_sel_hi:[1,0,0]
	s_nop 0
	v_pk_fma_f32 v[108:109], v[104:105], v[108:109], s[94:95] op_sel_hi:[1,1,0]
	s_nop 0
	v_pk_fma_f32 v[108:109], v[104:105], v[108:109], s[96:97] op_sel_hi:[1,1,0]
	s_nop 0
	v_pk_fma_f32 v[108:109], v[104:105], v[108:109], s[30:31] op_sel_hi:[1,1,0]
	s_nop 0
	v_pk_mul_f32 v[104:105], v[104:105], v[108:109]
	v_pk_mul_f32 v[108:109], v[96:97], v[96:97]
	v_pk_mul_f32 v[104:105], v[106:107], v[104:105]
	v_pk_mul_f32 v[108:109], v[108:109], s[2:3] op_sel_hi:[1,0]
	v_pk_mul_f32 v[106:107], v[98:99], v[104:105]
	v_pk_fma_f32 v[104:105], v[98:99], v[104:105], v[98:99] neg_lo:[1,0,0] neg_hi:[1,0,0]
	v_exp_f32_e32 v108, v108
	v_cndmask_b32_e32 v98, v104, v106, vcc
	v_cmp_gt_f32_e32 vcc, 0, v99
	v_and_b32_e32 v104, 0x7fffffff, v96
	v_exp_f32_e32 v109, v109
	v_cndmask_b32_e32 v99, v105, v107, vcc
	v_and_b32_e32 v105, 0x7fffffff, v97
	v_pk_fma_f32 v[104:105], v[104:105], s[90:91], 1.0 op_sel_hi:[1,0,0]
	v_cmp_gt_f32_e32 vcc, 0, v96
	v_rcp_f32_e32 v104, v104
	v_rcp_f32_e32 v105, v105
	s_nop 0
	v_pk_fma_f32 v[106:107], v[104:105], s[92:93], v[92:93] op_sel_hi:[1,0,0]
	s_nop 0
	v_pk_fma_f32 v[106:107], v[104:105], v[106:107], s[94:95] op_sel_hi:[1,1,0]
	s_nop 0
	v_pk_fma_f32 v[106:107], v[104:105], v[106:107], s[96:97] op_sel_hi:[1,1,0]
	s_nop 0
	v_pk_fma_f32 v[106:107], v[104:105], v[106:107], s[30:31] op_sel_hi:[1,1,0]
	s_nop 0
	v_pk_mul_f32 v[104:105], v[104:105], v[106:107]
	v_pk_mul_f32 v[106:107], v[94:95], v[94:95]
	v_pk_mul_f32 v[104:105], v[108:109], v[104:105]
	s_nop 0
	v_pk_mul_f32 v[108:109], v[96:97], v[104:105]
	v_pk_fma_f32 v[104:105], v[96:97], v[104:105], v[96:97] neg_lo:[1,0,0] neg_hi:[1,0,0]
	s_nop 0
	v_cndmask_b32_e32 v96, v104, v108, vcc
	v_cmp_gt_f32_e32 vcc, 0, v97
	v_and_b32_e32 v104, 0x7fffffff, v94
	s_nop 0
	v_cndmask_b32_e32 v97, v105, v109, vcc
	v_and_b32_e32 v105, 0x7fffffff, v95
	v_pk_fma_f32 v[104:105], v[104:105], s[90:91], 1.0 op_sel_hi:[1,0,0]
	v_cmp_gt_f32_e32 vcc, 0, v94
	v_rcp_f32_e32 v104, v104
	v_rcp_f32_e32 v105, v105
	s_nop 0
	v_pk_fma_f32 v[92:93], v[104:105], s[92:93], v[92:93] op_sel_hi:[1,0,0]
	s_nop 0
	v_pk_fma_f32 v[92:93], v[104:105], v[92:93], s[94:95] op_sel_hi:[1,1,0]
	s_nop 0
	v_pk_fma_f32 v[92:93], v[104:105], v[92:93], s[96:97] op_sel_hi:[1,1,0]
	s_nop 0
	v_pk_fma_f32 v[92:93], v[104:105], v[92:93], s[30:31] op_sel_hi:[1,1,0]
	s_nop 0
	v_pk_mul_f32 v[92:93], v[104:105], v[92:93]
	v_pk_mul_f32 v[104:105], v[106:107], s[2:3] op_sel_hi:[1,0]
	s_nop 0
	v_exp_f32_e32 v104, v104
	v_exp_f32_e32 v105, v105
	s_nop 0
	v_pk_mul_f32 v[92:93], v[104:105], v[92:93]
	s_nop 0
	v_pk_mul_f32 v[104:105], v[94:95], v[92:93]
	v_pk_fma_f32 v[92:93], v[94:95], v[92:93], v[94:95] neg_lo:[1,0,0] neg_hi:[1,0,0]
	s_nop 0
	v_cndmask_b32_e32 v94, v92, v104, vcc
	v_cmp_gt_f32_e32 vcc, 0, v95
	s_nop 1
	v_cndmask_b32_e32 v95, v93, v105, vcc

; __device__ __forceinline__ float ss_get(const ss_t* p) { const ss_t v = *p; return (float)(unsigned)(v >> 32) + (float)(unsigned)v * 2.3283064365386963e-10f; }
; __device__ __forceinline__ unsigned pkbf(float lo, float hi) { typedef float f2_t __attribute__((ext_vector_type(2))); typedef __bf16 b2_t __attribute__((ext_vector_type(2))); f2_t v = {lo, hi}; b2_t b = __builtin_convertvector(v, b2_t); return __builtin_bit_cast(unsigned, b); }
; __device__ __forceinline__ f32x2 gelu_pk(f32x2 v) {
;     const f32x2 av = __builtin_elementwise_abs(v), d = av * 0.2316418882f + 1.0f;
;     f32x2 t; t.x = __builtin_amdgcn_rcpf(d.x); t.y = __builtin_amdgcn_rcpf(d.y);
;     f32x2 q = t * 0.5307027145f + (-0.7265760135f); q = q * t + 0.7107068705f; q = q * t + (-0.142248368f); q = q * t + 0.127414796f; q = q * t;
;     const f32x2 s = (v * v) * (-0.72134752044f);
;     f32x2 e; e.x = __builtin_amdgcn_exp2f(s.x); e.y = __builtin_amdgcn_exp2f(s.y);
;     const f32x2 m = v * (q * e), r = v - m;
;     f32x2 o; o.x = v.x < 0.f ? m.x : r.x; o.y = v.y < 0.f ? m.y : r.y; return o;
;     __device__ __forceinline__ void operator()(const f32x4 (&acc)[2][2][4][2], const Unit& u, int wr, int wc, int fr, int fq) const {
;     ...
;             for (int m = 0; m < 4; ++m) { const int row = row0 + ai * HALF + m * 16; bf16_t* rowp = O + (size_t)row * ldc + col0;
;                 const float rs = 1.0f / sqrtf(ss_get(ssq + row) * (1.0f / 2048.f) + 1e-6f);
; #pragma unroll
;                 for (int bj = 0; bj < 2; ++bj) { f32x4 v0 = acc[ai][bj][m][0] * rs, v1 = acc[ai][bj][m][1] * rs;
;                     if (act) { f32x2 a = gelu_pk((f32x2){v0[0], v0[1]}), b = gelu_pk((f32x2){v0[2], v0[3]}), c = gelu_pk((f32x2){v1[0], v1[1]}), d = gelu_pk((f32x2){v1[2], v1[3]});
;                         v0 = (f32x4){a.x, a.y, b.x, b.y}; v1 = (f32x4){c.x, c.y, d.x, d.y}; }
;                     u32x4 w; w.x = pkbf(v0[0], v0[1]); w.y = pkbf(v0[2], v0[3]); w.z = pkbf(v1[0], v1[1]); w.w = pkbf(v1[2], v1[3]);
.LBB0_189:
	v_cvt_pk_bf16_f32 v88, v88, v89
	v_cvt_pk_bf16_f32 v89, v90, v91
	v_cvt_pk_bf16_f32 v90, v84, v85
	v_cvt_pk_bf16_f32 v91, v86, v87
	global_store_dwordx4 v[92:93], v[88:91], off offset:256
	s_nop 1
	v_mov_b32_e32 v84, v176
	v_mov_b32_e32 v85, v177
	v_mov_b32_e32 v87, v2
	v_mov_b32_e32 v86, v85
	v_lshlrev_b64 v[86:87], s15, v[86:87]
	v_min_u32_e32 v85, 1, v86
	v_or_b32_e32 v85, v87, v85
	v_cvt_f32_u32_e32 v85, v85
	v_cvt_f32_u32_e32 v84, v84
	v_ldexp_f32 v85, v85, s52
	v_fmac_f32_e32 v85, 0x2f800000, v84
	v_fmamk_f32 v84, v85, 0x3a000000, v205
	v_rsq_f32_e32 v84, v84
	s_nop 0
	s_nop 1
	s_nop 0
	s_nop 1
	s_nop 1
	s_nop 1
	s_and_b64 vcc, exec, s[36:37]
	v_pk_mul_f32 v[82:83], v[82:83], v[84:85] op_sel_hi:[1,0]
	v_pk_mul_f32 v[86:87], v[80:81], v[84:85] op_sel_hi:[1,0]
	v_pk_mul_f32 v[78:79], v[78:79], v[84:85] op_sel_hi:[1,0]
	v_pk_mul_f32 v[80:81], v[76:77], v[84:85] op_sel_hi:[1,0]
	s_cbranch_vccnz .LBB0_191
	v_and_b32_e32 v77, 0x7fffffff, v87
	v_and_b32_e32 v76, 0x7fffffff, v86
	v_pk_fma_f32 v[76:77], v[76:77], s[90:91], 1.0 op_sel_hi:[1,0,0]
	s_mov_b32 s2, 0xbf3a00e3
	v_rcp_f32_e32 v88, v76
	v_rcp_f32_e32 v89, v77
	v_mov_b64_e32 v[76:77], s[2:3]
	v_pk_mul_f32 v[92:93], v[86:87], v[86:87]
	s_mov_b32 s2, 0xbf38aa3b
	v_pk_fma_f32 v[90:91], v[88:89], s[92:93], v[76:77] op_sel_hi:[1,0,0]
	v_pk_mul_f32 v[92:93], v[92:93], s[2:3] op_sel_hi:[1,0]
	v_pk_fma_f32 v[90:91], v[88:89], v[90:91], s[94:95] op_sel_hi:[1,1,0]
	v_exp_f32_e32 v92, v92
	v_exp_f32_e32 v93, v93
	v_pk_fma_f32 v[90:91], v[88:89], v[90:91], s[96:97] op_sel_hi:[1,1,0]
	v_cmp_gt_f32_e32 vcc, 0, v86
	v_pk_fma_f32 v[90:91], v[88:89], v[90:91], s[30:31] op_sel_hi:[1,1,0]
	s_nop 0
	v_pk_mul_f32 v[88:89], v[88:89], v[90:91]
	v_pk_mul_f32 v[90:91], v[82:83], v[82:83]
	v_pk_mul_f32 v[88:89], v[92:93], v[88:89]
	v_pk_mul_f32 v[90:91], v[90:91], s[2:3] op_sel_hi:[1,0]
	v_pk_mul_f32 v[92:93], v[86:87], v[88:89]
	v_pk_fma_f32 v[88:89], v[86:87], v[88:89], v[86:87] neg_lo:[1,0,0] neg_hi:[1,0,0]
	v_exp_f32_e32 v90, v90
	v_cndmask_b32_e32 v86, v88, v92, vcc
	v_cmp_gt_f32_e32 vcc, 0, v87
	v_and_b32_e32 v88, 0x7fffffff, v82
	v_exp_f32_e32 v91, v91
	v_cndmask_b32_e32 v87, v89, v93, vcc
	v_and_b32_e32 v89, 0x7fffffff, v83
	v_pk_fma_f32 v[88:89], v[88:89], s[90:91], 1.0 op_sel_hi:[1,0,0]
	v_cmp_gt_f32_e32 vcc, 0, v82
	v_rcp_f32_e32 v88, v88
	v_rcp_f32_e32 v89, v89
	s_nop 0
	v_pk_fma_f32 v[92:93], v[88:89], s[92:93], v[76:77] op_sel_hi:[1,0,0]
	s_nop 0
	v_pk_fma_f32 v[92:93], v[88:89], v[92:93], s[94:95] op_sel_hi:[1,1,0]
	s_nop 0
	v_pk_fma_f32 v[92:93], v[88:89], v[92:93], s[96:97] op_sel_hi:[1,1,0]
	s_nop 0
	v_pk_fma_f32 v[92:93], v[88:89], v[92:93], s[30:31] op_sel_hi:[1,1,0]
	s_nop 0
	v_pk_mul_f32 v[88:89], v[88:89], v[92:93]
	v_pk_mul_f32 v[92:93], v[80:81], v[80:81]
	v_pk_mul_f32 v[88:89], v[90:91], v[88:89]
	v_pk_mul_f32 v[92:93], v[92:93], s[2:3] op_sel_hi:[1,0]
	v_pk_mul_f32 v[90:91], v[82:83], v[88:89]
	v_pk_fma_f32 v[88:89], v[82:83], v[88:89], v[82:83] neg_lo:[1,0,0] neg_hi:[1,0,0]
	v_exp_f32_e32 v92, v92
	v_cndmask_b32_e32 v82, v88, v90, vcc
	v_cmp_gt_f32_e32 vcc, 0, v83
	v_and_b32_e32 v88, 0x7fffffff, v80
	v_exp_f32_e32 v93, v93
	v_cndmask_b32_e32 v83, v89, v91, vcc
	v_and_b32_e32 v89, 0x7fffffff, v81
	v_pk_fma_f32 v[88:89], v[88:89], s[90:91], 1.0 op_sel_hi:[1,0,0]
	v_cmp_gt_f32_e32 vcc, 0, v80
	v_rcp_f32_e32 v88, v88
	v_rcp_f32_e32 v89, v89
	s_nop 0
	v_pk_fma_f32 v[90:91], v[88:89], s[92:93], v[76:77] op_sel_hi:[1,0,0]
	s_nop 0
	v_pk_fma_f32 v[90:91], v[88:89], v[90:91], s[94:95] op_sel_hi:[1,1,0]
	s_nop 0
	v_pk_fma_f32 v[90:91], v[88:89], v[90:91], s[96:97] op_sel_hi:[1,1,0]
	s_nop 0
	v_pk_fma_f32 v[90:91], v[88:89], v[90:91], s[30:31] op_sel_hi:[1,1,0]
	s_nop 0
	v_pk_mul_f32 v[88:89], v[88:89], v[90:91]
	v_pk_mul_f32 v[90:91], v[78:79], v[78:79]
	v_pk_mul_f32 v[88:89], v[92:93], v[88:89]
	s_nop 0
	v_pk_mul_f32 v[92:93], v[80:81], v[88:89]
	v_pk_fma_f32 v[88:89], v[80:81], v[88:89], v[80:81] neg_lo:[1,0,0] neg_hi:[1,0,0]
	s_nop 0
	v_cndmask_b32_e32 v80, v88, v92, vcc
	v_cmp_gt_f32_e32 vcc, 0, v81
	v_and_b32_e32 v88, 0x7fffffff, v78
	s_nop 0
	v_cndmask_b32_e32 v81, v89, v93, vcc
	v_and_b32_e32 v89, 0x7fffffff, v79
	v_pk_fma_f32 v[88:89], v[88:89], s[90:91], 1.0 op_sel_hi:[1,0,0]
	v_cmp_gt_f32_e32 vcc, 0, v78
	v_rcp_f32_e32 v88, v88
	v_rcp_f32_e32 v89, v89
	s_nop 0
	v_pk_fma_f32 v[76:77], v[88:89], s[92:93], v[76:77] op_sel_hi:[1,0,0]
	s_nop 0
	v_pk_fma_f32 v[76:77], v[88:89], v[76:77], s[94:95] op_sel_hi:[1,1,0]
	s_nop 0
	v_pk_fma_f32 v[76:77], v[88:89], v[76:77], s[96:97] op_sel_hi:[1,1,0]
	s_nop 0
	v_pk_fma_f32 v[76:77], v[88:89], v[76:77], s[30:31] op_sel_hi:[1,1,0]
	s_nop 0
	v_pk_mul_f32 v[76:77], v[88:89], v[76:77]
	v_pk_mul_f32 v[88:89], v[90:91], s[2:3] op_sel_hi:[1,0]
	s_nop 0
	v_exp_f32_e32 v88, v88
	v_exp_f32_e32 v89, v89
	s_nop 0
	v_pk_mul_f32 v[76:77], v[88:89], v[76:77]
	s_nop 0
	v_pk_mul_f32 v[88:89], v[78:79], v[76:77]
	v_pk_fma_f32 v[76:77], v[78:79], v[76:77], v[78:79] neg_lo:[1,0,0] neg_hi:[1,0,0]
	s_nop 0
	v_cndmask_b32_e32 v78, v76, v88, vcc
	v_cmp_gt_f32_e32 vcc, 0, v79
	s_nop 1
	v_cndmask_b32_e32 v79, v77, v89, vcc

; __device__ __forceinline__ float ss_get(const ss_t* p) { const ss_t v = *p; return (float)(unsigned)(v >> 32) + (float)(unsigned)v * 2.3283064365386963e-10f; }
; __device__ __forceinline__ unsigned pkbf(float lo, float hi) { typedef float f2_t __attribute__((ext_vector_type(2))); typedef __bf16 b2_t __attribute__((ext_vector_type(2))); f2_t v = {lo, hi}; b2_t b = __builtin_convertvector(v, b2_t); return __builtin_bit_cast(unsigned, b); }
; __device__ __forceinline__ f32x2 gelu_pk(f32x2 v) {
;     const f32x2 av = __builtin_elementwise_abs(v), d = av * 0.2316418882f + 1.0f;
;     f32x2 t; t.x = __builtin_amdgcn_rcpf(d.x); t.y = __builtin_amdgcn_rcpf(d.y);
;     f32x2 q = t * 0.5307027145f + (-0.7265760135f); q = q * t + 0.7107068705f; q = q * t + (-0.142248368f); q = q * t + 0.127414796f; q = q * t;
;     const f32x2 s = (v * v) * (-0.72134752044f);
;     f32x2 e; e.x = __builtin_amdgcn_exp2f(s.x); e.y = __builtin_amdgcn_exp2f(s.y);
;     const f32x2 m = v * (q * e), r = v - m;
;     f32x2 o; o.x = v.x < 0.f ? m.x : r.x; o.y = v.y < 0.f ? m.y : r.y; return o;
;     __device__ __forceinline__ void operator()(const f32x4 (&acc)[2][2][4][2], const Unit& u, int wr, int wc, int fr, int fq) const {
;     ...
;             for (int m = 0; m < 4; ++m) { const int row = row0 + ai * HALF + m * 16; bf16_t* rowp = O + (size_t)row * ldc + col0;
;                 const float rs = 1.0f / sqrtf(ss_get(ssq + row) * (1.0f / 2048.f) + 1e-6f);
; #pragma unroll
;                 for (int bj = 0; bj < 2; ++bj) { f32x4 v0 = acc[ai][bj][m][0] * rs, v1 = acc[ai][bj][m][1] * rs;
;                     if (act) { f32x2 a = gelu_pk((f32x2){v0[0], v0[1]}), b = gelu_pk((f32x2){v0[2], v0[3]}), c = gelu_pk((f32x2){v1[0], v1[1]}), d = gelu_pk((f32x2){v1[2], v1[3]});
;                         v0 = (f32x4){a.x, a.y, b.x, b.y}; v1 = (f32x4){c.x, c.y, d.x, d.y}; }
;                     u32x4 w; w.x = pkbf(v0[0], v0[1]); w.y = pkbf(v0[2], v0[3]); w.z = pkbf(v1[0], v1[1]); w.w = pkbf(v1[2], v1[3]);
.LBB0_193:
	v_cvt_pk_bf16_f32 v72, v72, v73
	v_cvt_pk_bf16_f32 v73, v74, v75
	v_cvt_pk_bf16_f32 v74, v68, v69
	v_cvt_pk_bf16_f32 v75, v70, v71
	global_store_dwordx4 v[76:77], v[72:75], off offset:256
	s_nop 1
	v_mov_b32_e32 v68, v178
	v_mov_b32_e32 v69, v179
	v_mov_b32_e32 v71, v2
	v_mov_b32_e32 v70, v69
	v_lshlrev_b64 v[70:71], s15, v[70:71]
	v_min_u32_e32 v69, 1, v70
	v_or_b32_e32 v69, v71, v69
	v_cvt_f32_u32_e32 v69, v69
	v_cvt_f32_u32_e32 v68, v68
	v_ldexp_f32 v69, v69, s52
	v_fmac_f32_e32 v69, 0x2f800000, v68
	v_fmamk_f32 v68, v69, 0x3a000000, v205
	v_rsq_f32_e32 v68, v68
	s_nop 0
	s_nop 1
	s_nop 0
	s_nop 1
	s_nop 1
	s_nop 1
	s_and_b64 vcc, exec, s[36:37]
	v_pk_mul_f32 v[66:67], v[66:67], v[68:69] op_sel_hi:[1,0]
	v_pk_mul_f32 v[70:71], v[64:65], v[68:69] op_sel_hi:[1,0]
	v_pk_mul_f32 v[62:63], v[62:63], v[68:69] op_sel_hi:[1,0]
	v_pk_mul_f32 v[64:65], v[60:61], v[68:69] op_sel_hi:[1,0]
	s_cbranch_vccnz .LBB0_195
	v_and_b32_e32 v61, 0x7fffffff, v71
	v_and_b32_e32 v60, 0x7fffffff, v70
	v_pk_fma_f32 v[60:61], v[60:61], s[90:91], 1.0 op_sel_hi:[1,0,0]
	s_mov_b32 s2, 0xbf3a00e3
	v_rcp_f32_e32 v72, v60
	v_rcp_f32_e32 v73, v61
	v_mov_b64_e32 v[60:61], s[2:3]
	v_pk_mul_f32 v[76:77], v[70:71], v[70:71]
	s_mov_b32 s2, 0xbf38aa3b
	v_pk_fma_f32 v[74:75], v[72:73], s[92:93], v[60:61] op_sel_hi:[1,0,0]
	v_pk_mul_f32 v[76:77], v[76:77], s[2:3] op_sel_hi:[1,0]
	v_pk_fma_f32 v[74:75], v[72:73], v[74:75], s[94:95] op_sel_hi:[1,1,0]
	v_exp_f32_e32 v76, v76
	v_exp_f32_e32 v77, v77
	v_pk_fma_f32 v[74:75], v[72:73], v[74:75], s[96:97] op_sel_hi:[1,1,0]
	v_cmp_gt_f32_e32 vcc, 0, v70
	v_pk_fma_f32 v[74:75], v[72:73], v[74:75], s[30:31] op_sel_hi:[1,1,0]
	s_nop 0
	v_pk_mul_f32 v[72:73], v[72:73], v[74:75]
	v_pk_mul_f32 v[74:75], v[66:67], v[66:67]
	v_pk_mul_f32 v[72:73], v[76:77], v[72:73]
	v_pk_mul_f32 v[74:75], v[74:75], s[2:3] op_sel_hi:[1,0]
	v_pk_mul_f32 v[76:77], v[70:71], v[72:73]
	v_pk_fma_f32 v[72:73], v[70:71], v[72:73], v[70:71] neg_lo:[1,0,0] neg_hi:[1,0,0]
	v_exp_f32_e32 v74, v74
	v_cndmask_b32_e32 v70, v72, v76, vcc
	v_cmp_gt_f32_e32 vcc, 0, v71
	v_and_b32_e32 v72, 0x7fffffff, v66
	v_exp_f32_e32 v75, v75
	v_cndmask_b32_e32 v71, v73, v77, vcc
	v_and_b32_e32 v73, 0x7fffffff, v67
	v_pk_fma_f32 v[72:73], v[72:73], s[90:91], 1.0 op_sel_hi:[1,0,0]
	v_cmp_gt_f32_e32 vcc, 0, v66
	v_rcp_f32_e32 v72, v72
	v_rcp_f32_e32 v73, v73
	s_nop 0
	v_pk_fma_f32 v[76:77], v[72:73], s[92:93], v[60:61] op_sel_hi:[1,0,0]
	s_nop 0
	v_pk_fma_f32 v[76:77], v[72:73], v[76:77], s[94:95] op_sel_hi:[1,1,0]
	s_nop 0
	v_pk_fma_f32 v[76:77], v[72:73], v[76:77], s[96:97] op_sel_hi:[1,1,0]
	s_nop 0
	v_pk_fma_f32 v[76:77], v[72:73], v[76:77], s[30:31] op_sel_hi:[1,1,0]
	s_nop 0
	v_pk_mul_f32 v[72:73], v[72:73], v[76:77]
	v_pk_mul_f32 v[76:77], v[64:65], v[64:65]
	v_pk_mul_f32 v[72:73], v[74:75], v[72:73]
	v_pk_mul_f32 v[76:77], v[76:77], s[2:3] op_sel_hi:[1,0]
	v_pk_mul_f32 v[74:75], v[66:67], v[72:73]
	v_pk_fma_f32 v[72:73], v[66:67], v[72:73], v[66:67] neg_lo:[1,0,0] neg_hi:[1,0,0]
	v_exp_f32_e32 v76, v76
	v_cndmask_b32_e32 v66, v72, v74, vcc
	v_cmp_gt_f32_e32 vcc, 0, v67
	v_and_b32_e32 v72, 0x7fffffff, v64
	v_exp_f32_e32 v77, v77
	v_cndmask_b32_e32 v67, v73, v75, vcc
	v_and_b32_e32 v73, 0x7fffffff, v65
	v_pk_fma_f32 v[72:73], v[72:73], s[90:91], 1.0 op_sel_hi:[1,0,0]
	v_cmp_gt_f32_e32 vcc, 0, v64
	v_rcp_f32_e32 v72, v72
	v_rcp_f32_e32 v73, v73
	s_nop 0
	v_pk_fma_f32 v[74:75], v[72:73], s[92:93], v[60:61] op_sel_hi:[1,0,0]
	s_nop 0
	v_pk_fma_f32 v[74:75], v[72:73], v[74:75], s[94:95] op_sel_hi:[1,1,0]
	s_nop 0
	v_pk_fma_f32 v[74:75], v[72:73], v[74:75], s[96:97] op_sel_hi:[1,1,0]
	s_nop 0
	v_pk_fma_f32 v[74:75], v[72:73], v[74:75], s[30:31] op_sel_hi:[1,1,0]
	s_nop 0
	v_pk_mul_f32 v[72:73], v[72:73], v[74:75]
	v_pk_mul_f32 v[74:75], v[62:63], v[62:63]
	v_pk_mul_f32 v[72:73], v[76:77], v[72:73]
	s_nop 0
	v_pk_mul_f32 v[76:77], v[64:65], v[72:73]
	v_pk_fma_f32 v[72:73], v[64:65], v[72:73], v[64:65] neg_lo:[1,0,0] neg_hi:[1,0,0]
	s_nop 0
	v_cndmask_b32_e32 v64, v72, v76, vcc
	v_cmp_gt_f32_e32 vcc, 0, v65
	v_and_b32_e32 v72, 0x7fffffff, v62
	s_nop 0
	v_cndmask_b32_e32 v65, v73, v77, vcc
	v_and_b32_e32 v73, 0x7fffffff, v63
	v_pk_fma_f32 v[72:73], v[72:73], s[90:91], 1.0 op_sel_hi:[1,0,0]
	v_cmp_gt_f32_e32 vcc, 0, v62
	v_rcp_f32_e32 v72, v72
	v_rcp_f32_e32 v73, v73
	s_nop 0
	v_pk_fma_f32 v[60:61], v[72:73], s[92:93], v[60:61] op_sel_hi:[1,0,0]
	s_nop 0
	v_pk_fma_f32 v[60:61], v[72:73], v[60:61], s[94:95] op_sel_hi:[1,1,0]
	s_nop 0
	v_pk_fma_f32 v[60:61], v[72:73], v[60:61], s[96:97] op_sel_hi:[1,1,0]
	s_nop 0
	v_pk_fma_f32 v[60:61], v[72:73], v[60:61], s[30:31] op_sel_hi:[1,1,0]
	s_nop 0
	v_pk_mul_f32 v[60:61], v[72:73], v[60:61]
	v_pk_mul_f32 v[72:73], v[74:75], s[2:3] op_sel_hi:[1,0]
	s_nop 0
	v_exp_f32_e32 v72, v72
	v_exp_f32_e32 v73, v73
	s_nop 0
	v_pk_mul_f32 v[60:61], v[72:73], v[60:61]
	s_nop 0
	v_pk_mul_f32 v[72:73], v[62:63], v[60:61]
	v_pk_fma_f32 v[60:61], v[62:63], v[60:61], v[62:63] neg_lo:[1,0,0] neg_hi:[1,0,0]
	s_nop 0
	v_cndmask_b32_e32 v62, v60, v72, vcc
	v_cmp_gt_f32_e32 vcc, 0, v63
	s_nop 1
	v_cndmask_b32_e32 v63, v61, v73, vcc

; __device__ __forceinline__ float ss_get(const ss_t* p) { const ss_t v = *p; return (float)(unsigned)(v >> 32) + (float)(unsigned)v * 2.3283064365386963e-10f; }
; __device__ __forceinline__ unsigned pkbf(float lo, float hi) { typedef float f2_t __attribute__((ext_vector_type(2))); typedef __bf16 b2_t __attribute__((ext_vector_type(2))); f2_t v = {lo, hi}; b2_t b = __builtin_convertvector(v, b2_t); return __builtin_bit_cast(unsigned, b); }
; __device__ __forceinline__ f32x2 gelu_pk(f32x2 v) {
;     const f32x2 av = __builtin_elementwise_abs(v), d = av * 0.2316418882f + 1.0f;
;     f32x2 t; t.x = __builtin_amdgcn_rcpf(d.x); t.y = __builtin_amdgcn_rcpf(d.y);
;     f32x2 q = t * 0.5307027145f + (-0.7265760135f); q = q * t + 0.7107068705f; q = q * t + (-0.142248368f); q = q * t + 0.127414796f; q = q * t;
;     const f32x2 s = (v * v) * (-0.72134752044f);
;     f32x2 e; e.x = __builtin_amdgcn_exp2f(s.x); e.y = __builtin_amdgcn_exp2f(s.y);
;     const f32x2 m = v * (q * e), r = v - m;
;     f32x2 o; o.x = v.x < 0.f ? m.x : r.x; o.y = v.y < 0.f ? m.y : r.y; return o;
;     __device__ __forceinline__ void operator()(const f32x4 (&acc)[2][2][4][2], const Unit& u, int wr, int wc, int fr, int fq) const {
;     ...
;             for (int m = 0; m < 4; ++m) { const int row = row0 + ai * HALF + m * 16; bf16_t* rowp = O + (size_t)row * ldc + col0;
;                 const float rs = 1.0f / sqrtf(ss_get(ssq + row) * (1.0f / 2048.f) + 1e-6f);
; #pragma unroll
;                 for (int bj = 0; bj < 2; ++bj) { f32x4 v0 = acc[ai][bj][m][0] * rs, v1 = acc[ai][bj][m][1] * rs;
;                     if (act) { f32x2 a = gelu_pk((f32x2){v0[0], v0[1]}), b = gelu_pk((f32x2){v0[2], v0[3]}), c = gelu_pk((f32x2){v1[0], v1[1]}), d = gelu_pk((f32x2){v1[2], v1[3]});
;                         v0 = (f32x4){a.x, a.y, b.x, b.y}; v1 = (f32x4){c.x, c.y, d.x, d.y}; }
;                     u32x4 w; w.x = pkbf(v0[0], v0[1]); w.y = pkbf(v0[2], v0[3]); w.z = pkbf(v1[0], v1[1]); w.w = pkbf(v1[2], v1[3]);
.LBB0_197:
	v_cvt_pk_bf16_f32 v56, v56, v57
	v_cvt_pk_bf16_f32 v57, v58, v59
	v_cvt_pk_bf16_f32 v58, v52, v53
	v_cvt_pk_bf16_f32 v59, v54, v55
	global_store_dwordx4 v[60:61], v[56:59], off offset:256
	s_nop 1
	v_mov_b32_e32 v52, v180
	v_mov_b32_e32 v53, v181
	v_mov_b32_e32 v55, v2
	v_mov_b32_e32 v54, v53
	v_lshlrev_b64 v[54:55], s15, v[54:55]
	v_min_u32_e32 v53, 1, v54
	v_or_b32_e32 v53, v55, v53
	v_cvt_f32_u32_e32 v53, v53
	v_cvt_f32_u32_e32 v52, v52
	v_ldexp_f32 v53, v53, s52
	v_fmac_f32_e32 v53, 0x2f800000, v52
	v_fmamk_f32 v52, v53, 0x3a000000, v205
	v_rsq_f32_e32 v52, v52
	s_nop 0
	s_nop 1
	s_nop 0
	s_nop 1
	s_nop 1
	s_nop 1
	s_and_b64 vcc, exec, s[36:37]
	v_pk_mul_f32 v[50:51], v[50:51], v[52:53] op_sel_hi:[1,0]
	v_pk_mul_f32 v[54:55], v[48:49], v[52:53] op_sel_hi:[1,0]
	v_pk_mul_f32 v[46:47], v[46:47], v[52:53] op_sel_hi:[1,0]
	v_pk_mul_f32 v[48:49], v[44:45], v[52:53] op_sel_hi:[1,0]
	s_cbranch_vccnz .LBB0_199
	v_and_b32_e32 v45, 0x7fffffff, v55
	v_and_b32_e32 v44, 0x7fffffff, v54
	v_pk_fma_f32 v[44:45], v[44:45], s[90:91], 1.0 op_sel_hi:[1,0,0]
	s_mov_b32 s2, 0xbf3a00e3
	v_rcp_f32_e32 v56, v44
	v_rcp_f32_e32 v57, v45
	v_mov_b64_e32 v[44:45], s[2:3]
	v_pk_mul_f32 v[60:61], v[54:55], v[54:55]
	s_mov_b32 s2, 0xbf38aa3b
	v_pk_fma_f32 v[58:59], v[56:57], s[92:93], v[44:45] op_sel_hi:[1,0,0]
	v_pk_mul_f32 v[60:61], v[60:61], s[2:3] op_sel_hi:[1,0]
	v_pk_fma_f32 v[58:59], v[56:57], v[58:59], s[94:95] op_sel_hi:[1,1,0]
	v_exp_f32_e32 v60, v60
	v_exp_f32_e32 v61, v61
	v_pk_fma_f32 v[58:59], v[56:57], v[58:59], s[96:97] op_sel_hi:[1,1,0]
	v_cmp_gt_f32_e32 vcc, 0, v54
	v_pk_fma_f32 v[58:59], v[56:57], v[58:59], s[30:31] op_sel_hi:[1,1,0]
	s_nop 0
	v_pk_mul_f32 v[56:57], v[56:57], v[58:59]
	v_pk_mul_f32 v[58:59], v[50:51], v[50:51]
	v_pk_mul_f32 v[56:57], v[60:61], v[56:57]
	v_pk_mul_f32 v[58:59], v[58:59], s[2:3] op_sel_hi:[1,0]
	v_pk_mul_f32 v[60:61], v[54:55], v[56:57]
	v_pk_fma_f32 v[56:57], v[54:55], v[56:57], v[54:55] neg_lo:[1,0,0] neg_hi:[1,0,0]
	v_exp_f32_e32 v58, v58
	v_cndmask_b32_e32 v54, v56, v60, vcc
	v_cmp_gt_f32_e32 vcc, 0, v55
	v_and_b32_e32 v56, 0x7fffffff, v50
	v_exp_f32_e32 v59, v59
	v_cndmask_b32_e32 v55, v57, v61, vcc
	v_and_b32_e32 v57, 0x7fffffff, v51
	v_pk_fma_f32 v[56:57], v[56:57], s[90:91], 1.0 op_sel_hi:[1,0,0]
	v_cmp_gt_f32_e32 vcc, 0, v50
	v_rcp_f32_e32 v56, v56
	v_rcp_f32_e32 v57, v57
	s_nop 0
	v_pk_fma_f32 v[60:61], v[56:57], s[92:93], v[44:45] op_sel_hi:[1,0,0]
	s_nop 0
	v_pk_fma_f32 v[60:61], v[56:57], v[60:61], s[94:95] op_sel_hi:[1,1,0]
	s_nop 0
	v_pk_fma_f32 v[60:61], v[56:57], v[60:61], s[96:97] op_sel_hi:[1,1,0]
	s_nop 0
	v_pk_fma_f32 v[60:61], v[56:57], v[60:61], s[30:31] op_sel_hi:[1,1,0]
	s_nop 0
	v_pk_mul_f32 v[56:57], v[56:57], v[60:61]
	v_pk_mul_f32 v[60:61], v[48:49], v[48:49]
	v_pk_mul_f32 v[56:57], v[58:59], v[56:57]
	v_pk_mul_f32 v[60:61], v[60:61], s[2:3] op_sel_hi:[1,0]
	v_pk_mul_f32 v[58:59], v[50:51], v[56:57]
	v_pk_fma_f32 v[56:57], v[50:51], v[56:57], v[50:51] neg_lo:[1,0,0] neg_hi:[1,0,0]
	v_exp_f32_e32 v60, v60
	v_cndmask_b32_e32 v50, v56, v58, vcc
	v_cmp_gt_f32_e32 vcc, 0, v51
	v_and_b32_e32 v56, 0x7fffffff, v48
	v_exp_f32_e32 v61, v61
	v_cndmask_b32_e32 v51, v57, v59, vcc
	v_and_b32_e32 v57, 0x7fffffff, v49
	v_pk_fma_f32 v[56:57], v[56:57], s[90:91], 1.0 op_sel_hi:[1,0,0]
	v_cmp_gt_f32_e32 vcc, 0, v48
	v_rcp_f32_e32 v56, v56
	v_rcp_f32_e32 v57, v57
	s_nop 0
	v_pk_fma_f32 v[58:59], v[56:57], s[92:93], v[44:45] op_sel_hi:[1,0,0]
	s_nop 0
	v_pk_fma_f32 v[58:59], v[56:57], v[58:59], s[94:95] op_sel_hi:[1,1,0]
	s_nop 0
	v_pk_fma_f32 v[58:59], v[56:57], v[58:59], s[96:97] op_sel_hi:[1,1,0]
	s_nop 0
	v_pk_fma_f32 v[58:59], v[56:57], v[58:59], s[30:31] op_sel_hi:[1,1,0]
	s_nop 0
	v_pk_mul_f32 v[56:57], v[56:57], v[58:59]
	v_pk_mul_f32 v[58:59], v[46:47], v[46:47]
	v_pk_mul_f32 v[56:57], v[60:61], v[56:57]
	s_nop 0
	v_pk_mul_f32 v[60:61], v[48:49], v[56:57]
	v_pk_fma_f32 v[56:57], v[48:49], v[56:57], v[48:49] neg_lo:[1,0,0] neg_hi:[1,0,0]
	s_nop 0
	v_cndmask_b32_e32 v48, v56, v60, vcc
	v_cmp_gt_f32_e32 vcc, 0, v49
	v_and_b32_e32 v56, 0x7fffffff, v46
	s_nop 0
	v_cndmask_b32_e32 v49, v57, v61, vcc
	v_and_b32_e32 v57, 0x7fffffff, v47
	v_pk_fma_f32 v[56:57], v[56:57], s[90:91], 1.0 op_sel_hi:[1,0,0]
	v_cmp_gt_f32_e32 vcc, 0, v46
	v_rcp_f32_e32 v56, v56
	v_rcp_f32_e32 v57, v57
	s_nop 0
	v_pk_fma_f32 v[44:45], v[56:57], s[92:93], v[44:45] op_sel_hi:[1,0,0]
	s_nop 0
	v_pk_fma_f32 v[44:45], v[56:57], v[44:45], s[94:95] op_sel_hi:[1,1,0]
	s_nop 0
	v_pk_fma_f32 v[44:45], v[56:57], v[44:45], s[96:97] op_sel_hi:[1,1,0]
	s_nop 0
	v_pk_fma_f32 v[44:45], v[56:57], v[44:45], s[30:31] op_sel_hi:[1,1,0]
	s_nop 0
	v_pk_mul_f32 v[44:45], v[56:57], v[44:45]
	v_pk_mul_f32 v[56:57], v[58:59], s[2:3] op_sel_hi:[1,0]
	s_nop 0
	v_exp_f32_e32 v56, v56
	v_exp_f32_e32 v57, v57
	s_nop 0
	v_pk_mul_f32 v[44:45], v[56:57], v[44:45]
	s_nop 0
	v_pk_mul_f32 v[56:57], v[46:47], v[44:45]
	v_pk_fma_f32 v[44:45], v[46:47], v[44:45], v[46:47] neg_lo:[1,0,0] neg_hi:[1,0,0]
	s_nop 0
	v_cndmask_b32_e32 v46, v44, v56, vcc
	v_cmp_gt_f32_e32 vcc, 0, v47
	s_nop 1
	v_cndmask_b32_e32 v47, v45, v57, vcc

; __device__ __forceinline__ float ss_get(const ss_t* p) { const ss_t v = *p; return (float)(unsigned)(v >> 32) + (float)(unsigned)v * 2.3283064365386963e-10f; }
; __device__ __forceinline__ unsigned pkbf(float lo, float hi) { typedef float f2_t __attribute__((ext_vector_type(2))); typedef __bf16 b2_t __attribute__((ext_vector_type(2))); f2_t v = {lo, hi}; b2_t b = __builtin_convertvector(v, b2_t); return __builtin_bit_cast(unsigned, b); }
; __device__ __forceinline__ f32x2 gelu_pk(f32x2 v) {
;     const f32x2 av = __builtin_elementwise_abs(v), d = av * 0.2316418882f + 1.0f;
;     f32x2 t; t.x = __builtin_amdgcn_rcpf(d.x); t.y = __builtin_amdgcn_rcpf(d.y);
;     f32x2 q = t * 0.5307027145f + (-0.7265760135f); q = q * t + 0.7107068705f; q = q * t + (-0.142248368f); q = q * t + 0.127414796f; q = q * t;
;     const f32x2 s = (v * v) * (-0.72134752044f);
;     f32x2 e; e.x = __builtin_amdgcn_exp2f(s.x); e.y = __builtin_amdgcn_exp2f(s.y);
;     const f32x2 m = v * (q * e), r = v - m;
;     f32x2 o; o.x = v.x < 0.f ? m.x : r.x; o.y = v.y < 0.f ? m.y : r.y; return o;
;     __device__ __forceinline__ void operator()(const f32x4 (&acc)[2][2][4][2], const Unit& u, int wr, int wc, int fr, int fq) const {
;     ...
;             for (int m = 0; m < 4; ++m) { const int row = row0 + ai * HALF + m * 16; bf16_t* rowp = O + (size_t)row * ldc + col0;
;                 const float rs = 1.0f / sqrtf(ss_get(ssq + row) * (1.0f / 2048.f) + 1e-6f);
; #pragma unroll
;                 for (int bj = 0; bj < 2; ++bj) { f32x4 v0 = acc[ai][bj][m][0] * rs, v1 = acc[ai][bj][m][1] * rs;
;                     if (act) { f32x2 a = gelu_pk((f32x2){v0[0], v0[1]}), b = gelu_pk((f32x2){v0[2], v0[3]}), c = gelu_pk((f32x2){v1[0], v1[1]}), d = gelu_pk((f32x2){v1[2], v1[3]});
;                         v0 = (f32x4){a.x, a.y, b.x, b.y}; v1 = (f32x4){c.x, c.y, d.x, d.y}; }
;                     u32x4 w; w.x = pkbf(v0[0], v0[1]); w.y = pkbf(v0[2], v0[3]); w.z = pkbf(v1[0], v1[1]); w.w = pkbf(v1[2], v1[3]);
.LBB0_201:
	v_cvt_pk_bf16_f32 v40, v40, v41
	v_cvt_pk_bf16_f32 v41, v42, v43
	v_cvt_pk_bf16_f32 v42, v36, v37
	v_cvt_pk_bf16_f32 v43, v38, v39
	global_store_dwordx4 v[44:45], v[40:43], off offset:256
	s_nop 1
	v_mov_b32_e32 v36, v182
	v_mov_b32_e32 v37, v183
	v_mov_b32_e32 v39, v2
	v_mov_b32_e32 v38, v37
	v_lshlrev_b64 v[38:39], s15, v[38:39]
	v_min_u32_e32 v37, 1, v38
	v_or_b32_e32 v37, v39, v37
	v_cvt_f32_u32_e32 v37, v37
	v_cvt_f32_u32_e32 v36, v36
	v_ldexp_f32 v37, v37, s52
	v_fmac_f32_e32 v37, 0x2f800000, v36
	v_fmamk_f32 v36, v37, 0x3a000000, v205
	v_rsq_f32_e32 v36, v36
	s_nop 0
	s_nop 1
	s_nop 0
	s_nop 1
	s_nop 1
	s_nop 1
	s_and_b64 vcc, exec, s[36:37]
	v_pk_mul_f32 v[34:35], v[34:35], v[36:37] op_sel_hi:[1,0]
	v_pk_mul_f32 v[38:39], v[32:33], v[36:37] op_sel_hi:[1,0]
	v_pk_mul_f32 v[30:31], v[30:31], v[36:37] op_sel_hi:[1,0]
	v_pk_mul_f32 v[32:33], v[28:29], v[36:37] op_sel_hi:[1,0]
	s_cbranch_vccnz .LBB0_203
	v_and_b32_e32 v29, 0x7fffffff, v39
	v_and_b32_e32 v28, 0x7fffffff, v38
	v_pk_fma_f32 v[28:29], v[28:29], s[90:91], 1.0 op_sel_hi:[1,0,0]
	s_mov_b32 s2, 0xbf3a00e3
	v_rcp_f32_e32 v40, v28
	v_rcp_f32_e32 v41, v29
	v_mov_b64_e32 v[28:29], s[2:3]
	v_pk_mul_f32 v[44:45], v[38:39], v[38:39]
	s_mov_b32 s2, 0xbf38aa3b
	v_pk_fma_f32 v[42:43], v[40:41], s[92:93], v[28:29] op_sel_hi:[1,0,0]
	v_pk_mul_f32 v[44:45], v[44:45], s[2:3] op_sel_hi:[1,0]
	v_pk_fma_f32 v[42:43], v[40:41], v[42:43], s[94:95] op_sel_hi:[1,1,0]
	v_exp_f32_e32 v44, v44
	v_exp_f32_e32 v45, v45
	v_pk_fma_f32 v[42:43], v[40:41], v[42:43], s[96:97] op_sel_hi:[1,1,0]
	v_cmp_gt_f32_e32 vcc, 0, v38
	v_pk_fma_f32 v[42:43], v[40:41], v[42:43], s[30:31] op_sel_hi:[1,1,0]
	s_nop 0
	v_pk_mul_f32 v[40:41], v[40:41], v[42:43]
	v_pk_mul_f32 v[42:43], v[34:35], v[34:35]
	v_pk_mul_f32 v[40:41], v[44:45], v[40:41]
	v_pk_mul_f32 v[42:43], v[42:43], s[2:3] op_sel_hi:[1,0]
	v_pk_mul_f32 v[44:45], v[38:39], v[40:41]
	v_pk_fma_f32 v[40:41], v[38:39], v[40:41], v[38:39] neg_lo:[1,0,0] neg_hi:[1,0,0]
	v_exp_f32_e32 v42, v42
	v_cndmask_b32_e32 v38, v40, v44, vcc
	v_cmp_gt_f32_e32 vcc, 0, v39
	v_and_b32_e32 v40, 0x7fffffff, v34
	v_exp_f32_e32 v43, v43
	v_cndmask_b32_e32 v39, v41, v45, vcc
	v_and_b32_e32 v41, 0x7fffffff, v35
	v_pk_fma_f32 v[40:41], v[40:41], s[90:91], 1.0 op_sel_hi:[1,0,0]
	v_cmp_gt_f32_e32 vcc, 0, v34
	v_rcp_f32_e32 v40, v40
	v_rcp_f32_e32 v41, v41
	s_nop 0
	v_pk_fma_f32 v[44:45], v[40:41], s[92:93], v[28:29] op_sel_hi:[1,0,0]
	s_nop 0
	v_pk_fma_f32 v[44:45], v[40:41], v[44:45], s[94:95] op_sel_hi:[1,1,0]
	s_nop 0
	v_pk_fma_f32 v[44:45], v[40:41], v[44:45], s[96:97] op_sel_hi:[1,1,0]
	s_nop 0
	v_pk_fma_f32 v[44:45], v[40:41], v[44:45], s[30:31] op_sel_hi:[1,1,0]
	s_nop 0
	v_pk_mul_f32 v[40:41], v[40:41], v[44:45]
	v_pk_mul_f32 v[44:45], v[32:33], v[32:33]
	v_pk_mul_f32 v[40:41], v[42:43], v[40:41]
	v_pk_mul_f32 v[44:45], v[44:45], s[2:3] op_sel_hi:[1,0]
	v_pk_mul_f32 v[42:43], v[34:35], v[40:41]
	v_pk_fma_f32 v[40:41], v[34:35], v[40:41], v[34:35] neg_lo:[1,0,0] neg_hi:[1,0,0]
	v_exp_f32_e32 v44, v44
	v_cndmask_b32_e32 v34, v40, v42, vcc
	v_cmp_gt_f32_e32 vcc, 0, v35
	v_and_b32_e32 v40, 0x7fffffff, v32
	v_exp_f32_e32 v45, v45
	v_cndmask_b32_e32 v35, v41, v43, vcc
	v_and_b32_e32 v41, 0x7fffffff, v33
	v_pk_fma_f32 v[40:41], v[40:41], s[90:91], 1.0 op_sel_hi:[1,0,0]
	v_cmp_gt_f32_e32 vcc, 0, v32
	v_rcp_f32_e32 v40, v40
	v_rcp_f32_e32 v41, v41
	s_nop 0
	v_pk_fma_f32 v[42:43], v[40:41], s[92:93], v[28:29] op_sel_hi:[1,0,0]
	s_nop 0
	v_pk_fma_f32 v[42:43], v[40:41], v[42:43], s[94:95] op_sel_hi:[1,1,0]
	s_nop 0
	v_pk_fma_f32 v[42:43], v[40:41], v[42:43], s[96:97] op_sel_hi:[1,1,0]
	s_nop 0
	v_pk_fma_f32 v[42:43], v[40:41], v[42:43], s[30:31] op_sel_hi:[1,1,0]
	s_nop 0
	v_pk_mul_f32 v[40:41], v[40:41], v[42:43]
	v_pk_mul_f32 v[42:43], v[30:31], v[30:31]
	v_pk_mul_f32 v[40:41], v[44:45], v[40:41]
	s_nop 0
	v_pk_mul_f32 v[44:45], v[32:33], v[40:41]
	v_pk_fma_f32 v[40:41], v[32:33], v[40:41], v[32:33] neg_lo:[1,0,0] neg_hi:[1,0,0]
	s_nop 0
	v_cndmask_b32_e32 v32, v40, v44, vcc
	v_cmp_gt_f32_e32 vcc, 0, v33
	v_and_b32_e32 v40, 0x7fffffff, v30
	s_nop 0
	v_cndmask_b32_e32 v33, v41, v45, vcc
	v_and_b32_e32 v41, 0x7fffffff, v31
	v_pk_fma_f32 v[40:41], v[40:41], s[90:91], 1.0 op_sel_hi:[1,0,0]
	v_cmp_gt_f32_e32 vcc, 0, v30
	v_rcp_f32_e32 v40, v40
	v_rcp_f32_e32 v41, v41
	s_nop 0
	v_pk_fma_f32 v[28:29], v[40:41], s[92:93], v[28:29] op_sel_hi:[1,0,0]
	s_nop 0
	v_pk_fma_f32 v[28:29], v[40:41], v[28:29], s[94:95] op_sel_hi:[1,1,0]
	s_nop 0
	v_pk_fma_f32 v[28:29], v[40:41], v[28:29], s[96:97] op_sel_hi:[1,1,0]
	s_nop 0
	v_pk_fma_f32 v[28:29], v[40:41], v[28:29], s[30:31] op_sel_hi:[1,1,0]
	s_nop 0
	v_pk_mul_f32 v[28:29], v[40:41], v[28:29]
	v_pk_mul_f32 v[40:41], v[42:43], s[2:3] op_sel_hi:[1,0]
	s_nop 0
	v_exp_f32_e32 v40, v40
	v_exp_f32_e32 v41, v41
	s_nop 0
	v_pk_mul_f32 v[28:29], v[40:41], v[28:29]
	s_nop 0
	v_pk_mul_f32 v[40:41], v[30:31], v[28:29]
	v_pk_fma_f32 v[28:29], v[30:31], v[28:29], v[30:31] neg_lo:[1,0,0] neg_hi:[1,0,0]
	s_nop 0
	v_cndmask_b32_e32 v30, v28, v40, vcc
	v_cmp_gt_f32_e32 vcc, 0, v31
	s_nop 1
	v_cndmask_b32_e32 v31, v29, v41, vcc

; __device__ __forceinline__ float ss_get(const ss_t* p) { const ss_t v = *p; return (float)(unsigned)(v >> 32) + (float)(unsigned)v * 2.3283064365386963e-10f; }
; __device__ __forceinline__ unsigned pkbf(float lo, float hi) { typedef float f2_t __attribute__((ext_vector_type(2))); typedef __bf16 b2_t __attribute__((ext_vector_type(2))); f2_t v = {lo, hi}; b2_t b = __builtin_convertvector(v, b2_t); return __builtin_bit_cast(unsigned, b); }
; __device__ __forceinline__ f32x2 gelu_pk(f32x2 v) {
;     const f32x2 av = __builtin_elementwise_abs(v), d = av * 0.2316418882f + 1.0f;
;     f32x2 t; t.x = __builtin_amdgcn_rcpf(d.x); t.y = __builtin_amdgcn_rcpf(d.y);
;     f32x2 q = t * 0.5307027145f + (-0.7265760135f); q = q * t + 0.7107068705f; q = q * t + (-0.142248368f); q = q * t + 0.127414796f; q = q * t;
;     const f32x2 s = (v * v) * (-0.72134752044f);
;     f32x2 e; e.x = __builtin_amdgcn_exp2f(s.x); e.y = __builtin_amdgcn_exp2f(s.y);
;     const f32x2 m = v * (q * e), r = v - m;
;     f32x2 o; o.x = v.x < 0.f ? m.x : r.x; o.y = v.y < 0.f ? m.y : r.y; return o;
;     __device__ __forceinline__ void operator()(const f32x4 (&acc)[2][2][4][2], const Unit& u, int wr, int wc, int fr, int fq) const {
;     ...
;             for (int m = 0; m < 4; ++m) { const int row = row0 + ai * HALF + m * 16; bf16_t* rowp = O + (size_t)row * ldc + col0;
;                 const float rs = 1.0f / sqrtf(ss_get(ssq + row) * (1.0f / 2048.f) + 1e-6f);
; #pragma unroll
;                 for (int bj = 0; bj < 2; ++bj) { f32x4 v0 = acc[ai][bj][m][0] * rs, v1 = acc[ai][bj][m][1] * rs;
;                     if (act) { f32x2 a = gelu_pk((f32x2){v0[0], v0[1]}), b = gelu_pk((f32x2){v0[2], v0[3]}), c = gelu_pk((f32x2){v1[0], v1[1]}), d = gelu_pk((f32x2){v1[2], v1[3]});
;                         v0 = (f32x4){a.x, a.y, b.x, b.y}; v1 = (f32x4){c.x, c.y, d.x, d.y}; }
;                     u32x4 w; w.x = pkbf(v0[0], v0[1]); w.y = pkbf(v0[2], v0[3]); w.z = pkbf(v1[0], v1[1]); w.w = pkbf(v1[2], v1[3]);
.LBB0_205:
	v_cvt_pk_bf16_f32 v24, v24, v25
	v_cvt_pk_bf16_f32 v25, v26, v27
	v_cvt_pk_bf16_f32 v26, v20, v21
	v_cvt_pk_bf16_f32 v27, v22, v23
	global_store_dwordx4 v[28:29], v[24:27], off offset:256
	s_nop 1
	v_mov_b32_e32 v20, v184
	v_mov_b32_e32 v21, v185
	v_mov_b32_e32 v23, v2
	v_mov_b32_e32 v22, v21
	v_lshlrev_b64 v[22:23], s15, v[22:23]
	v_min_u32_e32 v21, 1, v22
	v_or_b32_e32 v21, v23, v21
	v_cvt_f32_u32_e32 v21, v21
	v_cvt_f32_u32_e32 v20, v20
	v_ldexp_f32 v21, v21, s52
	v_fmac_f32_e32 v21, 0x2f800000, v20
	v_fmamk_f32 v20, v21, 0x3a000000, v205
	v_rsq_f32_e32 v20, v20
	s_nop 0
	s_nop 1
	s_nop 0
	s_nop 1
	s_nop 1
	s_nop 1
	s_and_b64 vcc, exec, s[36:37]
	v_pk_mul_f32 v[18:19], v[18:19], v[20:21] op_sel_hi:[1,0]
	v_pk_mul_f32 v[22:23], v[16:17], v[20:21] op_sel_hi:[1,0]
	v_pk_mul_f32 v[14:15], v[14:15], v[20:21] op_sel_hi:[1,0]
	v_pk_mul_f32 v[16:17], v[12:13], v[20:21] op_sel_hi:[1,0]
	s_cbranch_vccnz .LBB0_207
	v_and_b32_e32 v13, 0x7fffffff, v23
	v_and_b32_e32 v12, 0x7fffffff, v22
	v_pk_fma_f32 v[12:13], v[12:13], s[90:91], 1.0 op_sel_hi:[1,0,0]
	s_mov_b32 s2, 0xbf3a00e3
	v_rcp_f32_e32 v24, v12
	v_rcp_f32_e32 v25, v13
	v_mov_b64_e32 v[12:13], s[2:3]
	v_pk_mul_f32 v[28:29], v[22:23], v[22:23]
	s_mov_b32 s2, 0xbf38aa3b
	v_pk_fma_f32 v[26:27], v[24:25], s[92:93], v[12:13] op_sel_hi:[1,0,0]
	v_pk_mul_f32 v[28:29], v[28:29], s[2:3] op_sel_hi:[1,0]
	v_pk_fma_f32 v[26:27], v[24:25], v[26:27], s[94:95] op_sel_hi:[1,1,0]
	v_exp_f32_e32 v28, v28
	v_exp_f32_e32 v29, v29
	v_pk_fma_f32 v[26:27], v[24:25], v[26:27], s[96:97] op_sel_hi:[1,1,0]
	v_cmp_gt_f32_e32 vcc, 0, v22
	v_pk_fma_f32 v[26:27], v[24:25], v[26:27], s[30:31] op_sel_hi:[1,1,0]
	s_nop 0
	v_pk_mul_f32 v[24:25], v[24:25], v[26:27]
	v_pk_mul_f32 v[26:27], v[18:19], v[18:19]
	v_pk_mul_f32 v[24:25], v[28:29], v[24:25]
	v_pk_mul_f32 v[26:27], v[26:27], s[2:3] op_sel_hi:[1,0]
	v_pk_mul_f32 v[28:29], v[22:23], v[24:25]
	v_pk_fma_f32 v[24:25], v[22:23], v[24:25], v[22:23] neg_lo:[1,0,0] neg_hi:[1,0,0]
	v_exp_f32_e32 v26, v26
	v_cndmask_b32_e32 v22, v24, v28, vcc
	v_cmp_gt_f32_e32 vcc, 0, v23
	v_and_b32_e32 v24, 0x7fffffff, v18
	v_exp_f32_e32 v27, v27
	v_cndmask_b32_e32 v23, v25, v29, vcc
	v_and_b32_e32 v25, 0x7fffffff, v19
	v_pk_fma_f32 v[24:25], v[24:25], s[90:91], 1.0 op_sel_hi:[1,0,0]
	v_cmp_gt_f32_e32 vcc, 0, v18
	v_rcp_f32_e32 v24, v24
	v_rcp_f32_e32 v25, v25
	s_nop 0
	v_pk_fma_f32 v[28:29], v[24:25], s[92:93], v[12:13] op_sel_hi:[1,0,0]
	s_nop 0
	v_pk_fma_f32 v[28:29], v[24:25], v[28:29], s[94:95] op_sel_hi:[1,1,0]
	s_nop 0
	v_pk_fma_f32 v[28:29], v[24:25], v[28:29], s[96:97] op_sel_hi:[1,1,0]
	s_nop 0
	v_pk_fma_f32 v[28:29], v[24:25], v[28:29], s[30:31] op_sel_hi:[1,1,0]
	s_nop 0
	v_pk_mul_f32 v[24:25], v[24:25], v[28:29]
	v_pk_mul_f32 v[28:29], v[16:17], v[16:17]
	v_pk_mul_f32 v[24:25], v[26:27], v[24:25]
	v_pk_mul_f32 v[28:29], v[28:29], s[2:3] op_sel_hi:[1,0]
	v_pk_mul_f32 v[26:27], v[18:19], v[24:25]
	v_pk_fma_f32 v[24:25], v[18:19], v[24:25], v[18:19] neg_lo:[1,0,0] neg_hi:[1,0,0]
	v_exp_f32_e32 v28, v28
	v_cndmask_b32_e32 v18, v24, v26, vcc
	v_cmp_gt_f32_e32 vcc, 0, v19
	v_and_b32_e32 v24, 0x7fffffff, v16
	v_exp_f32_e32 v29, v29
	v_cndmask_b32_e32 v19, v25, v27, vcc
	v_and_b32_e32 v25, 0x7fffffff, v17
	v_pk_fma_f32 v[24:25], v[24:25], s[90:91], 1.0 op_sel_hi:[1,0,0]
	v_cmp_gt_f32_e32 vcc, 0, v16
	v_rcp_f32_e32 v24, v24
	v_rcp_f32_e32 v25, v25
	s_nop 0
	v_pk_fma_f32 v[26:27], v[24:25], s[92:93], v[12:13] op_sel_hi:[1,0,0]
	s_nop 0
	v_pk_fma_f32 v[26:27], v[24:25], v[26:27], s[94:95] op_sel_hi:[1,1,0]
	s_nop 0
	v_pk_fma_f32 v[26:27], v[24:25], v[26:27], s[96:97] op_sel_hi:[1,1,0]
	s_nop 0
	v_pk_fma_f32 v[26:27], v[24:25], v[26:27], s[30:31] op_sel_hi:[1,1,0]
	s_nop 0
	v_pk_mul_f32 v[24:25], v[24:25], v[26:27]
	v_pk_mul_f32 v[26:27], v[14:15], v[14:15]
	v_pk_mul_f32 v[24:25], v[28:29], v[24:25]
	s_nop 0
	v_pk_mul_f32 v[28:29], v[16:17], v[24:25]
	v_pk_fma_f32 v[24:25], v[16:17], v[24:25], v[16:17] neg_lo:[1,0,0] neg_hi:[1,0,0]
	s_nop 0
	v_cndmask_b32_e32 v16, v24, v28, vcc
	v_cmp_gt_f32_e32 vcc, 0, v17
	v_and_b32_e32 v24, 0x7fffffff, v14
	s_nop 0
	v_cndmask_b32_e32 v17, v25, v29, vcc
	v_and_b32_e32 v25, 0x7fffffff, v15
	v_pk_fma_f32 v[24:25], v[24:25], s[90:91], 1.0 op_sel_hi:[1,0,0]
	v_cmp_gt_f32_e32 vcc, 0, v14
	v_rcp_f32_e32 v24, v24
	v_rcp_f32_e32 v25, v25
	s_nop 0
	v_pk_fma_f32 v[12:13], v[24:25], s[92:93], v[12:13] op_sel_hi:[1,0,0]
	s_nop 0
	v_pk_fma_f32 v[12:13], v[24:25], v[12:13], s[94:95] op_sel_hi:[1,1,0]
	s_nop 0
	v_pk_fma_f32 v[12:13], v[24:25], v[12:13], s[96:97] op_sel_hi:[1,1,0]
	s_nop 0
	v_pk_fma_f32 v[12:13], v[24:25], v[12:13], s[30:31] op_sel_hi:[1,1,0]
	s_nop 0
	v_pk_mul_f32 v[12:13], v[24:25], v[12:13]
	v_pk_mul_f32 v[24:25], v[26:27], s[2:3] op_sel_hi:[1,0]
	s_nop 0
	v_exp_f32_e32 v24, v24
	v_exp_f32_e32 v25, v25
	s_nop 0
	v_pk_mul_f32 v[12:13], v[24:25], v[12:13]
	s_nop 0
	v_pk_mul_f32 v[24:25], v[14:15], v[12:13]
	v_pk_fma_f32 v[12:13], v[14:15], v[12:13], v[14:15] neg_lo:[1,0,0] neg_hi:[1,0,0]
	s_nop 0
	v_cndmask_b32_e32 v14, v12, v24, vcc
	v_cmp_gt_f32_e32 vcc, 0, v15
	s_nop 1
	v_cndmask_b32_e32 v15, v13, v25, vcc

; __device__ __forceinline__ float ss_get(const ss_t* p) { const ss_t v = *p; return (float)(unsigned)(v >> 32) + (float)(unsigned)v * 2.3283064365386963e-10f; }
;     __device__ __forceinline__ void mid(f32x4 (&acc)[2][2][4][2], const Unit& u, int wr, int wc, int fr, int fq) const {
;     ...
;             for (int m = 0; m < 4; ++m) { const int row = row0 + ai * HALF + m * 16;
;                 const float ra = 1.0f / sqrtf(ss_get(ssa + row) * (1.0f / 1024.f) + 1e-6f), rbi = sqrtf(ss_get(ssb + row) * (1.0f / 1024.f) + 1e-6f); const float ratio = ra * rbi;
; #pragma unroll
;                 for (int bj = 0; bj < 2; ++bj)
; #pragma unroll
;                     for (int n = 0; n < 2; ++n) acc[ai][bj][m][n] = acc[ai][bj][m][n] * ratio; }
.LBB0_927:
	s_cmpk_lg_i32 s46, 0x800
	s_cbranch_scc1 .LBB0_926
	v_mov_b32_e32 v0, v193
	s_flbit_i32_b32 s2, 0
	v_ashrrev_i32_e32 v1, 31, v0
	v_lshlrev_b64 v[0:1], 3, v[0:1]
	v_lshl_add_u64 v[132:133], s[6:7], 0, v[0:1]
	global_load_dwordx2 v[134:135], v[132:133], off
	v_mov_b32_e32 v137, v2
	s_min_u32 s48, s2, 32
	s_sub_i32 s49, 32, s48
	v_lshl_add_u64 v[0:1], s[8:9], 0, v[0:1]
	global_load_dwordx2 v[140:141], v[0:1], off
	global_load_dwordx2 v[142:143], v[132:133], off offset:128
	global_load_dwordx2 v[144:145], v[0:1], off offset:128
	global_load_dwordx2 v[146:147], v[132:133], off offset:256
	global_load_dwordx2 v[148:149], v[0:1], off offset:256
	global_load_dwordx2 v[150:151], v[132:133], off offset:384
	global_load_dwordx2 v[152:153], v[0:1], off offset:384
	global_load_dwordx2 v[154:155], v[132:133], off offset:1024
	global_load_dwordx2 v[212:213], v[0:1], off offset:1024
	global_load_dwordx2 v[214:215], v[132:133], off offset:1152
	global_load_dwordx2 v[216:217], v[0:1], off offset:1152
	global_load_dwordx2 v[218:219], v[132:133], off offset:1280
	global_load_dwordx2 v[220:221], v[132:133], off offset:1408
	global_load_dwordx2 v[222:223], v[0:1], off offset:1280
	global_load_dwordx2 v[224:225], v[0:1], off offset:1408
	s_waitcnt vmcnt(0)
	v_mov_b32_e32 v136, v135
	v_lshlrev_b64 v[136:137], s48, v[136:137]
	v_min_u32_e32 v3, 1, v136
	v_or_b32_e32 v3, v137, v3
	v_cvt_f32_u32_e32 v3, v3
	v_cvt_f32_u32_e32 v134, v134
	v_ldexp_f32 v3, v3, s49
	v_fmac_f32_e32 v3, 0x2f800000, v134
	v_fmamk_f32 v3, v3, 0x3a800000, v205
	v_rsq_f32_e32 v3, v3
	s_nop 0
	s_nop 0
	s_nop 0
	s_nop 0
	s_nop 1
	s_nop 1
	s_nop 0
	s_nop 1
	v_mov_b32_e32 v134, v140
	v_mov_b32_e32 v135, v141
	v_mov_b32_e32 v137, v2
	v_mov_b32_e32 v136, v135
	v_lshlrev_b64 v[136:137], s48, v[136:137]
	v_min_u32_e32 v135, 1, v136
	v_or_b32_e32 v135, v137, v135
	v_cvt_f32_u32_e32 v135, v135
	v_cvt_f32_u32_e32 v134, v134
	v_ldexp_f32 v135, v135, s49
	v_fmac_f32_e32 v135, 0x2f800000, v134
	v_fmamk_f32 v134, v135, 0x3a800000, v205
	v_cmp_gt_f32_e32 vcc, s97, v134
	v_mul_f32_e32 v135, 0x4f800000, v134
	s_nop 0
	v_cndmask_b32_e32 v134, v134, v135, vcc
	v_sqrt_f32_e32 v135, v134
	s_nop 0
	v_add_u32_e32 v136, -1, v135
	v_fma_f32 v137, -v136, v135, v134
	v_cmp_ge_f32_e64 s[2:3], 0, v137
	v_add_u32_e32 v137, 1, v135
	s_nop 0
	v_cndmask_b32_e64 v136, v135, v136, s[2:3]
	v_fma_f32 v135, -v137, v135, v134
	v_cmp_lt_f32_e64 s[2:3], 0, v135
	s_nop 1
	v_cndmask_b32_e64 v135, v136, v137, s[2:3]
	v_mul_f32_e32 v136, 0x37800000, v135
	v_cndmask_b32_e32 v135, v135, v136, vcc
	v_cmp_class_f32_e32 vcc, v134, v206
	v_mov_b32_e32 v137, v2
	s_nop 0
	v_cndmask_b32_e32 v134, v135, v134, vcc
	v_mul_f32_e32 v134, v3, v134
	v_pk_mul_f32 v[130:131], v[130:131], v[134:135] op_sel_hi:[1,0]
	v_pk_mul_f32 v[128:129], v[128:129], v[134:135] op_sel_hi:[1,0]
	v_pk_mul_f32 v[126:127], v[126:127], v[134:135] op_sel_hi:[1,0]
	v_pk_mul_f32 v[124:125], v[124:125], v[134:135] op_sel_hi:[1,0]
	v_pk_mul_f32 v[122:123], v[122:123], v[134:135] op_sel_hi:[1,0]
	v_pk_mul_f32 v[120:121], v[120:121], v[134:135] op_sel_hi:[1,0]
	v_pk_mul_f32 v[118:119], v[118:119], v[134:135] op_sel_hi:[1,0]
	v_pk_mul_f32 v[116:117], v[116:117], v[134:135] op_sel_hi:[1,0]
	s_nop 1
	v_mov_b32_e32 v134, v142
	v_mov_b32_e32 v135, v143
	v_mov_b32_e32 v136, v135
	v_lshlrev_b64 v[136:137], s48, v[136:137]
	v_min_u32_e32 v3, 1, v136
	v_or_b32_e32 v3, v137, v3
	v_cvt_f32_u32_e32 v3, v3
	v_cvt_f32_u32_e32 v134, v134
	v_ldexp_f32 v3, v3, s49
	v_fmac_f32_e32 v3, 0x2f800000, v134
	v_fmamk_f32 v3, v3, 0x3a800000, v205
	v_rsq_f32_e32 v3, v3
	s_nop 0
	s_nop 0
	s_nop 0
	s_nop 0
	s_nop 1
	s_nop 1
	s_nop 0
	s_nop 1
	v_mov_b32_e32 v134, v144
	v_mov_b32_e32 v135, v145
	v_mov_b32_e32 v137, v2
	v_mov_b32_e32 v136, v135
	v_lshlrev_b64 v[136:137], s48, v[136:137]
	v_min_u32_e32 v135, 1, v136
	v_or_b32_e32 v135, v137, v135
	v_cvt_f32_u32_e32 v135, v135
	v_cvt_f32_u32_e32 v134, v134
	v_ldexp_f32 v135, v135, s49
	v_fmac_f32_e32 v135, 0x2f800000, v134
	v_fmamk_f32 v134, v135, 0x3a800000, v205
	v_cmp_gt_f32_e32 vcc, s97, v134
	v_mul_f32_e32 v135, 0x4f800000, v134
	s_nop 0
	v_cndmask_b32_e32 v134, v134, v135, vcc
	v_sqrt_f32_e32 v135, v134
	s_nop 0
	v_add_u32_e32 v136, -1, v135
	v_fma_f32 v137, -v136, v135, v134
	v_cmp_ge_f32_e64 s[2:3], 0, v137
	v_add_u32_e32 v137, 1, v135
	s_nop 0
	v_cndmask_b32_e64 v136, v135, v136, s[2:3]
	v_fma_f32 v135, -v137, v135, v134
	v_cmp_lt_f32_e64 s[2:3], 0, v135
	s_nop 1
	v_cndmask_b32_e64 v135, v136, v137, s[2:3]
	v_mul_f32_e32 v136, 0x37800000, v135
	v_cndmask_b32_e32 v135, v135, v136, vcc
	v_cmp_class_f32_e32 vcc, v134, v206
	v_mov_b32_e32 v137, v2
	s_nop 0
	v_cndmask_b32_e32 v134, v135, v134, vcc
	v_mul_f32_e32 v134, v3, v134
	v_pk_mul_f32 v[114:115], v[114:115], v[134:135] op_sel_hi:[1,0]
	v_pk_mul_f32 v[112:113], v[112:113], v[134:135] op_sel_hi:[1,0]
	v_pk_mul_f32 v[110:111], v[110:111], v[134:135] op_sel_hi:[1,0]
	v_pk_mul_f32 v[108:109], v[108:109], v[134:135] op_sel_hi:[1,0]
	v_pk_mul_f32 v[106:107], v[106:107], v[134:135] op_sel_hi:[1,0]
	v_pk_mul_f32 v[104:105], v[104:105], v[134:135] op_sel_hi:[1,0]
	v_pk_mul_f32 v[102:103], v[102:103], v[134:135] op_sel_hi:[1,0]
	v_pk_mul_f32 v[100:101], v[100:101], v[134:135] op_sel_hi:[1,0]
	s_nop 1
	v_mov_b32_e32 v134, v146
	v_mov_b32_e32 v135, v147
	v_mov_b32_e32 v136, v135
	v_lshlrev_b64 v[136:137], s48, v[136:137]
	v_min_u32_e32 v3, 1, v136
	v_or_b32_e32 v3, v137, v3
	v_cvt_f32_u32_e32 v3, v3
	v_cvt_f32_u32_e32 v134, v134
	v_ldexp_f32 v3, v3, s49
	v_fmac_f32_e32 v3, 0x2f800000, v134
	v_fmamk_f32 v3, v3, 0x3a800000, v205
	v_rsq_f32_e32 v3, v3
	s_nop 0
	s_nop 0
	s_nop 0
	s_nop 0
	s_nop 1
	s_nop 1
; __device__ __forceinline__ float ss_get(const ss_t* p) { const ss_t v = *p; return (float)(unsigned)(v >> 32) + (float)(unsigned)v * 2.3283064365386963e-10f; }
;     __device__ __forceinline__ void mid(f32x4 (&acc)[2][2][4][2], const Unit& u, int wr, int wc, int fr, int fq) const {
;         int row0 = u.pm * BM + wr * 64 + fr; asm volatile("" : "+v"(row0));
; #pragma unroll
;         for (int ai = 0; ai < 2; ++ai)
; #pragma unroll
;             for (int m = 0; m < 4; ++m) { const int row = row0 + ai * HALF + m * 16;
;                 const float ra = 1.0f / sqrtf(ss_get(ssa + row) * (1.0f / 1024.f) + 1e-6f), rbi = sqrtf(ss_get(ssb + row) * (1.0f / 1024.f) + 1e-6f); const float ratio = ra * rbi;
; #pragma unroll
;                 for (int bj = 0; bj < 2; ++bj)
; #pragma unroll
;                     for (int n = 0; n < 2; ++n) acc[ai][bj][m][n] = acc[ai][bj][m][n] * ratio; }
	s_nop 0
	s_nop 1
	v_mov_b32_e32 v134, v148
	v_mov_b32_e32 v135, v149
	v_mov_b32_e32 v137, v2
	v_mov_b32_e32 v136, v135
	v_lshlrev_b64 v[136:137], s48, v[136:137]
	v_min_u32_e32 v135, 1, v136
	v_or_b32_e32 v135, v137, v135
	v_cvt_f32_u32_e32 v135, v135
	v_cvt_f32_u32_e32 v134, v134
	v_ldexp_f32 v135, v135, s49
	v_fmac_f32_e32 v135, 0x2f800000, v134
	v_fmamk_f32 v134, v135, 0x3a800000, v205
	v_cmp_gt_f32_e32 vcc, s97, v134
	v_mul_f32_e32 v135, 0x4f800000, v134
	s_nop 0
	v_cndmask_b32_e32 v134, v134, v135, vcc
	v_sqrt_f32_e32 v135, v134
	s_nop 0
	v_add_u32_e32 v136, -1, v135
	v_fma_f32 v137, -v136, v135, v134
	v_cmp_ge_f32_e64 s[2:3], 0, v137
	v_add_u32_e32 v137, 1, v135
	s_nop 0
	v_cndmask_b32_e64 v136, v135, v136, s[2:3]
	v_fma_f32 v135, -v137, v135, v134
	v_cmp_lt_f32_e64 s[2:3], 0, v135
	s_nop 1
	v_cndmask_b32_e64 v135, v136, v137, s[2:3]
	v_mul_f32_e32 v136, 0x37800000, v135
	v_cndmask_b32_e32 v135, v135, v136, vcc
	v_cmp_class_f32_e32 vcc, v134, v206
	v_mov_b32_e32 v137, v2
	s_nop 0
	v_cndmask_b32_e32 v134, v135, v134, vcc
	v_mul_f32_e32 v134, v3, v134
	v_pk_mul_f32 v[98:99], v[98:99], v[134:135] op_sel_hi:[1,0]
	v_pk_mul_f32 v[96:97], v[96:97], v[134:135] op_sel_hi:[1,0]
	v_pk_mul_f32 v[94:95], v[94:95], v[134:135] op_sel_hi:[1,0]
	v_pk_mul_f32 v[92:93], v[92:93], v[134:135] op_sel_hi:[1,0]
	v_pk_mul_f32 v[90:91], v[90:91], v[134:135] op_sel_hi:[1,0]
	v_pk_mul_f32 v[88:89], v[88:89], v[134:135] op_sel_hi:[1,0]
	v_pk_mul_f32 v[86:87], v[86:87], v[134:135] op_sel_hi:[1,0]
	v_pk_mul_f32 v[84:85], v[84:85], v[134:135] op_sel_hi:[1,0]
	s_nop 1
	v_mov_b32_e32 v134, v150
	v_mov_b32_e32 v135, v151
	v_mov_b32_e32 v136, v135
	v_lshlrev_b64 v[136:137], s48, v[136:137]
	v_min_u32_e32 v3, 1, v136
	v_or_b32_e32 v3, v137, v3
	v_cvt_f32_u32_e32 v3, v3
	v_cvt_f32_u32_e32 v134, v134
	v_ldexp_f32 v3, v3, s49
	v_fmac_f32_e32 v3, 0x2f800000, v134
	v_fmamk_f32 v3, v3, 0x3a800000, v205
	v_rsq_f32_e32 v3, v3
	s_nop 0
	s_nop 0
	s_nop 0
	s_nop 0
	s_nop 1
	s_nop 1
	s_nop 0
	s_nop 1
	v_mov_b32_e32 v134, v152
	v_mov_b32_e32 v135, v153
	v_mov_b32_e32 v137, v2
	v_mov_b32_e32 v136, v135
	v_lshlrev_b64 v[136:137], s48, v[136:137]
	v_min_u32_e32 v135, 1, v136
	v_or_b32_e32 v135, v137, v135
	v_cvt_f32_u32_e32 v135, v135
	v_cvt_f32_u32_e32 v134, v134
	v_ldexp_f32 v135, v135, s49
	v_fmac_f32_e32 v135, 0x2f800000, v134
	v_fmamk_f32 v134, v135, 0x3a800000, v205
	v_cmp_gt_f32_e32 vcc, s97, v134
	v_mul_f32_e32 v135, 0x4f800000, v134
	s_nop 0
	v_cndmask_b32_e32 v134, v134, v135, vcc
	v_sqrt_f32_e32 v135, v134
	s_nop 0
	v_add_u32_e32 v136, -1, v135
	v_fma_f32 v137, -v136, v135, v134
	v_cmp_ge_f32_e64 s[2:3], 0, v137
	v_add_u32_e32 v137, 1, v135
	s_nop 0
	v_cndmask_b32_e64 v136, v135, v136, s[2:3]
	v_fma_f32 v135, -v137, v135, v134
	v_cmp_lt_f32_e64 s[2:3], 0, v135
	s_nop 1
	v_cndmask_b32_e64 v135, v136, v137, s[2:3]
	v_mul_f32_e32 v136, 0x37800000, v135
	v_cndmask_b32_e32 v135, v135, v136, vcc
	v_cmp_class_f32_e32 vcc, v134, v206
	v_mov_b32_e32 v137, v2
	s_nop 0
	v_cndmask_b32_e32 v134, v135, v134, vcc
	v_mul_f32_e32 v134, v3, v134
	v_pk_mul_f32 v[82:83], v[82:83], v[134:135] op_sel_hi:[1,0]
	v_pk_mul_f32 v[80:81], v[80:81], v[134:135] op_sel_hi:[1,0]
	v_pk_mul_f32 v[78:79], v[78:79], v[134:135] op_sel_hi:[1,0]
	v_pk_mul_f32 v[76:77], v[76:77], v[134:135] op_sel_hi:[1,0]
	v_pk_mul_f32 v[74:75], v[74:75], v[134:135] op_sel_hi:[1,0]
	v_pk_mul_f32 v[72:73], v[72:73], v[134:135] op_sel_hi:[1,0]
	v_pk_mul_f32 v[70:71], v[70:71], v[134:135] op_sel_hi:[1,0]
	v_pk_mul_f32 v[68:69], v[68:69], v[134:135] op_sel_hi:[1,0]
	s_nop 1
	v_mov_b32_e32 v134, v154
	v_mov_b32_e32 v135, v155
	v_mov_b32_e32 v136, v135
	v_lshlrev_b64 v[136:137], s48, v[136:137]
	v_min_u32_e32 v3, 1, v136
	v_or_b32_e32 v3, v137, v3
	v_cvt_f32_u32_e32 v3, v3
	v_cvt_f32_u32_e32 v134, v134
	v_ldexp_f32 v3, v3, s49
	v_fmac_f32_e32 v3, 0x2f800000, v134
	v_fmamk_f32 v3, v3, 0x3a800000, v205
	v_rsq_f32_e32 v3, v3
	s_nop 0
	s_nop 0
	s_nop 0
	s_nop 0
	s_nop 1
	s_nop 1
	s_nop 0
	s_nop 1
	v_mov_b32_e32 v134, v212
	v_mov_b32_e32 v135, v213
	v_mov_b32_e32 v137, v2
	v_mov_b32_e32 v136, v135
	v_lshlrev_b64 v[136:137], s48, v[136:137]
	v_min_u32_e32 v135, 1, v136
	v_or_b32_e32 v135, v137, v135
	v_cvt_f32_u32_e32 v135, v135
	v_cvt_f32_u32_e32 v134, v134
	v_ldexp_f32 v135, v135, s49
	v_fmac_f32_e32 v135, 0x2f800000, v134
	v_fmamk_f32 v134, v135, 0x3a800000, v205
	v_cmp_gt_f32_e32 vcc, s97, v134
	v_mul_f32_e32 v135, 0x4f800000, v134
	s_nop 0
	v_cndmask_b32_e32 v134, v134, v135, vcc
	v_sqrt_f32_e32 v135, v134
	s_nop 0
	v_add_u32_e32 v136, -1, v135
	v_fma_f32 v137, -v136, v135, v134
	v_cmp_ge_f32_e64 s[2:3], 0, v137
	v_add_u32_e32 v137, 1, v135
	s_nop 0
	v_cndmask_b32_e64 v136, v135, v136, s[2:3]
	v_fma_f32 v135, -v137, v135, v134
	v_cmp_lt_f32_e64 s[2:3], 0, v135
	s_nop 1
	v_cndmask_b32_e64 v135, v136, v137, s[2:3]
	v_mul_f32_e32 v136, 0x37800000, v135
	v_cndmask_b32_e32 v135, v135, v136, vcc
	v_cmp_class_f32_e32 vcc, v134, v206
	v_mov_b32_e32 v137, v2
	s_nop 0
	v_cndmask_b32_e32 v134, v135, v134, vcc
	v_mul_f32_e32 v134, v3, v134
	v_pk_mul_f32 v[66:67], v[66:67], v[134:135] op_sel_hi:[1,0]
	v_pk_mul_f32 v[64:65], v[64:65], v[134:135] op_sel_hi:[1,0]
	v_pk_mul_f32 v[62:63], v[62:63], v[134:135] op_sel_hi:[1,0]
	v_pk_mul_f32 v[60:61], v[60:61], v[134:135] op_sel_hi:[1,0]
	v_pk_mul_f32 v[58:59], v[58:59], v[134:135] op_sel_hi:[1,0]
	v_pk_mul_f32 v[56:57], v[56:57], v[134:135] op_sel_hi:[1,0]
	v_pk_mul_f32 v[54:55], v[54:55], v[134:135] op_sel_hi:[1,0]
	v_pk_mul_f32 v[52:53], v[52:53], v[134:135] op_sel_hi:[1,0]
	s_nop 1
	v_mov_b32_e32 v134, v214
	v_mov_b32_e32 v135, v215
	v_mov_b32_e32 v136, v135
	v_lshlrev_b64 v[136:137], s48, v[136:137]
; __device__ __forceinline__ float ss_get(const ss_t* p) { const ss_t v = *p; return (float)(unsigned)(v >> 32) + (float)(unsigned)v * 2.3283064365386963e-10f; }
;     __device__ __forceinline__ void mid(f32x4 (&acc)[2][2][4][2], const Unit& u, int wr, int wc, int fr, int fq) const {
;     ...
;                 const float ra = 1.0f / sqrtf(ss_get(ssa + row) * (1.0f / 1024.f) + 1e-6f), rbi = sqrtf(ss_get(ssb + row) * (1.0f / 1024.f) + 1e-6f); const float ratio = ra * rbi;
; #pragma unroll
;                 for (int bj = 0; bj < 2; ++bj)
; #pragma unroll
;                     for (int n = 0; n < 2; ++n) acc[ai][bj][m][n] = acc[ai][bj][m][n] * ratio; }
	v_min_u32_e32 v3, 1, v136
	v_or_b32_e32 v3, v137, v3
	v_cvt_f32_u32_e32 v3, v3
	v_cvt_f32_u32_e32 v134, v134
	v_ldexp_f32 v3, v3, s49
	v_fmac_f32_e32 v3, 0x2f800000, v134
	v_fmamk_f32 v3, v3, 0x3a800000, v205
	v_rsq_f32_e32 v3, v3
	s_nop 0
	s_nop 0
	s_nop 0
	s_nop 0
	s_nop 1
	s_nop 1
	s_nop 0
	s_nop 1
	v_mov_b32_e32 v134, v216
	v_mov_b32_e32 v135, v217
	v_mov_b32_e32 v137, v2
	v_mov_b32_e32 v136, v135
	v_lshlrev_b64 v[136:137], s48, v[136:137]
	v_min_u32_e32 v135, 1, v136
	v_or_b32_e32 v135, v137, v135
	v_cvt_f32_u32_e32 v135, v135
	v_cvt_f32_u32_e32 v134, v134
	v_ldexp_f32 v135, v135, s49
	v_fmac_f32_e32 v135, 0x2f800000, v134
	v_fmamk_f32 v134, v135, 0x3a800000, v205
	v_cmp_gt_f32_e32 vcc, s97, v134
	v_mul_f32_e32 v135, 0x4f800000, v134
	s_nop 0
	v_cndmask_b32_e32 v134, v134, v135, vcc
	v_sqrt_f32_e32 v135, v134
	s_nop 0
	v_add_u32_e32 v136, -1, v135
	v_fma_f32 v137, -v136, v135, v134
	v_cmp_ge_f32_e64 s[2:3], 0, v137
	v_add_u32_e32 v137, 1, v135
	s_nop 0
	v_cndmask_b32_e64 v136, v135, v136, s[2:3]
	v_fma_f32 v135, -v137, v135, v134
	v_cmp_lt_f32_e64 s[2:3], 0, v135
	s_nop 1
	v_cndmask_b32_e64 v135, v136, v137, s[2:3]
	v_mul_f32_e32 v136, 0x37800000, v135
	v_cndmask_b32_e32 v135, v135, v136, vcc
	v_cmp_class_f32_e32 vcc, v134, v206
	v_mov_b32_e32 v137, v2
	s_nop 0
	v_cndmask_b32_e32 v134, v135, v134, vcc
	v_mul_f32_e32 v134, v3, v134
	v_pk_mul_f32 v[50:51], v[50:51], v[134:135] op_sel_hi:[1,0]
	v_pk_mul_f32 v[48:49], v[48:49], v[134:135] op_sel_hi:[1,0]
	v_pk_mul_f32 v[46:47], v[46:47], v[134:135] op_sel_hi:[1,0]
	v_pk_mul_f32 v[44:45], v[44:45], v[134:135] op_sel_hi:[1,0]
	v_pk_mul_f32 v[42:43], v[42:43], v[134:135] op_sel_hi:[1,0]
	v_pk_mul_f32 v[40:41], v[40:41], v[134:135] op_sel_hi:[1,0]
	v_pk_mul_f32 v[38:39], v[38:39], v[134:135] op_sel_hi:[1,0]
	v_pk_mul_f32 v[36:37], v[36:37], v[134:135] op_sel_hi:[1,0]
	s_nop 1
	v_mov_b32_e32 v134, v218
	v_mov_b32_e32 v135, v219
	v_mov_b32_e32 v136, v135
	v_lshlrev_b64 v[136:137], s48, v[136:137]
	v_min_u32_e32 v3, 1, v136
	v_or_b32_e32 v3, v137, v3
	v_cvt_f32_u32_e32 v3, v3
	v_cvt_f32_u32_e32 v134, v134
	s_nop 1
	v_mov_b32_e32 v132, v220
	v_mov_b32_e32 v133, v221
	v_ldexp_f32 v3, v3, s49
	v_fmac_f32_e32 v3, 0x2f800000, v134
	v_fmamk_f32 v3, v3, 0x3a800000, v205
	v_rsq_f32_e32 v3, v3
	s_nop 0
	v_cvt_f32_u32_e32 v132, v132
	s_nop 0
	s_nop 0
	s_nop 1
	s_nop 1
	s_nop 0
	s_nop 1
	v_mov_b32_e32 v134, v222
	v_mov_b32_e32 v135, v223
	v_mov_b32_e32 v137, v2
	s_nop 1
	v_mov_b32_e32 v0, v224
	v_mov_b32_e32 v1, v225
	v_mov_b32_e32 v136, v135
	v_lshlrev_b64 v[136:137], s48, v[136:137]
	v_min_u32_e32 v135, 1, v136
	v_or_b32_e32 v135, v137, v135
	v_cvt_f32_u32_e32 v135, v135
	v_cvt_f32_u32_e32 v134, v134
	v_cvt_f32_u32_e32 v0, v0
	v_ldexp_f32 v135, v135, s49
	v_fmac_f32_e32 v135, 0x2f800000, v134
	v_fmamk_f32 v134, v135, 0x3a800000, v205
	v_cmp_gt_f32_e32 vcc, s97, v134
	v_mul_f32_e32 v135, 0x4f800000, v134
	s_nop 0
	v_cndmask_b32_e32 v134, v134, v135, vcc
	v_sqrt_f32_e32 v135, v134
	s_nop 0
	v_add_u32_e32 v136, -1, v135
	v_fma_f32 v137, -v136, v135, v134
	v_cmp_ge_f32_e64 s[2:3], 0, v137
	v_add_u32_e32 v137, 1, v135
	s_nop 0
	v_cndmask_b32_e64 v136, v135, v136, s[2:3]
	v_fma_f32 v135, -v137, v135, v134
	v_cmp_lt_f32_e64 s[2:3], 0, v135
	s_nop 1
	v_cndmask_b32_e64 v135, v136, v137, s[2:3]
	v_mul_f32_e32 v136, 0x37800000, v135
	v_cndmask_b32_e32 v135, v135, v136, vcc
	v_cmp_class_f32_e32 vcc, v134, v206
	s_nop 1
	v_cndmask_b32_e32 v134, v135, v134, vcc
	v_mul_f32_e32 v134, v3, v134
	v_pk_mul_f32 v[34:35], v[34:35], v[134:135] op_sel_hi:[1,0]
	v_pk_mul_f32 v[32:33], v[32:33], v[134:135] op_sel_hi:[1,0]
	v_pk_mul_f32 v[30:31], v[30:31], v[134:135] op_sel_hi:[1,0]
	v_pk_mul_f32 v[28:29], v[28:29], v[134:135] op_sel_hi:[1,0]
	v_pk_mul_f32 v[26:27], v[26:27], v[134:135] op_sel_hi:[1,0]
	v_pk_mul_f32 v[24:25], v[24:25], v[134:135] op_sel_hi:[1,0]
	v_pk_mul_f32 v[22:23], v[22:23], v[134:135] op_sel_hi:[1,0]
	v_pk_mul_f32 v[20:21], v[20:21], v[134:135] op_sel_hi:[1,0]
	v_mov_b32_e32 v134, v133
	v_mov_b32_e32 v135, v2
	v_lshlrev_b64 v[134:135], s48, v[134:135]
	v_min_u32_e32 v3, 1, v134
	v_or_b32_e32 v3, v135, v3
	v_cvt_f32_u32_e32 v3, v3
	v_ldexp_f32 v3, v3, s49
	v_fmac_f32_e32 v3, 0x2f800000, v132
	v_fmamk_f32 v3, v3, 0x3a800000, v205
	v_rsq_f32_e32 v3, v3
	s_nop 0
	s_nop 0
	s_nop 0
	s_nop 0
	s_nop 1
	s_nop 1
	s_nop 0
	v_mov_b32_e32 v132, v1
	v_mov_b32_e32 v133, v2
	v_lshlrev_b64 v[132:133], s48, v[132:133]
	v_min_u32_e32 v1, 1, v132
	v_or_b32_e32 v1, v133, v1
	v_cvt_f32_u32_e32 v1, v1
	v_ldexp_f32 v1, v1, s49
	v_fmac_f32_e32 v1, 0x2f800000, v0
	v_fmamk_f32 v0, v1, 0x3a800000, v205
	v_cmp_gt_f32_e32 vcc, s97, v0
	v_mul_f32_e32 v1, 0x4f800000, v0
	s_nop 0
	v_cndmask_b32_e32 v0, v0, v1, vcc
	v_sqrt_f32_e32 v1, v0
	s_nop 0
	v_add_u32_e32 v132, -1, v1
	v_fma_f32 v133, -v132, v1, v0
	v_cmp_ge_f32_e64 s[2:3], 0, v133
	v_add_u32_e32 v133, 1, v1
	s_nop 0
	v_cndmask_b32_e64 v132, v1, v132, s[2:3]
	v_fma_f32 v1, -v133, v1, v0
	v_cmp_lt_f32_e64 s[2:3], 0, v1
	s_nop 1
	v_cndmask_b32_e64 v1, v132, v133, s[2:3]
	v_mul_f32_e32 v132, 0x37800000, v1
	v_cndmask_b32_e32 v1, v1, v132, vcc
	v_cmp_class_f32_e32 vcc, v0, v206
	s_nop 1
	v_cndmask_b32_e32 v0, v1, v0, vcc
	v_mul_f32_e32 v0, v3, v0
	v_pk_mul_f32 v[18:19], v[18:19], v[0:1] op_sel_hi:[1,0]
	v_pk_mul_f32 v[16:17], v[16:17], v[0:1] op_sel_hi:[1,0]
	v_pk_mul_f32 v[14:15], v[14:15], v[0:1] op_sel_hi:[1,0]
	v_pk_mul_f32 v[12:13], v[12:13], v[0:1] op_sel_hi:[1,0]
	v_pk_mul_f32 v[10:11], v[10:11], v[0:1] op_sel_hi:[1,0]
	v_pk_mul_f32 v[8:9], v[8:9], v[0:1] op_sel_hi:[1,0]
	v_pk_mul_f32 v[6:7], v[6:7], v[0:1] op_sel_hi:[1,0]
	v_pk_mul_f32 v[4:5], v[4:5], v[0:1] op_sel_hi:[1,0]
	s_branch .LBB0_926

; __device__ __forceinline__ void ss_add(ss_t* p, float sq) { const float fl = floorf(sq); const unsigned hi = (unsigned)fl, lo = (unsigned)((sq - fl) * 4294967296.0f); atomicAdd(p, ((ss_t)hi << 32) | (ss_t)lo); }
;     __device__ __forceinline__ void operator()(const f32x4 (&acc)[2][2][4][2], const Unit& u, int wr, int wc, int fr, int fq) const {
;         int row0 = u.pm * BM + wr * 64 + fr; asm volatile("" : "+v"(row0));     const int col0 = u.pn * BM + wc * 32 + 8 * fq;
; #pragma unroll
;         for (int ai = 0; ai < 2; ++ai) {
;             u32x4 res[4][2];
; #pragma unroll
;             for (int m = 0; m < 4; ++m) { const bf16_t* rowp = XB + (size_t)(row0 + ai * HALF + m * 16) * ldc + col0;
; #pragma unroll
;                 for (int bj = 0; bj < 2; ++bj) res[m][bj] = *(const u32x4*)(rowp + bj * HALF); }
;             asm volatile("" ::: "memory");
; #pragma unroll
;             for (int m = 0; m < 4; ++m) { const int row = row0 + ai * HALF + m * 16; const size_t off = (size_t)row * ldc + col0;
;                 float rs = 1.0f; if (KS) rs = 1.0f / sqrtf(ss_get(ssb + row) * (1.0f / 1024.f) + 1e-6f);
;                 float sq = 0.f;
; #pragma unroll
;                 for (int bj = 0; bj < 2; ++bj) { const u32x4 r = res[m][bj];
;                     const f32x4 x0 = (f32x4){__uint_as_float(r.x << 16), __uint_as_float(r.x & 0xffff0000u), __uint_as_float(r.y << 16), __uint_as_float(r.y & 0xffff0000u)};
;                     const f32x4 x1 = (f32x4){__uint_as_float(r.z << 16), __uint_as_float(r.z & 0xffff0000u), __uint_as_float(r.w << 16), __uint_as_float(r.w & 0xffff0000u)};
;                     const f32x4 v0 = x0 + acc[ai][bj][m][0] * rs, v1 = x1 + acc[ai][bj][m][1] * rs;
;                     if (OUT) { *(f32x4*)(OUT + off + bj * HALF) = v0; *(f32x4*)(OUT + off + bj * HALF + 4) = v1; }
;                     else { sq += ((v0[0] * v0[0] + v0[1] * v0[1]) + (v0[2] * v0[2] + v0[3] * v0[3])) + ((v1[0] * v1[0] + v1[1] * v1[1]) + (v1[2] * v1[2] + v1[3] * v1[3]));
;                         u32x4 w; w.x = pkbf(v0[0], v0[1]); w.y = pkbf(v0[2], v0[3]); w.z = pkbf(v1[0], v1[1]); w.w = pkbf(v1[2], v1[3]); *(u32x4*)(XB + off + bj * HALF) = w; } }
;                 if (!OUT) { sq += __shfl_xor(sq, 16); sq += __shfl_xor(sq, 32); if (fq == 0) ss_add(ssq_out + row, sq); } }
.LBB0_931:
	v_lshl_or_b32 v0, s60, 8, v194
	v_mov_b32_e32 v182, v193
	v_ashrrev_i32_e32 v1, 31, v0
	v_lshlrev_b64 v[212:213], 1, v[0:1]
	v_ashrrev_i32_e32 v183, 31, v182
	v_lshl_add_u64 v[184:185], s[64:65], 0, v[212:213]
	v_lshlrev_b64 v[214:215], 12, v[182:183]
	v_add_u32_e32 v190, 16, v182
	v_lshl_add_u64 v[132:133], v[184:185], 0, v[214:215]
	v_ashrrev_i32_e32 v191, 31, v190
	global_load_dwordx4 v[196:199], v[132:133], off
	global_load_dwordx4 v[200:203], v[132:133], off offset:256
	v_lshlrev_b64 v[132:133], 12, v[190:191]
	v_add_u32_e32 v188, 32, v182
	v_lshl_add_u64 v[132:133], v[184:185], 0, v[132:133]
	v_ashrrev_i32_e32 v189, 31, v188
	global_load_dwordx4 v[152:155], v[132:133], off
	global_load_dwordx4 v[148:151], v[132:133], off offset:256
	v_lshlrev_b64 v[132:133], 12, v[188:189]
	v_add_u32_e32 v186, 48, v182
	v_lshl_add_u64 v[132:133], v[184:185], 0, v[132:133]
	v_ashrrev_i32_e32 v187, 31, v186
	global_load_dwordx4 v[144:147], v[132:133], off
	global_load_dwordx4 v[140:143], v[132:133], off offset:256
	v_lshlrev_b64 v[132:133], 12, v[186:187]
	v_lshl_add_u64 v[132:133], v[184:185], 0, v[132:133]
	global_load_dwordx4 v[136:139], v[132:133], off
	s_nop 0
	global_load_dwordx4 v[132:135], v[132:133], off offset:256
	v_lshl_add_u64 v[180:181], v[182:183], 3, s[8:9]
	global_load_dwordx2 v[216:217], v[180:181], off
	global_load_dwordx2 v[222:223], v[180:181], off offset:128
	global_load_dwordx2 v[224:225], v[180:181], off offset:256
	global_load_dwordx2 v[226:227], v[180:181], off offset:384
	global_load_dwordx2 v[228:229], v[180:181], off offset:1024
	global_load_dwordx2 v[230:231], v[180:181], off offset:1152
	global_load_dwordx2 v[232:233], v[180:181], off offset:1280
	global_load_dwordx2 v[234:235], v[180:181], off offset:1408
	s_flbit_i32_b32 s2, 0
	v_mov_b32_e32 v219, v2
	s_min_u32 s43, s2, 32
	s_sub_i32 s46, 32, s43
	s_waitcnt vmcnt(0)
	v_and_b32_e32 v221, 0xffff0000, v198
	v_mov_b32_e32 v218, v217
	v_lshlrev_b64 v[218:219], s43, v[218:219]
	v_min_u32_e32 v3, 1, v218
	v_or_b32_e32 v3, v219, v3
	v_cvt_f32_u32_e32 v3, v3
	v_cvt_f32_u32_e32 v216, v216
	v_ldexp_f32 v3, v3, s46
	v_fmac_f32_e32 v3, 0x2f800000, v216
	v_fmamk_f32 v3, v3, 0x3a800000, v205
	v_rsq_f32_e32 v216, v3
	s_nop 0
	s_nop 0
	s_nop 0
	s_nop 0
	s_nop 1
	s_nop 1
	s_nop 0
	v_lshlrev_b32_e32 v218, 16, v196
	v_and_b32_e32 v219, 0xffff0000, v196
	v_lshlrev_b32_e32 v196, 16, v197
	v_and_b32_e32 v197, 0xffff0000, v197
	v_lshlrev_b32_e32 v220, 16, v198
	v_lshlrev_b32_e32 v198, 16, v199
	v_and_b32_e32 v199, 0xffff0000, v199
	v_pk_fma_f32 v[130:131], v[130:131], v[216:217], v[196:197] op_sel_hi:[1,0,1]
	v_pk_fma_f32 v[128:129], v[128:129], v[216:217], v[218:219] op_sel_hi:[1,0,1]
	v_pk_fma_f32 v[196:197], v[126:127], v[216:217], v[198:199] op_sel_hi:[1,0,1]
	v_pk_fma_f32 v[126:127], v[124:125], v[216:217], v[220:221] op_sel_hi:[1,0,1]
	v_mul_f32_e32 v3, v129, v129
	v_mul_f32_e32 v124, v131, v131
	v_fmac_f32_e32 v3, v128, v128
	v_fmac_f32_e32 v124, v130, v130
	v_add_f32_e32 v3, v3, v124
	v_mul_f32_e32 v124, v127, v127
	v_mul_f32_e32 v125, v197, v197
	v_fmac_f32_e32 v124, v126, v126
	v_fmac_f32_e32 v125, v196, v196
	v_add_f32_e32 v124, v124, v125
	v_add_f32_e32 v3, v3, v124
	v_cvt_pk_bf16_f32 v124, v128, v129
	v_lshl_add_u64 v[128:129], s[64:65], 0, v[214:215]
	v_cvt_pk_bf16_f32 v125, v130, v131
	v_cvt_pk_bf16_f32 v126, v126, v127
	v_cvt_pk_bf16_f32 v127, v196, v197
	v_lshl_add_u64 v[128:129], v[128:129], 0, v[212:213]
	global_store_dwordx4 v[128:129], v[124:127], off
	v_lshlrev_b32_e32 v130, 16, v202
	v_and_b32_e32 v131, 0xffff0000, v202
	v_lshlrev_b32_e32 v124, 16, v200
	v_and_b32_e32 v125, 0xffff0000, v200
	v_lshlrev_b32_e32 v126, 16, v201
	v_and_b32_e32 v127, 0xffff0000, v201
	v_pk_fma_f32 v[122:123], v[122:123], v[216:217], v[126:127] op_sel_hi:[1,0,1]
	v_pk_fma_f32 v[120:121], v[120:121], v[216:217], v[124:125] op_sel_hi:[1,0,1]
	v_lshlrev_b32_e32 v196, 16, v203
	v_and_b32_e32 v197, 0xffff0000, v203
	v_pk_fma_f32 v[126:127], v[116:117], v[216:217], v[130:131] op_sel_hi:[1,0,1]
	v_mul_f32_e32 v116, v121, v121
	v_mul_f32_e32 v117, v123, v123
	v_pk_fma_f32 v[124:125], v[118:119], v[216:217], v[196:197] op_sel_hi:[1,0,1]
	v_fmac_f32_e32 v116, v120, v120
	v_fmac_f32_e32 v117, v122, v122
	v_add_f32_e32 v116, v116, v117
	v_mul_f32_e32 v117, v127, v127
	v_mul_f32_e32 v118, v125, v125
	v_fmac_f32_e32 v117, v126, v126
	v_fmac_f32_e32 v118, v124, v124
	v_add_f32_e32 v117, v117, v118
	v_add_f32_e32 v116, v116, v117
	v_and_b32_e32 v117, 64, v208
	v_add_f32_e32 v116, v3, v116
	v_xor_b32_e32 v3, 16, v208
	v_add_u32_e32 v117, 64, v117
	v_cmp_lt_i32_e32 vcc, v3, v117
	v_cvt_pk_bf16_f32 v118, v120, v121
	v_cvt_pk_bf16_f32 v119, v122, v123
	v_cndmask_b32_e32 v3, v208, v3, vcc
	v_cvt_pk_bf16_f32 v120, v126, v127
	v_cvt_pk_bf16_f32 v121, v124, v125
	v_lshlrev_b32_e32 v3, 2, v3
	global_store_dwordx4 v[128:129], v[118:121], off offset:256
	ds_bpermute_b32 v118, v3, v116
	s_waitcnt lgkmcnt(0)
	v_add_f32_e32 v116, v116, v118
	v_xor_b32_e32 v118, 32, v208
	v_cmp_lt_i32_e32 vcc, v118, v117
	s_nop 1
	v_cndmask_b32_e32 v117, v208, v118, vcc
	v_lshlrev_b32_e32 v117, 2, v117
	ds_bpermute_b32 v118, v117, v116
	s_and_saveexec_b64 s[2:3], s[40:41]
	s_cbranch_execz .LBB0_933
	s_waitcnt lgkmcnt(0)
	v_add_f32_e32 v116, v116, v118
	v_floor_f32_e32 v118, v116
	v_sub_f32_e32 v116, v116, v118
	v_mul_f32_e32 v116, 0x4f800000, v116
	v_cvt_u32_f32_e32 v119, v118
	v_cvt_u32_f32_e32 v118, v116
	v_lshl_add_u64 v[120:121], v[182:183], 3, s[4:5]
	global_atomic_add_x2 v[120:121], v[118:119], off
; __device__ __forceinline__ void ss_add(ss_t* p, float sq) { const float fl = floorf(sq); const unsigned hi = (unsigned)fl, lo = (unsigned)((sq - fl) * 4294967296.0f); atomicAdd(p, ((ss_t)hi << 32) | (ss_t)lo); }
; __device__ __forceinline__ float ss_get(const ss_t* p) { const ss_t v = *p; return (float)(unsigned)(v >> 32) + (float)(unsigned)v * 2.3283064365386963e-10f; }
; __device__ __forceinline__ unsigned pkbf(float lo, float hi) { typedef float f2_t __attribute__((ext_vector_type(2))); typedef __bf16 b2_t __attribute__((ext_vector_type(2))); f2_t v = {lo, hi}; b2_t b = __builtin_convertvector(v, b2_t); return __builtin_bit_cast(unsigned, b); }
;     __device__ __forceinline__ void operator()(const f32x4 (&acc)[2][2][4][2], const Unit& u, int wr, int wc, int fr, int fq) const {
;     ...
;             for (int m = 0; m < 4; ++m) { const int row = row0 + ai * HALF + m * 16; const size_t off = (size_t)row * ldc + col0;
;                 float rs = 1.0f; if (KS) rs = 1.0f / sqrtf(ss_get(ssb + row) * (1.0f / 1024.f) + 1e-6f);
;                 float sq = 0.f;
; #pragma unroll
;                 for (int bj = 0; bj < 2; ++bj) { const u32x4 r = res[m][bj];
;                     const f32x4 x0 = (f32x4){__uint_as_float(r.x << 16), __uint_as_float(r.x & 0xffff0000u), __uint_as_float(r.y << 16), __uint_as_float(r.y & 0xffff0000u)};
;                     const f32x4 x1 = (f32x4){__uint_as_float(r.z << 16), __uint_as_float(r.z & 0xffff0000u), __uint_as_float(r.w << 16), __uint_as_float(r.w & 0xffff0000u)};
;                     const f32x4 v0 = x0 + acc[ai][bj][m][0] * rs, v1 = x1 + acc[ai][bj][m][1] * rs;
;                     if (OUT) { *(f32x4*)(OUT + off + bj * HALF) = v0; *(f32x4*)(OUT + off + bj * HALF + 4) = v1; }
;                     else { sq += ((v0[0] * v0[0] + v0[1] * v0[1]) + (v0[2] * v0[2] + v0[3] * v0[3])) + ((v1[0] * v1[0] + v1[1] * v1[1]) + (v1[2] * v1[2] + v1[3] * v1[3]));
;                         u32x4 w; w.x = pkbf(v0[0], v0[1]); w.y = pkbf(v0[2], v0[3]); w.z = pkbf(v1[0], v1[1]); w.w = pkbf(v1[2], v1[3]); *(u32x4*)(XB + off + bj * HALF) = w; } }
;                 if (!OUT) { sq += __shfl_xor(sq, 16); sq += __shfl_xor(sq, 32); if (fq == 0) ss_add(ssq_out + row, sq); } }
.LBB0_933:
	s_or_b64 exec, exec, s[2:3]
	s_nop 1
	v_mov_b32_e32 v120, v222
	v_mov_b32_e32 v121, v223
	v_mov_b32_e32 v123, v2
	v_lshlrev_b32_e32 v126, 16, v155
	v_and_b32_e32 v127, 0xffff0000, v155
	v_and_b32_e32 v125, 0xffff0000, v154
	s_waitcnt lgkmcnt(0)
	v_lshlrev_b64 v[118:119], 11, v[190:191]
	v_mov_b32_e32 v122, v121
	v_lshlrev_b64 v[122:123], s43, v[122:123]
	v_min_u32_e32 v116, 1, v122
	v_or_b32_e32 v116, v123, v116
	v_cvt_f32_u32_e32 v116, v116
	v_cvt_f32_u32_e32 v120, v120
	v_ldexp_f32 v116, v116, s46
	v_fmac_f32_e32 v116, 0x2f800000, v120
	v_fmamk_f32 v116, v116, 0x3a800000, v205
	v_rsq_f32_e32 v116, v116
	s_nop 0
	s_nop 0
	s_nop 0
	s_nop 0
	s_nop 1
	s_nop 1
	s_nop 0
	v_lshlrev_b32_e32 v120, 16, v152
	v_and_b32_e32 v121, 0xffff0000, v152
	v_lshlrev_b32_e32 v122, 16, v153
	v_and_b32_e32 v123, 0xffff0000, v153
	v_pk_fma_f32 v[114:115], v[114:115], v[116:117], v[122:123] op_sel_hi:[1,0,1]
	v_pk_fma_f32 v[112:113], v[112:113], v[116:117], v[120:121] op_sel_hi:[1,0,1]
	v_lshlrev_b32_e32 v124, 16, v154
	v_pk_fma_f32 v[120:121], v[110:111], v[116:117], v[126:127] op_sel_hi:[1,0,1]
	v_mul_f32_e32 v110, v113, v113
	v_mul_f32_e32 v111, v115, v115
	v_pk_fma_f32 v[108:109], v[108:109], v[116:117], v[124:125] op_sel_hi:[1,0,1]
	v_fmac_f32_e32 v110, v112, v112
	v_fmac_f32_e32 v111, v114, v114
	v_add_f32_e32 v110, v110, v111
	v_mul_f32_e32 v111, v109, v109
	v_mul_f32_e32 v122, v121, v121
	v_fmac_f32_e32 v111, v108, v108
	v_fmac_f32_e32 v122, v120, v120
	v_add_f32_e32 v111, v111, v122
	v_add_f32_e32 v122, v110, v111
	v_cvt_pk_bf16_f32 v110, v112, v113
	v_cvt_pk_bf16_f32 v112, v108, v109
	v_lshl_add_u64 v[108:109], v[118:119], 1, s[64:65]
	v_cvt_pk_bf16_f32 v111, v114, v115
	v_cvt_pk_bf16_f32 v113, v120, v121
	v_lshl_add_u64 v[108:109], v[0:1], 1, v[108:109]
	global_store_dwordx4 v[108:109], v[110:113], off
	v_lshlrev_b32_e32 v114, 16, v150
	v_and_b32_e32 v115, 0xffff0000, v150
	v_lshlrev_b32_e32 v110, 16, v148
	v_and_b32_e32 v111, 0xffff0000, v148
	v_lshlrev_b32_e32 v112, 16, v149
	v_and_b32_e32 v113, 0xffff0000, v149
	v_lshlrev_b32_e32 v118, 16, v151
	v_and_b32_e32 v119, 0xffff0000, v151
	v_pk_fma_f32 v[106:107], v[106:107], v[116:117], v[112:113] op_sel_hi:[1,0,1]
	v_pk_fma_f32 v[104:105], v[104:105], v[116:117], v[110:111] op_sel_hi:[1,0,1]
	v_pk_fma_f32 v[110:111], v[102:103], v[116:117], v[118:119] op_sel_hi:[1,0,1]
	v_pk_fma_f32 v[102:103], v[100:101], v[116:117], v[114:115] op_sel_hi:[1,0,1]
	v_mul_f32_e32 v100, v105, v105
	v_mul_f32_e32 v101, v107, v107
	v_fmac_f32_e32 v100, v104, v104
	v_fmac_f32_e32 v101, v106, v106
	v_add_f32_e32 v100, v100, v101
	v_mul_f32_e32 v101, v103, v103
	v_mul_f32_e32 v112, v111, v111
	v_fmac_f32_e32 v101, v102, v102
	v_fmac_f32_e32 v112, v110, v110
	v_add_f32_e32 v101, v101, v112
	v_add_f32_e32 v100, v100, v101
	v_add_f32_e32 v112, v122, v100
	v_cvt_pk_bf16_f32 v100, v104, v105
	v_cvt_pk_bf16_f32 v101, v106, v107
	v_cvt_pk_bf16_f32 v102, v102, v103
	v_cvt_pk_bf16_f32 v103, v110, v111
	global_store_dwordx4 v[108:109], v[100:103], off offset:256
	ds_bpermute_b32 v100, v3, v112
	s_waitcnt lgkmcnt(0)
	v_add_f32_e32 v100, v112, v100
	ds_bpermute_b32 v101, v117, v100
	s_and_saveexec_b64 s[2:3], s[40:41]
	s_cbranch_execz .LBB0_935
	s_waitcnt lgkmcnt(0)
	v_add_f32_e32 v102, v100, v101
	v_floor_f32_e32 v104, v102
	v_sub_f32_e32 v102, v102, v104
	v_mul_f32_e32 v102, 0x4f800000, v102
	v_cvt_u32_f32_e32 v103, v104
	v_cvt_u32_f32_e32 v102, v102
	v_lshl_add_u64 v[100:101], v[190:191], 3, s[4:5]
	global_atomic_add_x2 v[100:101], v[102:103], off
.LBB0_935:
	s_or_b64 exec, exec, s[2:3]
	s_waitcnt lgkmcnt(0)
	s_nop 1
	v_mov_b32_e32 v100, v224
	v_mov_b32_e32 v101, v225
	v_mov_b32_e32 v105, v2
	v_lshlrev_b32_e32 v110, 16, v147
	v_and_b32_e32 v111, 0xffff0000, v147
	v_lshlrev_b32_e32 v108, 16, v146
	v_and_b32_e32 v109, 0xffff0000, v146
	v_lshlrev_b64 v[102:103], 11, v[188:189]
	v_mov_b32_e32 v104, v101
	v_lshlrev_b64 v[104:105], s43, v[104:105]
	v_min_u32_e32 v101, 1, v104
	v_or_b32_e32 v101, v105, v101
	v_cvt_f32_u32_e32 v101, v101
	v_cvt_f32_u32_e32 v100, v100
	v_ldexp_f32 v101, v101, s46
	v_fmac_f32_e32 v101, 0x2f800000, v100
	v_fmamk_f32 v100, v101, 0x3a800000, v205
	v_rsq_f32_e32 v100, v100
	s_nop 0
	s_nop 0
	s_nop 0
	s_nop 0
	s_nop 1
	s_nop 1
	s_nop 0
	v_lshlrev_b32_e32 v104, 16, v144
	v_and_b32_e32 v105, 0xffff0000, v144
	v_lshlrev_b32_e32 v106, 16, v145
	v_and_b32_e32 v107, 0xffff0000, v145
	v_pk_fma_f32 v[98:99], v[98:99], v[100:101], v[106:107] op_sel_hi:[1,0,1]
	v_pk_fma_f32 v[96:97], v[96:97], v[100:101], v[104:105] op_sel_hi:[1,0,1]
	v_pk_fma_f32 v[104:105], v[94:95], v[100:101], v[110:111] op_sel_hi:[1,0,1]
	v_mul_f32_e32 v94, v97, v97
	v_mul_f32_e32 v95, v99, v99
	v_pk_fma_f32 v[92:93], v[92:93], v[100:101], v[108:109] op_sel_hi:[1,0,1]
	v_fmac_f32_e32 v94, v96, v96
	v_fmac_f32_e32 v95, v98, v98
	v_add_f32_e32 v94, v94, v95
	v_mul_f32_e32 v95, v93, v93
	v_mul_f32_e32 v101, v105, v105
	v_fmac_f32_e32 v95, v92, v92
	v_fmac_f32_e32 v101, v104, v104
	v_add_f32_e32 v95, v95, v101
	v_add_f32_e32 v101, v94, v95
	v_cvt_pk_bf16_f32 v94, v96, v97
	v_cvt_pk_bf16_f32 v96, v92, v93
	v_lshl_add_u64 v[92:93], v[102:103], 1, s[64:65]
	v_cvt_pk_bf16_f32 v95, v98, v99
	v_cvt_pk_bf16_f32 v97, v104, v105
	v_lshl_add_u64 v[92:93], v[0:1], 1, v[92:93]
	global_store_dwordx4 v[92:93], v[94:97], off
	v_lshlrev_b32_e32 v98, 16, v142
	v_and_b32_e32 v99, 0xffff0000, v142
	v_lshlrev_b32_e32 v94, 16, v140
	v_and_b32_e32 v95, 0xffff0000, v140
	v_lshlrev_b32_e32 v96, 16, v141
	v_and_b32_e32 v97, 0xffff0000, v141
	v_lshlrev_b32_e32 v102, 16, v143
	v_and_b32_e32 v103, 0xffff0000, v143
	v_pk_fma_f32 v[90:91], v[90:91], v[100:101], v[96:97] op_sel_hi:[1,0,1]
	v_pk_fma_f32 v[88:89], v[88:89], v[100:101], v[94:95] op_sel_hi:[1,0,1]
	v_pk_fma_f32 v[94:95], v[86:87], v[100:101], v[102:103] op_sel_hi:[1,0,1]
	v_pk_fma_f32 v[86:87], v[84:85], v[100:101], v[98:99] op_sel_hi:[1,0,1]
	v_mul_f32_e32 v84, v89, v89
	v_mul_f32_e32 v85, v91, v91
	v_fmac_f32_e32 v84, v88, v88
	v_fmac_f32_e32 v85, v90, v90
	v_add_f32_e32 v84, v84, v85
	v_mul_f32_e32 v85, v87, v87
	v_mul_f32_e32 v96, v95, v95
	v_fmac_f32_e32 v85, v86, v86
	v_fmac_f32_e32 v96, v94, v94
	v_add_f32_e32 v85, v85, v96
	v_add_f32_e32 v84, v84, v85
	v_add_f32_e32 v96, v101, v84
	v_cvt_pk_bf16_f32 v84, v88, v89
	v_cvt_pk_bf16_f32 v85, v90, v91
	v_cvt_pk_bf16_f32 v86, v86, v87
	v_cvt_pk_bf16_f32 v87, v94, v95
	global_store_dwordx4 v[92:93], v[84:87], off offset:256
	ds_bpermute_b32 v84, v3, v96
	s_waitcnt lgkmcnt(0)
	v_add_f32_e32 v84, v96, v84
	ds_bpermute_b32 v85, v117, v84
	s_and_saveexec_b64 s[2:3], s[40:41]
	s_cbranch_execz .LBB0_937
	s_waitcnt lgkmcnt(0)
	v_add_f32_e32 v86, v84, v85
	v_floor_f32_e32 v88, v86
	v_sub_f32_e32 v86, v86, v88
	v_mul_f32_e32 v86, 0x4f800000, v86
	v_cvt_u32_f32_e32 v87, v88
	v_cvt_u32_f32_e32 v86, v86
	v_lshl_add_u64 v[84:85], v[188:189], 3, s[4:5]
	global_atomic_add_x2 v[84:85], v[86:87], off
; __device__ __forceinline__ void ss_add(ss_t* p, float sq) { const float fl = floorf(sq); const unsigned hi = (unsigned)fl, lo = (unsigned)((sq - fl) * 4294967296.0f); atomicAdd(p, ((ss_t)hi << 32) | (ss_t)lo); }
; __device__ __forceinline__ float ss_get(const ss_t* p) { const ss_t v = *p; return (float)(unsigned)(v >> 32) + (float)(unsigned)v * 2.3283064365386963e-10f; }
;     __device__ __forceinline__ void operator()(const f32x4 (&acc)[2][2][4][2], const Unit& u, int wr, int wc, int fr, int fq) const {
;     ...
;             for (int m = 0; m < 4; ++m) { const bf16_t* rowp = XB + (size_t)(row0 + ai * HALF + m * 16) * ldc + col0;
; #pragma unroll
;                 for (int bj = 0; bj < 2; ++bj) res[m][bj] = *(const u32x4*)(rowp + bj * HALF); }
;             asm volatile("" ::: "memory");
; #pragma unroll
;             for (int m = 0; m < 4; ++m) { const int row = row0 + ai * HALF + m * 16; const size_t off = (size_t)row * ldc + col0;
;                 float rs = 1.0f; if (KS) rs = 1.0f / sqrtf(ss_get(ssb + row) * (1.0f / 1024.f) + 1e-6f);
;                 float sq = 0.f;
; #pragma unroll
;                 for (int bj = 0; bj < 2; ++bj) { const u32x4 r = res[m][bj];
;                     const f32x4 x0 = (f32x4){__uint_as_float(r.x << 16), __uint_as_float(r.x & 0xffff0000u), __uint_as_float(r.y << 16), __uint_as_float(r.y & 0xffff0000u)};
;                     const f32x4 x1 = (f32x4){__uint_as_float(r.z << 16), __uint_as_float(r.z & 0xffff0000u), __uint_as_float(r.w << 16), __uint_as_float(r.w & 0xffff0000u)};
;                     const f32x4 v0 = x0 + acc[ai][bj][m][0] * rs, v1 = x1 + acc[ai][bj][m][1] * rs;
;                     if (OUT) { *(f32x4*)(OUT + off + bj * HALF) = v0; *(f32x4*)(OUT + off + bj * HALF + 4) = v1; }
;                     else { sq += ((v0[0] * v0[0] + v0[1] * v0[1]) + (v0[2] * v0[2] + v0[3] * v0[3])) + ((v1[0] * v1[0] + v1[1] * v1[1]) + (v1[2] * v1[2] + v1[3] * v1[3]));
;                         u32x4 w; w.x = pkbf(v0[0], v0[1]); w.y = pkbf(v0[2], v0[3]); w.z = pkbf(v1[0], v1[1]); w.w = pkbf(v1[2], v1[3]); *(u32x4*)(XB + off + bj * HALF) = w; } }
;                 if (!OUT) { sq += __shfl_xor(sq, 16); sq += __shfl_xor(sq, 32); if (fq == 0) ss_add(ssq_out + row, sq); } }
.LBB0_937:
	s_or_b64 exec, exec, s[2:3]
	s_waitcnt lgkmcnt(0)
	s_nop 1
	v_mov_b32_e32 v84, v226
	v_mov_b32_e32 v85, v227
	v_mov_b32_e32 v89, v2
	v_lshlrev_b32_e32 v94, 16, v139
	v_and_b32_e32 v95, 0xffff0000, v139
	v_lshlrev_b32_e32 v92, 16, v138
	v_and_b32_e32 v93, 0xffff0000, v138
	v_lshlrev_b64 v[86:87], 11, v[186:187]
	v_mov_b32_e32 v88, v85
	v_lshlrev_b64 v[88:89], s43, v[88:89]
	v_min_u32_e32 v85, 1, v88
	v_or_b32_e32 v85, v89, v85
	v_cvt_f32_u32_e32 v85, v85
	v_cvt_f32_u32_e32 v84, v84
	v_ldexp_f32 v85, v85, s46
	v_fmac_f32_e32 v85, 0x2f800000, v84
	v_fmamk_f32 v84, v85, 0x3a800000, v205
	v_rsq_f32_e32 v84, v84
	s_nop 0
	s_nop 0
	s_nop 0
	s_nop 0
	s_nop 1
	s_nop 1
	s_nop 0
	v_lshlrev_b32_e32 v88, 16, v136
	v_and_b32_e32 v89, 0xffff0000, v136
	v_lshlrev_b32_e32 v90, 16, v137
	v_and_b32_e32 v91, 0xffff0000, v137
	v_pk_fma_f32 v[82:83], v[82:83], v[84:85], v[90:91] op_sel_hi:[1,0,1]
	v_pk_fma_f32 v[80:81], v[80:81], v[84:85], v[88:89] op_sel_hi:[1,0,1]
	v_pk_fma_f32 v[88:89], v[78:79], v[84:85], v[94:95] op_sel_hi:[1,0,1]
	v_mul_f32_e32 v78, v81, v81
	v_mul_f32_e32 v79, v83, v83
	v_pk_fma_f32 v[76:77], v[76:77], v[84:85], v[92:93] op_sel_hi:[1,0,1]
	v_fmac_f32_e32 v78, v80, v80
	v_fmac_f32_e32 v79, v82, v82
	v_add_f32_e32 v78, v78, v79
	v_mul_f32_e32 v79, v77, v77
	v_mul_f32_e32 v85, v89, v89
	v_fmac_f32_e32 v79, v76, v76
	v_fmac_f32_e32 v85, v88, v88
	v_add_f32_e32 v79, v79, v85
	v_add_f32_e32 v85, v78, v79
	v_cvt_pk_bf16_f32 v78, v80, v81
	v_cvt_pk_bf16_f32 v80, v76, v77
	v_lshl_add_u64 v[76:77], v[86:87], 1, s[64:65]
	v_cvt_pk_bf16_f32 v79, v82, v83
	v_cvt_pk_bf16_f32 v81, v88, v89
	v_lshl_add_u64 v[76:77], v[0:1], 1, v[76:77]
	global_store_dwordx4 v[76:77], v[78:81], off
	v_lshlrev_b32_e32 v82, 16, v134
	v_and_b32_e32 v83, 0xffff0000, v134
	v_lshlrev_b32_e32 v78, 16, v132
	v_and_b32_e32 v79, 0xffff0000, v132
	v_lshlrev_b32_e32 v80, 16, v133
	v_and_b32_e32 v81, 0xffff0000, v133
	v_lshlrev_b32_e32 v86, 16, v135
	v_and_b32_e32 v87, 0xffff0000, v135
	v_pk_fma_f32 v[74:75], v[74:75], v[84:85], v[80:81] op_sel_hi:[1,0,1]
	v_pk_fma_f32 v[72:73], v[72:73], v[84:85], v[78:79] op_sel_hi:[1,0,1]
	v_pk_fma_f32 v[78:79], v[70:71], v[84:85], v[86:87] op_sel_hi:[1,0,1]
	v_pk_fma_f32 v[70:71], v[68:69], v[84:85], v[82:83] op_sel_hi:[1,0,1]
	v_mul_f32_e32 v68, v73, v73
	v_mul_f32_e32 v69, v75, v75
	v_fmac_f32_e32 v68, v72, v72
	v_fmac_f32_e32 v69, v74, v74
	v_add_f32_e32 v68, v68, v69
	v_mul_f32_e32 v69, v71, v71
	v_mul_f32_e32 v80, v79, v79
	v_fmac_f32_e32 v69, v70, v70
	v_fmac_f32_e32 v80, v78, v78
	v_add_f32_e32 v69, v69, v80
	v_add_f32_e32 v68, v68, v69
	v_add_f32_e32 v80, v85, v68
	v_cvt_pk_bf16_f32 v68, v72, v73
	v_cvt_pk_bf16_f32 v69, v74, v75
	v_cvt_pk_bf16_f32 v70, v70, v71
	v_cvt_pk_bf16_f32 v71, v78, v79
	global_store_dwordx4 v[76:77], v[68:71], off offset:256
	ds_bpermute_b32 v68, v3, v80
	s_waitcnt lgkmcnt(0)
	v_add_f32_e32 v68, v80, v68
	ds_bpermute_b32 v69, v117, v68
	s_and_saveexec_b64 s[2:3], s[40:41]
	s_cbranch_execz .LBB0_939
	s_waitcnt lgkmcnt(0)
	v_add_f32_e32 v70, v68, v69
	v_floor_f32_e32 v72, v70
	v_sub_f32_e32 v70, v70, v72
	v_mul_f32_e32 v70, 0x4f800000, v70
	v_cvt_u32_f32_e32 v71, v72
	v_cvt_u32_f32_e32 v70, v70
	v_lshl_add_u64 v[68:69], v[186:187], 3, s[4:5]
	global_atomic_add_x2 v[68:69], v[70:71], off
.LBB0_939:
	s_or_b64 exec, exec, s[2:3]
	v_add_u32_e32 v102, 0x80, v182
	v_ashrrev_i32_e32 v103, 31, v102
	v_lshlrev_b64 v[110:111], 12, v[102:103]
	v_add_u32_e32 v100, 0x90, v182
	s_waitcnt lgkmcnt(0)
	v_lshl_add_u64 v[68:69], v[184:185], 0, v[110:111]
	v_ashrrev_i32_e32 v101, 31, v100
	global_load_dwordx4 v[106:109], v[68:69], off
	global_load_dwordx4 v[92:95], v[68:69], off offset:256
	v_lshlrev_b64 v[68:69], 12, v[100:101]
	v_add_u32_e32 v98, 0xa0, v182
	v_lshl_add_u64 v[68:69], v[184:185], 0, v[68:69]
	v_ashrrev_i32_e32 v99, 31, v98
	global_load_dwordx4 v[88:91], v[68:69], off
	global_load_dwordx4 v[84:87], v[68:69], off offset:256
	v_lshlrev_b64 v[68:69], 12, v[98:99]
	v_add_u32_e32 v96, 0xb0, v182
	v_lshl_add_u64 v[68:69], v[184:185], 0, v[68:69]
	v_ashrrev_i32_e32 v97, 31, v96
	global_load_dwordx4 v[80:83], v[68:69], off
	global_load_dwordx4 v[76:79], v[68:69], off offset:256
	v_lshlrev_b64 v[68:69], 12, v[96:97]
	v_lshl_add_u64 v[68:69], v[184:185], 0, v[68:69]
	global_load_dwordx4 v[72:75], v[68:69], off
	s_nop 0
	global_load_dwordx4 v[68:71], v[68:69], off offset:256
	s_nop 1
	v_mov_b32_e32 v104, v228
	v_mov_b32_e32 v105, v229
	v_mov_b32_e32 v113, v2
	s_waitcnt vmcnt(0)
; __device__ __forceinline__ void ss_add(ss_t* p, float sq) { const float fl = floorf(sq); const unsigned hi = (unsigned)fl, lo = (unsigned)((sq - fl) * 4294967296.0f); atomicAdd(p, ((ss_t)hi << 32) | (ss_t)lo); }
; __device__ __forceinline__ float ss_get(const ss_t* p) { const ss_t v = *p; return (float)(unsigned)(v >> 32) + (float)(unsigned)v * 2.3283064365386963e-10f; }
; __device__ __forceinline__ unsigned pkbf(float lo, float hi) { typedef float f2_t __attribute__((ext_vector_type(2))); typedef __bf16 b2_t __attribute__((ext_vector_type(2))); f2_t v = {lo, hi}; b2_t b = __builtin_convertvector(v, b2_t); return __builtin_bit_cast(unsigned, b); }
;     __device__ __forceinline__ void operator()(const f32x4 (&acc)[2][2][4][2], const Unit& u, int wr, int wc, int fr, int fq) const {
;     ...
;             for (int m = 0; m < 4; ++m) { const int row = row0 + ai * HALF + m * 16; const size_t off = (size_t)row * ldc + col0;
;                 float rs = 1.0f; if (KS) rs = 1.0f / sqrtf(ss_get(ssb + row) * (1.0f / 1024.f) + 1e-6f);
;                 float sq = 0.f;
; #pragma unroll
;                 for (int bj = 0; bj < 2; ++bj) { const u32x4 r = res[m][bj];
;                     const f32x4 x0 = (f32x4){__uint_as_float(r.x << 16), __uint_as_float(r.x & 0xffff0000u), __uint_as_float(r.y << 16), __uint_as_float(r.y & 0xffff0000u)};
;                     const f32x4 x1 = (f32x4){__uint_as_float(r.z << 16), __uint_as_float(r.z & 0xffff0000u), __uint_as_float(r.w << 16), __uint_as_float(r.w & 0xffff0000u)};
;                     const f32x4 v0 = x0 + acc[ai][bj][m][0] * rs, v1 = x1 + acc[ai][bj][m][1] * rs;
;                     if (OUT) { *(f32x4*)(OUT + off + bj * HALF) = v0; *(f32x4*)(OUT + off + bj * HALF + 4) = v1; }
;                     else { sq += ((v0[0] * v0[0] + v0[1] * v0[1]) + (v0[2] * v0[2] + v0[3] * v0[3])) + ((v1[0] * v1[0] + v1[1] * v1[1]) + (v1[2] * v1[2] + v1[3] * v1[3]));
;                         u32x4 w; w.x = pkbf(v0[0], v0[1]); w.y = pkbf(v0[2], v0[3]); w.z = pkbf(v1[0], v1[1]); w.w = pkbf(v1[2], v1[3]); *(u32x4*)(XB + off + bj * HALF) = w; } }
;                 if (!OUT) { sq += __shfl_xor(sq, 16); sq += __shfl_xor(sq, 32); if (fq == 0) ss_add(ssq_out + row, sq); } }
	v_mov_b32_e32 v112, v105
	v_lshlrev_b64 v[112:113], s43, v[112:113]
	v_min_u32_e32 v105, 1, v112
	v_or_b32_e32 v105, v113, v105
	v_cvt_f32_u32_e32 v105, v105
	v_cvt_f32_u32_e32 v104, v104
	v_ldexp_f32 v105, v105, s46
	v_fmac_f32_e32 v105, 0x2f800000, v104
	v_fmamk_f32 v104, v105, 0x3a800000, v205
	v_rsq_f32_e32 v104, v104
	s_nop 0
	s_nop 0
	s_nop 0
	s_nop 0
	s_nop 1
	s_nop 1
	s_nop 0
	v_lshlrev_b32_e32 v112, 16, v106
	v_and_b32_e32 v113, 0xffff0000, v106
	v_lshlrev_b32_e32 v106, 16, v107
	v_and_b32_e32 v107, 0xffff0000, v107
	v_lshlrev_b32_e32 v114, 16, v108
	v_and_b32_e32 v115, 0xffff0000, v108
	v_lshlrev_b32_e32 v108, 16, v109
	v_and_b32_e32 v109, 0xffff0000, v109
	v_pk_fma_f32 v[66:67], v[66:67], v[104:105], v[106:107] op_sel_hi:[1,0,1]
	v_pk_fma_f32 v[64:65], v[64:65], v[104:105], v[112:113] op_sel_hi:[1,0,1]
	v_pk_fma_f32 v[106:107], v[62:63], v[104:105], v[108:109] op_sel_hi:[1,0,1]
	v_mul_f32_e32 v62, v65, v65
	v_mul_f32_e32 v63, v67, v67
	v_pk_fma_f32 v[60:61], v[60:61], v[104:105], v[114:115] op_sel_hi:[1,0,1]
	v_fmac_f32_e32 v62, v64, v64
	v_fmac_f32_e32 v63, v66, v66
	v_add_f32_e32 v62, v62, v63
	v_mul_f32_e32 v63, v61, v61
	v_mul_f32_e32 v105, v107, v107
	v_fmac_f32_e32 v63, v60, v60
	v_fmac_f32_e32 v105, v106, v106
	v_add_f32_e32 v63, v63, v105
	v_add_f32_e32 v105, v62, v63
	v_cvt_pk_bf16_f32 v62, v64, v65
	v_cvt_pk_bf16_f32 v64, v60, v61
	v_lshl_add_u64 v[60:61], s[64:65], 0, v[110:111]
	v_cvt_pk_bf16_f32 v63, v66, v67
	v_cvt_pk_bf16_f32 v65, v106, v107
	v_lshl_add_u64 v[60:61], v[0:1], 1, v[60:61]
	global_store_dwordx4 v[60:61], v[62:65], off
	v_lshlrev_b32_e32 v66, 16, v94
	v_and_b32_e32 v67, 0xffff0000, v94
	v_lshlrev_b32_e32 v62, 16, v92
	v_and_b32_e32 v63, 0xffff0000, v92
	v_lshlrev_b32_e32 v64, 16, v93
	v_and_b32_e32 v65, 0xffff0000, v93
	v_lshlrev_b32_e32 v92, 16, v95
	v_and_b32_e32 v93, 0xffff0000, v95
	v_pk_fma_f32 v[58:59], v[58:59], v[104:105], v[64:65] op_sel_hi:[1,0,1]
	v_pk_fma_f32 v[56:57], v[56:57], v[104:105], v[62:63] op_sel_hi:[1,0,1]
	v_pk_fma_f32 v[62:63], v[54:55], v[104:105], v[92:93] op_sel_hi:[1,0,1]
	v_pk_fma_f32 v[54:55], v[52:53], v[104:105], v[66:67] op_sel_hi:[1,0,1]
	v_mul_f32_e32 v52, v57, v57
	v_mul_f32_e32 v53, v59, v59
	v_fmac_f32_e32 v52, v56, v56
	v_fmac_f32_e32 v53, v58, v58
	v_add_f32_e32 v52, v52, v53
	v_mul_f32_e32 v53, v55, v55
	v_mul_f32_e32 v64, v63, v63
	v_fmac_f32_e32 v53, v54, v54
	v_fmac_f32_e32 v64, v62, v62
	v_add_f32_e32 v53, v53, v64
	v_add_f32_e32 v52, v52, v53
	v_add_f32_e32 v64, v105, v52
	v_cvt_pk_bf16_f32 v52, v56, v57
	v_cvt_pk_bf16_f32 v53, v58, v59
	v_cvt_pk_bf16_f32 v54, v54, v55
	v_cvt_pk_bf16_f32 v55, v62, v63
	global_store_dwordx4 v[60:61], v[52:55], off offset:256
	ds_bpermute_b32 v52, v3, v64
	s_waitcnt lgkmcnt(0)
	v_add_f32_e32 v52, v64, v52
	ds_bpermute_b32 v53, v117, v52
	s_and_saveexec_b64 s[2:3], s[40:41]
	s_cbranch_execz .LBB0_941
	s_waitcnt lgkmcnt(0)
	v_add_f32_e32 v54, v52, v53
	v_floor_f32_e32 v56, v54
	v_sub_f32_e32 v54, v54, v56
	v_mul_f32_e32 v54, 0x4f800000, v54
	v_cvt_u32_f32_e32 v55, v56
	v_cvt_u32_f32_e32 v54, v54
	v_lshl_add_u64 v[52:53], v[102:103], 3, s[4:5]
	global_atomic_add_x2 v[52:53], v[54:55], off
.LBB0_941:
	s_or_b64 exec, exec, s[2:3]
	s_waitcnt lgkmcnt(0)
	s_nop 1
	v_mov_b32_e32 v52, v230
	v_mov_b32_e32 v53, v231
	v_mov_b32_e32 v57, v2
	v_lshlrev_b32_e32 v62, 16, v91
	v_and_b32_e32 v63, 0xffff0000, v91
	v_lshlrev_b32_e32 v60, 16, v90
	v_and_b32_e32 v61, 0xffff0000, v90
	v_lshlrev_b64 v[54:55], 11, v[100:101]
	v_mov_b32_e32 v56, v53
	v_lshlrev_b64 v[56:57], s43, v[56:57]
	v_min_u32_e32 v53, 1, v56
	v_or_b32_e32 v53, v57, v53
	v_cvt_f32_u32_e32 v53, v53
	v_cvt_f32_u32_e32 v52, v52
	v_ldexp_f32 v53, v53, s46
	v_fmac_f32_e32 v53, 0x2f800000, v52
	v_fmamk_f32 v52, v53, 0x3a800000, v205
	v_rsq_f32_e32 v52, v52
	s_nop 0
	s_nop 0
	s_nop 0
	s_nop 0
	s_nop 1
	s_nop 1
	s_nop 0
	v_lshlrev_b32_e32 v56, 16, v88
	v_and_b32_e32 v57, 0xffff0000, v88
	v_lshlrev_b32_e32 v58, 16, v89
	v_and_b32_e32 v59, 0xffff0000, v89
	v_pk_fma_f32 v[50:51], v[50:51], v[52:53], v[58:59] op_sel_hi:[1,0,1]
	v_pk_fma_f32 v[48:49], v[48:49], v[52:53], v[56:57] op_sel_hi:[1,0,1]
	v_pk_fma_f32 v[56:57], v[46:47], v[52:53], v[62:63] op_sel_hi:[1,0,1]
	v_mul_f32_e32 v46, v49, v49
	v_mul_f32_e32 v47, v51, v51
	v_pk_fma_f32 v[44:45], v[44:45], v[52:53], v[60:61] op_sel_hi:[1,0,1]
	v_fmac_f32_e32 v46, v48, v48
	v_fmac_f32_e32 v47, v50, v50
	v_add_f32_e32 v46, v46, v47
	v_mul_f32_e32 v47, v45, v45
	v_mul_f32_e32 v53, v57, v57
	v_fmac_f32_e32 v47, v44, v44
	v_fmac_f32_e32 v53, v56, v56
	v_add_f32_e32 v47, v47, v53
	v_add_f32_e32 v53, v46, v47
	v_cvt_pk_bf16_f32 v46, v48, v49
	v_cvt_pk_bf16_f32 v48, v44, v45
	v_lshl_add_u64 v[44:45], v[54:55], 1, s[64:65]
	v_cvt_pk_bf16_f32 v47, v50, v51
	v_cvt_pk_bf16_f32 v49, v56, v57
	v_lshl_add_u64 v[44:45], v[0:1], 1, v[44:45]
	global_store_dwordx4 v[44:45], v[46:49], off
	v_lshlrev_b32_e32 v50, 16, v86
	v_and_b32_e32 v51, 0xffff0000, v86
	v_lshlrev_b32_e32 v46, 16, v84
	v_and_b32_e32 v47, 0xffff0000, v84
	v_lshlrev_b32_e32 v48, 16, v85
	v_and_b32_e32 v49, 0xffff0000, v85
	v_lshlrev_b32_e32 v54, 16, v87
	v_and_b32_e32 v55, 0xffff0000, v87
	v_pk_fma_f32 v[42:43], v[42:43], v[52:53], v[48:49] op_sel_hi:[1,0,1]
	v_pk_fma_f32 v[40:41], v[40:41], v[52:53], v[46:47] op_sel_hi:[1,0,1]
	v_pk_fma_f32 v[46:47], v[38:39], v[52:53], v[54:55] op_sel_hi:[1,0,1]
	v_pk_fma_f32 v[38:39], v[36:37], v[52:53], v[50:51] op_sel_hi:[1,0,1]
	v_mul_f32_e32 v36, v41, v41
	v_mul_f32_e32 v37, v43, v43
	v_fmac_f32_e32 v36, v40, v40
	v_fmac_f32_e32 v37, v42, v42
	v_add_f32_e32 v36, v36, v37
	v_mul_f32_e32 v37, v39, v39
	v_mul_f32_e32 v48, v47, v47
	v_fmac_f32_e32 v37, v38, v38
	v_fmac_f32_e32 v48, v46, v46
	v_add_f32_e32 v37, v37, v48
	v_add_f32_e32 v36, v36, v37
	v_add_f32_e32 v48, v53, v36
	v_cvt_pk_bf16_f32 v36, v40, v41
	v_cvt_pk_bf16_f32 v37, v42, v43
	v_cvt_pk_bf16_f32 v38, v38, v39
	v_cvt_pk_bf16_f32 v39, v46, v47
	global_store_dwordx4 v[44:45], v[36:39], off offset:256
	ds_bpermute_b32 v36, v3, v48
	s_waitcnt lgkmcnt(0)
	v_add_f32_e32 v36, v48, v36
	ds_bpermute_b32 v37, v117, v36
	s_and_saveexec_b64 s[2:3], s[40:41]
	s_cbranch_execz .LBB0_943
	s_waitcnt lgkmcnt(0)
	v_add_f32_e32 v38, v36, v37
	v_floor_f32_e32 v40, v38
	v_sub_f32_e32 v38, v38, v40
	v_mul_f32_e32 v38, 0x4f800000, v38
	v_cvt_u32_f32_e32 v39, v40
	v_cvt_u32_f32_e32 v38, v38
	v_lshl_add_u64 v[36:37], v[100:101], 3, s[4:5]
	global_atomic_add_x2 v[36:37], v[38:39], off
; __device__ __forceinline__ void ss_add(ss_t* p, float sq) { const float fl = floorf(sq); const unsigned hi = (unsigned)fl, lo = (unsigned)((sq - fl) * 4294967296.0f); atomicAdd(p, ((ss_t)hi << 32) | (ss_t)lo); }
; __device__ __forceinline__ float ss_get(const ss_t* p) { const ss_t v = *p; return (float)(unsigned)(v >> 32) + (float)(unsigned)v * 2.3283064365386963e-10f; }
; __device__ __forceinline__ unsigned pkbf(float lo, float hi) { typedef float f2_t __attribute__((ext_vector_type(2))); typedef __bf16 b2_t __attribute__((ext_vector_type(2))); f2_t v = {lo, hi}; b2_t b = __builtin_convertvector(v, b2_t); return __builtin_bit_cast(unsigned, b); }
;     __device__ __forceinline__ void operator()(const f32x4 (&acc)[2][2][4][2], const Unit& u, int wr, int wc, int fr, int fq) const {
;     ...
;             for (int m = 0; m < 4; ++m) { const int row = row0 + ai * HALF + m * 16; const size_t off = (size_t)row * ldc + col0;
;                 float rs = 1.0f; if (KS) rs = 1.0f / sqrtf(ss_get(ssb + row) * (1.0f / 1024.f) + 1e-6f);
;                 float sq = 0.f;
; #pragma unroll
;                 for (int bj = 0; bj < 2; ++bj) { const u32x4 r = res[m][bj];
;                     const f32x4 x0 = (f32x4){__uint_as_float(r.x << 16), __uint_as_float(r.x & 0xffff0000u), __uint_as_float(r.y << 16), __uint_as_float(r.y & 0xffff0000u)};
;                     const f32x4 x1 = (f32x4){__uint_as_float(r.z << 16), __uint_as_float(r.z & 0xffff0000u), __uint_as_float(r.w << 16), __uint_as_float(r.w & 0xffff0000u)};
;                     const f32x4 v0 = x0 + acc[ai][bj][m][0] * rs, v1 = x1 + acc[ai][bj][m][1] * rs;
;                     if (OUT) { *(f32x4*)(OUT + off + bj * HALF) = v0; *(f32x4*)(OUT + off + bj * HALF + 4) = v1; }
;                     else { sq += ((v0[0] * v0[0] + v0[1] * v0[1]) + (v0[2] * v0[2] + v0[3] * v0[3])) + ((v1[0] * v1[0] + v1[1] * v1[1]) + (v1[2] * v1[2] + v1[3] * v1[3]));
;                         u32x4 w; w.x = pkbf(v0[0], v0[1]); w.y = pkbf(v0[2], v0[3]); w.z = pkbf(v1[0], v1[1]); w.w = pkbf(v1[2], v1[3]); *(u32x4*)(XB + off + bj * HALF) = w; } }
;                 if (!OUT) { sq += __shfl_xor(sq, 16); sq += __shfl_xor(sq, 32); if (fq == 0) ss_add(ssq_out + row, sq); } }
.LBB0_943:
	s_or_b64 exec, exec, s[2:3]
	s_waitcnt lgkmcnt(0)
	s_nop 1
	v_mov_b32_e32 v36, v232
	v_mov_b32_e32 v37, v233
	v_mov_b32_e32 v41, v2
	v_lshlrev_b32_e32 v46, 16, v83
	v_and_b32_e32 v47, 0xffff0000, v83
	v_lshlrev_b32_e32 v44, 16, v82
	v_and_b32_e32 v45, 0xffff0000, v82
	v_lshlrev_b64 v[38:39], 11, v[98:99]
	v_mov_b32_e32 v40, v37
	v_lshlrev_b64 v[40:41], s43, v[40:41]
	v_min_u32_e32 v37, 1, v40
	v_or_b32_e32 v37, v41, v37
	v_cvt_f32_u32_e32 v37, v37
	v_cvt_f32_u32_e32 v36, v36
	v_ldexp_f32 v37, v37, s46
	v_fmac_f32_e32 v37, 0x2f800000, v36
	v_fmamk_f32 v36, v37, 0x3a800000, v205
	v_rsq_f32_e32 v36, v36
	s_nop 0
	s_nop 0
	s_nop 0
	s_nop 0
	s_nop 1
	s_nop 1
	s_nop 0
	v_lshlrev_b32_e32 v40, 16, v80
	v_and_b32_e32 v41, 0xffff0000, v80
	v_lshlrev_b32_e32 v42, 16, v81
	v_and_b32_e32 v43, 0xffff0000, v81
	v_pk_fma_f32 v[34:35], v[34:35], v[36:37], v[42:43] op_sel_hi:[1,0,1]
	v_pk_fma_f32 v[32:33], v[32:33], v[36:37], v[40:41] op_sel_hi:[1,0,1]
	v_pk_fma_f32 v[40:41], v[30:31], v[36:37], v[46:47] op_sel_hi:[1,0,1]
	v_mul_f32_e32 v30, v33, v33
	v_mul_f32_e32 v31, v35, v35
	v_pk_fma_f32 v[28:29], v[28:29], v[36:37], v[44:45] op_sel_hi:[1,0,1]
	v_fmac_f32_e32 v30, v32, v32
	v_fmac_f32_e32 v31, v34, v34
	v_add_f32_e32 v30, v30, v31
	v_mul_f32_e32 v31, v29, v29
	v_mul_f32_e32 v37, v41, v41
	v_fmac_f32_e32 v31, v28, v28
	v_fmac_f32_e32 v37, v40, v40
	v_add_f32_e32 v31, v31, v37
	v_add_f32_e32 v37, v30, v31
	v_cvt_pk_bf16_f32 v30, v32, v33
	v_cvt_pk_bf16_f32 v32, v28, v29
	v_lshl_add_u64 v[28:29], v[38:39], 1, s[64:65]
	v_cvt_pk_bf16_f32 v31, v34, v35
	v_cvt_pk_bf16_f32 v33, v40, v41
	v_lshl_add_u64 v[28:29], v[0:1], 1, v[28:29]
	global_store_dwordx4 v[28:29], v[30:33], off
	v_lshlrev_b32_e32 v34, 16, v78
	v_and_b32_e32 v35, 0xffff0000, v78
	v_lshlrev_b32_e32 v30, 16, v76
	v_and_b32_e32 v31, 0xffff0000, v76
	v_lshlrev_b32_e32 v32, 16, v77
	v_and_b32_e32 v33, 0xffff0000, v77
	v_lshlrev_b32_e32 v38, 16, v79
	v_and_b32_e32 v39, 0xffff0000, v79
	v_pk_fma_f32 v[26:27], v[26:27], v[36:37], v[32:33] op_sel_hi:[1,0,1]
	v_pk_fma_f32 v[24:25], v[24:25], v[36:37], v[30:31] op_sel_hi:[1,0,1]
	v_pk_fma_f32 v[30:31], v[22:23], v[36:37], v[38:39] op_sel_hi:[1,0,1]
	v_pk_fma_f32 v[22:23], v[20:21], v[36:37], v[34:35] op_sel_hi:[1,0,1]
	v_mul_f32_e32 v20, v25, v25
	v_mul_f32_e32 v21, v27, v27
	v_fmac_f32_e32 v20, v24, v24
	v_fmac_f32_e32 v21, v26, v26
	v_add_f32_e32 v20, v20, v21
	v_mul_f32_e32 v21, v23, v23
	v_mul_f32_e32 v32, v31, v31
	v_fmac_f32_e32 v21, v22, v22
	v_fmac_f32_e32 v32, v30, v30
	v_add_f32_e32 v21, v21, v32
	v_add_f32_e32 v20, v20, v21
	v_add_f32_e32 v32, v37, v20
	v_cvt_pk_bf16_f32 v20, v24, v25
	v_cvt_pk_bf16_f32 v21, v26, v27
	v_cvt_pk_bf16_f32 v22, v22, v23
	v_cvt_pk_bf16_f32 v23, v30, v31
	global_store_dwordx4 v[28:29], v[20:23], off offset:256
	ds_bpermute_b32 v20, v3, v32
	s_waitcnt lgkmcnt(0)
	v_add_f32_e32 v20, v32, v20
	ds_bpermute_b32 v21, v117, v20
	s_and_saveexec_b64 s[2:3], s[40:41]
	s_cbranch_execz .LBB0_945
	s_waitcnt lgkmcnt(0)
	v_add_f32_e32 v22, v20, v21
	v_floor_f32_e32 v24, v22
	v_sub_f32_e32 v22, v22, v24
	v_mul_f32_e32 v22, 0x4f800000, v22
	v_cvt_u32_f32_e32 v23, v24
	v_cvt_u32_f32_e32 v22, v22
	v_lshl_add_u64 v[20:21], v[98:99], 3, s[4:5]
	global_atomic_add_x2 v[20:21], v[22:23], off
.LBB0_945:
	s_or_b64 exec, exec, s[2:3]
	s_waitcnt lgkmcnt(0)
	s_nop 1
	v_mov_b32_e32 v20, v234
	v_mov_b32_e32 v21, v235
	v_mov_b32_e32 v25, v2
	v_lshlrev_b32_e32 v28, 16, v74
	v_and_b32_e32 v29, 0xffff0000, v74
	v_lshlrev_b32_e32 v30, 16, v75
	v_and_b32_e32 v31, 0xffff0000, v75
	v_lshlrev_b64 v[22:23], 11, v[96:97]
	v_mov_b32_e32 v24, v21
	v_lshlrev_b64 v[24:25], s43, v[24:25]
	v_min_u32_e32 v21, 1, v24
	v_or_b32_e32 v21, v25, v21
	v_cvt_f32_u32_e32 v21, v21
	v_cvt_f32_u32_e32 v20, v20
	v_ldexp_f32 v21, v21, s46
	v_fmac_f32_e32 v21, 0x2f800000, v20
	v_fmamk_f32 v20, v21, 0x3a800000, v205
	v_rsq_f32_e32 v20, v20
	s_nop 0
	s_nop 0
	s_nop 0
	s_nop 0
	s_nop 1
	s_nop 1
	s_nop 0
	v_lshlrev_b32_e32 v24, 16, v72
	v_and_b32_e32 v25, 0xffff0000, v72
	v_lshlrev_b32_e32 v26, 16, v73
	v_and_b32_e32 v27, 0xffff0000, v73
	v_pk_fma_f32 v[18:19], v[18:19], v[20:21], v[26:27] op_sel_hi:[1,0,1]
	v_pk_fma_f32 v[16:17], v[16:17], v[20:21], v[24:25] op_sel_hi:[1,0,1]
	v_pk_fma_f32 v[24:25], v[14:15], v[20:21], v[30:31] op_sel_hi:[1,0,1]
	v_pk_fma_f32 v[14:15], v[12:13], v[20:21], v[28:29] op_sel_hi:[1,0,1]
	v_mul_f32_e32 v12, v17, v17
	v_mul_f32_e32 v13, v19, v19
	v_fmac_f32_e32 v12, v16, v16
	v_fmac_f32_e32 v13, v18, v18
	v_add_f32_e32 v12, v12, v13
	v_mul_f32_e32 v13, v15, v15
	v_mul_f32_e32 v21, v25, v25
	v_fmac_f32_e32 v13, v14, v14
	v_fmac_f32_e32 v21, v24, v24
	v_add_f32_e32 v13, v13, v21
	v_add_f32_e32 v21, v12, v13
	v_cvt_pk_bf16_f32 v12, v16, v17
	v_lshl_add_u64 v[16:17], v[22:23], 1, s[64:65]
	v_cvt_pk_bf16_f32 v13, v18, v19
	v_cvt_pk_bf16_f32 v14, v14, v15
	v_cvt_pk_bf16_f32 v15, v24, v25
	v_lshl_add_u64 v[0:1], v[0:1], 1, v[16:17]
	global_store_dwordx4 v[0:1], v[12:15], off
	v_lshlrev_b32_e32 v16, 16, v70
	v_and_b32_e32 v17, 0xffff0000, v70
	v_lshlrev_b32_e32 v12, 16, v68
	v_and_b32_e32 v13, 0xffff0000, v68
	v_lshlrev_b32_e32 v14, 16, v69
	v_and_b32_e32 v15, 0xffff0000, v69
	v_lshlrev_b32_e32 v18, 16, v71
	v_and_b32_e32 v19, 0xffff0000, v71
	v_pk_fma_f32 v[10:11], v[10:11], v[20:21], v[14:15] op_sel_hi:[1,0,1]
	v_pk_fma_f32 v[8:9], v[8:9], v[20:21], v[12:13] op_sel_hi:[1,0,1]
	v_pk_fma_f32 v[12:13], v[6:7], v[20:21], v[18:19] op_sel_hi:[1,0,1]
	v_pk_fma_f32 v[6:7], v[4:5], v[20:21], v[16:17] op_sel_hi:[1,0,1]
	v_mul_f32_e32 v4, v9, v9
	v_mul_f32_e32 v5, v11, v11
	v_fmac_f32_e32 v4, v8, v8
	v_fmac_f32_e32 v5, v10, v10
	v_add_f32_e32 v4, v4, v5
	v_mul_f32_e32 v5, v7, v7
	v_mul_f32_e32 v14, v13, v13
	v_fmac_f32_e32 v5, v6, v6
	v_fmac_f32_e32 v14, v12, v12
	v_add_f32_e32 v5, v5, v14
	v_add_f32_e32 v4, v4, v5
	v_add_f32_e32 v14, v21, v4
	v_cvt_pk_bf16_f32 v4, v8, v9
	v_cvt_pk_bf16_f32 v5, v10, v11
	v_cvt_pk_bf16_f32 v6, v6, v7
	v_cvt_pk_bf16_f32 v7, v12, v13
	global_store_dwordx4 v[0:1], v[4:7], off offset:256
	ds_bpermute_b32 v0, v3, v14
	s_waitcnt lgkmcnt(0)
	v_add_f32_e32 v0, v14, v0
	ds_bpermute_b32 v1, v117, v0
	s_and_saveexec_b64 s[2:3], s[40:41]
	s_cbranch_execz .LBB0_947
	s_waitcnt lgkmcnt(0)
	v_add_f32_e32 v3, v0, v1
	v_floor_f32_e32 v4, v3
	v_sub_f32_e32 v3, v3, v4
	v_mul_f32_e32 v3, 0x4f800000, v3
	v_cvt_u32_f32_e32 v5, v4
	v_cvt_u32_f32_e32 v4, v3
	v_lshl_add_u64 v[0:1], v[96:97], 3, s[4:5]
	global_atomic_add_x2 v[0:1], v[4:5], off

; __device__ __forceinline__ float ss_get(const ss_t* p) { const ss_t v = *p; return (float)(unsigned)(v >> 32) + (float)(unsigned)v * 2.3283064365386963e-10f; }
; __device__ __forceinline__ unsigned pkbf(float lo, float hi) { typedef float f2_t __attribute__((ext_vector_type(2))); typedef __bf16 b2_t __attribute__((ext_vector_type(2))); f2_t v = {lo, hi}; b2_t b = __builtin_convertvector(v, b2_t); return __builtin_bit_cast(unsigned, b); }
;     __device__ __forceinline__ void operator()(const f32x4 (&acc)[2][2][4][2], const Unit& u, int wr, int wc, int fr, int fq) const {
;         int row0 = u.pm * BM + wr * 64 + fr; asm volatile("" : "+v"(row0));     const int col0 = u.pn * HALF + wc * 32 + 8 * fq;
; #pragma unroll
;         for (int ai = 0; ai < 2; ++ai)
; #pragma unroll
;             for (int m = 0; m < 4; ++m) { const int row = row0 + ai * HALF + m * 16; bf16_t* rowp = O + (size_t)row * ldc + col0;
;                 const float rs = 1.0f / sqrtf(ss_get(ssq + row) * (1.0f / 2048.f) + 1e-6f);
;                 const float c1 = -1.4426950408889634f * rs, rs2 = rs * rs;
;                 const f32x4 ga = acc[ai][0][m][0], gb = acc[ai][0][m][1], ua = acc[ai][1][m][0], ub = acc[ai][1][m][1];
;                 u32x4 w;
;                 { const f32x2 o = swiglu_pk((f32x2){ga[0], ga[1]}, (f32x2){ua[0], ua[1]}, c1, rs2); w.x = pkbf(o.x, o.y); }
;                 { const f32x2 o = swiglu_pk((f32x2){ga[2], ga[3]}, (f32x2){ua[2], ua[3]}, c1, rs2); w.y = pkbf(o.x, o.y); }
;                 { const f32x2 o = swiglu_pk((f32x2){gb[0], gb[1]}, (f32x2){ub[0], ub[1]}, c1, rs2); w.z = pkbf(o.x, o.y); }
;                 { const f32x2 o = swiglu_pk((f32x2){gb[2], gb[3]}, (f32x2){ub[2], ub[3]}, c1, rs2); w.w = pkbf(o.x, o.y); }
.LBB0_1054:
	v_mov_b32_e32 v142, v148
	v_readlane_b32 s2, v247, 4
	v_ashrrev_i32_e32 v143, 31, v142
	v_lshl_add_u64 v[146:147], v[142:143], 3, s[4:5]
	global_load_dwordx2 v[152:153], v[146:147], off
	global_load_dwordx2 v[172:173], v[146:147], off offset:128
	global_load_dwordx2 v[174:175], v[146:147], off offset:256
	global_load_dwordx2 v[176:177], v[146:147], off offset:384
	global_load_dwordx2 v[178:179], v[146:147], off offset:1024
	global_load_dwordx2 v[180:181], v[146:147], off offset:1152
	global_load_dwordx2 v[182:183], v[146:147], off offset:1280
	global_load_dwordx2 v[184:185], v[146:147], off offset:1408
	v_readlane_b32 s3, v247, 5
	v_mov_b32_e32 v157, v2
	v_pk_mul_f32 v[158:159], v[116:117], v[124:125]
	v_mov_b64_e32 v[144:145], s[2:3]
	s_flbit_i32_b32 s2, 0
	s_min_u32 s13, s2, 32
	s_sub_i32 s36, 32, s13
	v_lshl_or_b32 v154, s52, 7, v149
	v_ashrrev_i32_e32 v155, 31, v154
	s_movk_i32 s16, 0x2c00
	v_pk_mul_f32 v[130:131], v[122:123], v[130:131]
	v_pk_mul_f32 v[128:129], v[120:121], v[128:129]
	v_pk_mul_f32 v[126:127], v[118:119], v[126:127]
	v_pk_mul_f32 v[114:115], v[106:107], v[114:115]
	v_pk_mul_f32 v[112:113], v[104:105], v[112:113]
	v_pk_mul_f32 v[110:111], v[102:103], v[110:111]
	v_pk_mul_f32 v[108:109], v[100:101], v[108:109]
	v_pk_mul_f32 v[98:99], v[90:91], v[98:99]
	v_pk_mul_f32 v[96:97], v[88:89], v[96:97]
	v_pk_mul_f32 v[94:95], v[86:87], v[94:95]
	v_pk_mul_f32 v[92:93], v[84:85], v[92:93]
	v_pk_mul_f32 v[82:83], v[74:75], v[82:83]
	v_pk_mul_f32 v[80:81], v[72:73], v[80:81]
	v_pk_mul_f32 v[78:79], v[70:71], v[78:79]
	v_pk_mul_f32 v[76:77], v[68:69], v[76:77]
	v_pk_mul_f32 v[66:67], v[58:59], v[66:67]
	v_pk_mul_f32 v[64:65], v[56:57], v[64:65]
	v_pk_mul_f32 v[62:63], v[54:55], v[62:63]
	v_pk_mul_f32 v[60:61], v[52:53], v[60:61]
	v_pk_mul_f32 v[50:51], v[42:43], v[50:51]
	v_pk_mul_f32 v[48:49], v[40:41], v[48:49]
	v_pk_mul_f32 v[46:47], v[38:39], v[46:47]
	v_pk_mul_f32 v[44:45], v[36:37], v[44:45]
	v_pk_mul_f32 v[34:35], v[26:27], v[34:35]
	v_pk_mul_f32 v[32:33], v[24:25], v[32:33]
	v_pk_mul_f32 v[30:31], v[22:23], v[30:31]
	v_pk_mul_f32 v[28:29], v[20:21], v[28:29]
	v_pk_mul_f32 v[18:19], v[10:11], v[18:19]
	v_pk_mul_f32 v[16:17], v[8:9], v[16:17]
	v_pk_mul_f32 v[14:15], v[6:7], v[14:15]
	v_pk_mul_f32 v[12:13], v[4:5], v[12:13]
	s_waitcnt vmcnt(0)
	v_mov_b32_e32 v156, v153
	v_lshlrev_b64 v[124:125], s13, v[156:157]
	v_min_u32_e32 v124, 1, v124
	v_or_b32_e32 v124, v125, v124
	v_cvt_f32_u32_e32 v124, v124
	v_cvt_f32_u32_e32 v125, v152
	v_mad_i64_i32 v[152:153], s[2:3], v142, s16, v[144:145]
	v_ldexp_f32 v124, v124, s36
	v_fmac_f32_e32 v124, 0x2f800000, v125
	v_fmamk_f32 v124, v124, 0x3a000000, v205
	v_rsq_f32_e32 v143, v124
	s_nop 0
	s_nop 1
	v_lshlrev_b64 v[124:125], 1, v[154:155]
	v_lshl_add_u64 v[152:153], v[152:153], 0, v[124:125]
	s_nop 1
	s_nop 1
	s_nop 1
	v_mul_f32_e32 v154, 0xbfb8aa3b, v143
	v_pk_mul_f32 v[120:121], v[120:121], v[154:155] op_sel_hi:[1,0]
	v_pk_mul_f32 v[122:123], v[122:123], v[154:155] op_sel_hi:[1,0]
	v_pk_mul_f32 v[116:117], v[116:117], v[154:155] op_sel_hi:[1,0]
	v_pk_mul_f32 v[118:119], v[118:119], v[154:155] op_sel_hi:[1,0]
	v_exp_f32_e32 v120, v120
	v_exp_f32_e32 v121, v121
	v_exp_f32_e32 v122, v122
	v_exp_f32_e32 v123, v123
	v_exp_f32_e32 v116, v116
	v_exp_f32_e32 v117, v117
	v_exp_f32_e32 v118, v118
	v_exp_f32_e32 v119, v119
	v_pk_add_f32 v[120:121], v[120:121], 1.0 op_sel_hi:[1,0]
	v_pk_add_f32 v[122:123], v[122:123], 1.0 op_sel_hi:[1,0]
	v_pk_add_f32 v[116:117], v[116:117], 1.0 op_sel_hi:[1,0]
	v_pk_add_f32 v[118:119], v[118:119], 1.0 op_sel_hi:[1,0]
	v_rcp_f32_e32 v120, v120
	v_rcp_f32_e32 v121, v121
	v_rcp_f32_e32 v122, v122
	v_rcp_f32_e32 v123, v123
	v_rcp_f32_e32 v116, v116
	v_rcp_f32_e32 v117, v117
	v_rcp_f32_e32 v118, v118
	v_rcp_f32_e32 v119, v119
	v_mul_f32_e32 v156, v143, v143
	v_pk_mul_f32 v[120:121], v[156:157], v[120:121] op_sel_hi:[0,1]
	v_pk_mul_f32 v[122:123], v[156:157], v[122:123] op_sel_hi:[0,1]
	v_pk_mul_f32 v[116:117], v[156:157], v[116:117] op_sel_hi:[0,1]
	v_pk_mul_f32 v[118:119], v[156:157], v[118:119] op_sel_hi:[0,1]
	v_pk_mul_f32 v[120:121], v[128:129], v[120:121]
	v_pk_mul_f32 v[122:123], v[130:131], v[122:123]
	v_pk_mul_f32 v[128:129], v[158:159], v[116:117]
	v_pk_mul_f32 v[126:127], v[126:127], v[118:119]
	v_cvt_pk_bf16_f32 v116, v120, v121
	v_cvt_pk_bf16_f32 v117, v122, v123
	v_cvt_pk_bf16_f32 v118, v128, v129
	v_cvt_pk_bf16_f32 v119, v126, v127
	global_store_dwordx4 v[152:153], v[116:119], off
	s_nop 1
	v_mov_b32_e32 v116, v172
	v_mov_b32_e32 v117, v173
	s_nop 0
	v_mov_b32_e32 v119, v2
	v_mov_b32_e32 v118, v117
	v_lshlrev_b64 v[118:119], s13, v[118:119]
	v_min_u32_e32 v117, 1, v118
	v_or_b32_e32 v117, v119, v117
	v_cvt_f32_u32_e32 v117, v117
	v_cvt_f32_u32_e32 v116, v116
	v_ldexp_f32 v117, v117, s36
	v_fmac_f32_e32 v117, 0x2f800000, v116
	v_fmamk_f32 v116, v117, 0x3a000000, v205
	v_rsq_f32_e32 v119, v116
	s_nop 0
	s_nop 1
	v_add_u32_e32 v116, 16, v142
	v_mad_i64_i32 v[116:117], s[2:3], v116, s16, v[144:145]
	v_lshl_add_u64 v[116:117], v[116:117], 0, v[124:125]
	s_nop 0
	s_nop 1
	s_nop 1
	v_mul_f32_e32 v118, 0xbfb8aa3b, v119
	v_pk_mul_f32 v[104:105], v[104:105], v[118:119] op_sel_hi:[1,0]
	v_pk_mul_f32 v[106:107], v[106:107], v[118:119] op_sel_hi:[1,0]
	v_pk_mul_f32 v[100:101], v[100:101], v[118:119] op_sel_hi:[1,0]
	v_pk_mul_f32 v[102:103], v[102:103], v[118:119] op_sel_hi:[1,0]
	v_exp_f32_e32 v104, v104
	v_exp_f32_e32 v105, v105
	v_exp_f32_e32 v106, v106
	v_exp_f32_e32 v107, v107
	v_exp_f32_e32 v100, v100
	v_exp_f32_e32 v101, v101
	v_exp_f32_e32 v102, v102
	v_exp_f32_e32 v103, v103
	v_pk_add_f32 v[104:105], v[104:105], 1.0 op_sel_hi:[1,0]
; __device__ __forceinline__ float ss_get(const ss_t* p) { const ss_t v = *p; return (float)(unsigned)(v >> 32) + (float)(unsigned)v * 2.3283064365386963e-10f; }
; __device__ __forceinline__ unsigned pkbf(float lo, float hi) { typedef float f2_t __attribute__((ext_vector_type(2))); typedef __bf16 b2_t __attribute__((ext_vector_type(2))); f2_t v = {lo, hi}; b2_t b = __builtin_convertvector(v, b2_t); return __builtin_bit_cast(unsigned, b); }
;     __device__ __forceinline__ void operator()(const f32x4 (&acc)[2][2][4][2], const Unit& u, int wr, int wc, int fr, int fq) const {
;     ...
;             for (int m = 0; m < 4; ++m) { const int row = row0 + ai * HALF + m * 16; bf16_t* rowp = O + (size_t)row * ldc + col0;
;                 const float rs = 1.0f / sqrtf(ss_get(ssq + row) * (1.0f / 2048.f) + 1e-6f);
;                 const float c1 = -1.4426950408889634f * rs, rs2 = rs * rs;
;                 const f32x4 ga = acc[ai][0][m][0], gb = acc[ai][0][m][1], ua = acc[ai][1][m][0], ub = acc[ai][1][m][1];
;                 u32x4 w;
;                 { const f32x2 o = swiglu_pk((f32x2){ga[0], ga[1]}, (f32x2){ua[0], ua[1]}, c1, rs2); w.x = pkbf(o.x, o.y); }
;                 { const f32x2 o = swiglu_pk((f32x2){ga[2], ga[3]}, (f32x2){ua[2], ua[3]}, c1, rs2); w.y = pkbf(o.x, o.y); }
;                 { const f32x2 o = swiglu_pk((f32x2){gb[0], gb[1]}, (f32x2){ub[0], ub[1]}, c1, rs2); w.z = pkbf(o.x, o.y); }
;                 { const f32x2 o = swiglu_pk((f32x2){gb[2], gb[3]}, (f32x2){ub[2], ub[3]}, c1, rs2); w.w = pkbf(o.x, o.y); }
;                 *(u32x4*)rowp = w; }
	v_pk_add_f32 v[106:107], v[106:107], 1.0 op_sel_hi:[1,0]
	v_pk_add_f32 v[100:101], v[100:101], 1.0 op_sel_hi:[1,0]
	v_pk_add_f32 v[102:103], v[102:103], 1.0 op_sel_hi:[1,0]
	v_rcp_f32_e32 v104, v104
	v_rcp_f32_e32 v105, v105
	v_rcp_f32_e32 v106, v106
	v_rcp_f32_e32 v107, v107
	v_rcp_f32_e32 v100, v100
	v_rcp_f32_e32 v101, v101
	v_rcp_f32_e32 v102, v102
	v_rcp_f32_e32 v103, v103
	v_mul_f32_e32 v120, v119, v119
	v_pk_mul_f32 v[104:105], v[120:121], v[104:105] op_sel_hi:[0,1]
	v_pk_mul_f32 v[106:107], v[120:121], v[106:107] op_sel_hi:[0,1]
	v_pk_mul_f32 v[100:101], v[120:121], v[100:101] op_sel_hi:[0,1]
	v_pk_mul_f32 v[102:103], v[120:121], v[102:103] op_sel_hi:[0,1]
	v_pk_mul_f32 v[104:105], v[112:113], v[104:105]
	v_pk_mul_f32 v[106:107], v[114:115], v[106:107]
	v_pk_mul_f32 v[108:109], v[108:109], v[100:101]
	v_pk_mul_f32 v[110:111], v[110:111], v[102:103]
	v_cvt_pk_bf16_f32 v100, v104, v105
	v_cvt_pk_bf16_f32 v101, v106, v107
	v_cvt_pk_bf16_f32 v102, v108, v109
	v_cvt_pk_bf16_f32 v103, v110, v111
	global_store_dwordx4 v[116:117], v[100:103], off
	s_nop 1
	v_mov_b32_e32 v100, v174
	v_mov_b32_e32 v101, v175
	s_nop 0
	v_mov_b32_e32 v103, v2
	v_mov_b32_e32 v102, v101
	v_lshlrev_b64 v[102:103], s13, v[102:103]
	v_min_u32_e32 v101, 1, v102
	v_or_b32_e32 v101, v103, v101
	v_cvt_f32_u32_e32 v101, v101
	v_cvt_f32_u32_e32 v100, v100
	v_ldexp_f32 v101, v101, s36
	v_fmac_f32_e32 v101, 0x2f800000, v100
	v_fmamk_f32 v100, v101, 0x3a000000, v205
	v_rsq_f32_e32 v103, v100
	s_nop 0
	s_nop 1
	v_add_u32_e32 v100, 32, v142
	v_mad_i64_i32 v[100:101], s[2:3], v100, s16, v[144:145]
	v_lshl_add_u64 v[100:101], v[100:101], 0, v[124:125]
	s_nop 0
	s_nop 1
	s_nop 1
	v_mul_f32_e32 v102, 0xbfb8aa3b, v103
	v_pk_mul_f32 v[88:89], v[88:89], v[102:103] op_sel_hi:[1,0]
	v_pk_mul_f32 v[90:91], v[90:91], v[102:103] op_sel_hi:[1,0]
	v_pk_mul_f32 v[84:85], v[84:85], v[102:103] op_sel_hi:[1,0]
	v_pk_mul_f32 v[86:87], v[86:87], v[102:103] op_sel_hi:[1,0]
	v_exp_f32_e32 v88, v88
	v_exp_f32_e32 v89, v89
	v_exp_f32_e32 v90, v90
	v_exp_f32_e32 v91, v91
	v_exp_f32_e32 v84, v84
	v_exp_f32_e32 v85, v85
	v_exp_f32_e32 v86, v86
	v_exp_f32_e32 v87, v87
	v_pk_add_f32 v[88:89], v[88:89], 1.0 op_sel_hi:[1,0]
	v_pk_add_f32 v[90:91], v[90:91], 1.0 op_sel_hi:[1,0]
	v_pk_add_f32 v[84:85], v[84:85], 1.0 op_sel_hi:[1,0]
	v_pk_add_f32 v[86:87], v[86:87], 1.0 op_sel_hi:[1,0]
	v_rcp_f32_e32 v88, v88
	v_rcp_f32_e32 v89, v89
	v_rcp_f32_e32 v90, v90
	v_rcp_f32_e32 v91, v91
	v_rcp_f32_e32 v84, v84
	v_rcp_f32_e32 v85, v85
	v_rcp_f32_e32 v86, v86
	v_rcp_f32_e32 v87, v87
	v_mul_f32_e32 v104, v103, v103
	v_pk_mul_f32 v[88:89], v[104:105], v[88:89] op_sel_hi:[0,1]
	v_pk_mul_f32 v[90:91], v[104:105], v[90:91] op_sel_hi:[0,1]
	v_pk_mul_f32 v[84:85], v[104:105], v[84:85] op_sel_hi:[0,1]
	v_pk_mul_f32 v[86:87], v[104:105], v[86:87] op_sel_hi:[0,1]
	v_pk_mul_f32 v[88:89], v[96:97], v[88:89]
	v_pk_mul_f32 v[90:91], v[98:99], v[90:91]
	v_pk_mul_f32 v[92:93], v[92:93], v[84:85]
	v_pk_mul_f32 v[94:95], v[94:95], v[86:87]
	v_cvt_pk_bf16_f32 v84, v88, v89
	v_cvt_pk_bf16_f32 v85, v90, v91
	v_cvt_pk_bf16_f32 v86, v92, v93
	v_cvt_pk_bf16_f32 v87, v94, v95
	global_store_dwordx4 v[100:101], v[84:87], off
	s_nop 1
	v_mov_b32_e32 v84, v176
	v_mov_b32_e32 v85, v177
	s_nop 0
	v_mov_b32_e32 v87, v2
	v_mov_b32_e32 v86, v85
	v_lshlrev_b64 v[86:87], s13, v[86:87]
	v_min_u32_e32 v85, 1, v86
	v_or_b32_e32 v85, v87, v85
	v_cvt_f32_u32_e32 v85, v85
	v_cvt_f32_u32_e32 v84, v84
	v_ldexp_f32 v85, v85, s36
	v_fmac_f32_e32 v85, 0x2f800000, v84
	v_fmamk_f32 v84, v85, 0x3a000000, v205
	v_rsq_f32_e32 v87, v84
	s_nop 0
	s_nop 1
	v_add_u32_e32 v84, 48, v142
	v_mad_i64_i32 v[84:85], s[2:3], v84, s16, v[144:145]
	v_lshl_add_u64 v[84:85], v[84:85], 0, v[124:125]
	s_nop 0
	s_nop 1
	s_nop 1
	v_mul_f32_e32 v86, 0xbfb8aa3b, v87
	v_pk_mul_f32 v[72:73], v[72:73], v[86:87] op_sel_hi:[1,0]
	v_pk_mul_f32 v[74:75], v[74:75], v[86:87] op_sel_hi:[1,0]
	v_pk_mul_f32 v[68:69], v[68:69], v[86:87] op_sel_hi:[1,0]
	v_pk_mul_f32 v[70:71], v[70:71], v[86:87] op_sel_hi:[1,0]
	v_exp_f32_e32 v72, v72
	v_exp_f32_e32 v73, v73
	v_exp_f32_e32 v74, v74
	v_exp_f32_e32 v75, v75
	v_exp_f32_e32 v68, v68
	v_exp_f32_e32 v69, v69
	v_exp_f32_e32 v70, v70
	v_exp_f32_e32 v71, v71
	v_pk_add_f32 v[72:73], v[72:73], 1.0 op_sel_hi:[1,0]
	v_pk_add_f32 v[74:75], v[74:75], 1.0 op_sel_hi:[1,0]
	v_pk_add_f32 v[68:69], v[68:69], 1.0 op_sel_hi:[1,0]
	v_pk_add_f32 v[70:71], v[70:71], 1.0 op_sel_hi:[1,0]
	v_rcp_f32_e32 v72, v72
	v_rcp_f32_e32 v73, v73
	v_rcp_f32_e32 v74, v74
	v_rcp_f32_e32 v75, v75
	v_rcp_f32_e32 v68, v68
	v_rcp_f32_e32 v69, v69
	v_rcp_f32_e32 v70, v70
	v_rcp_f32_e32 v71, v71
	v_mul_f32_e32 v88, v87, v87
	v_pk_mul_f32 v[72:73], v[88:89], v[72:73] op_sel_hi:[0,1]
	v_pk_mul_f32 v[74:75], v[88:89], v[74:75] op_sel_hi:[0,1]
	v_pk_mul_f32 v[68:69], v[88:89], v[68:69] op_sel_hi:[0,1]
	v_pk_mul_f32 v[70:71], v[88:89], v[70:71] op_sel_hi:[0,1]
	v_pk_mul_f32 v[72:73], v[80:81], v[72:73]
	v_pk_mul_f32 v[74:75], v[82:83], v[74:75]
	v_pk_mul_f32 v[76:77], v[76:77], v[68:69]
	v_pk_mul_f32 v[78:79], v[78:79], v[70:71]
	v_cvt_pk_bf16_f32 v68, v72, v73
	v_cvt_pk_bf16_f32 v69, v74, v75
	v_cvt_pk_bf16_f32 v70, v76, v77
	v_cvt_pk_bf16_f32 v71, v78, v79
	global_store_dwordx4 v[84:85], v[68:71], off
	s_nop 1
	v_mov_b32_e32 v68, v178
	v_mov_b32_e32 v69, v179
	s_nop 0
	v_mov_b32_e32 v71, v2
	v_mov_b32_e32 v70, v69
	v_lshlrev_b64 v[70:71], s13, v[70:71]
	v_min_u32_e32 v69, 1, v70
	v_or_b32_e32 v69, v71, v69
	v_cvt_f32_u32_e32 v69, v69
	v_cvt_f32_u32_e32 v68, v68
	v_ldexp_f32 v69, v69, s36
	v_fmac_f32_e32 v69, 0x2f800000, v68
	v_fmamk_f32 v68, v69, 0x3a000000, v205
	v_rsq_f32_e32 v71, v68
	s_nop 0
; __device__ __forceinline__ float ss_get(const ss_t* p) { const ss_t v = *p; return (float)(unsigned)(v >> 32) + (float)(unsigned)v * 2.3283064365386963e-10f; }
; __device__ __forceinline__ unsigned pkbf(float lo, float hi) { typedef float f2_t __attribute__((ext_vector_type(2))); typedef __bf16 b2_t __attribute__((ext_vector_type(2))); f2_t v = {lo, hi}; b2_t b = __builtin_convertvector(v, b2_t); return __builtin_bit_cast(unsigned, b); }
;     __device__ __forceinline__ void operator()(const f32x4 (&acc)[2][2][4][2], const Unit& u, int wr, int wc, int fr, int fq) const {
;     ...
;             for (int m = 0; m < 4; ++m) { const int row = row0 + ai * HALF + m * 16; bf16_t* rowp = O + (size_t)row * ldc + col0;
;                 const float rs = 1.0f / sqrtf(ss_get(ssq + row) * (1.0f / 2048.f) + 1e-6f);
;                 const float c1 = -1.4426950408889634f * rs, rs2 = rs * rs;
;                 const f32x4 ga = acc[ai][0][m][0], gb = acc[ai][0][m][1], ua = acc[ai][1][m][0], ub = acc[ai][1][m][1];
;                 u32x4 w;
;                 { const f32x2 o = swiglu_pk((f32x2){ga[0], ga[1]}, (f32x2){ua[0], ua[1]}, c1, rs2); w.x = pkbf(o.x, o.y); }
;                 { const f32x2 o = swiglu_pk((f32x2){ga[2], ga[3]}, (f32x2){ua[2], ua[3]}, c1, rs2); w.y = pkbf(o.x, o.y); }
;                 { const f32x2 o = swiglu_pk((f32x2){gb[0], gb[1]}, (f32x2){ub[0], ub[1]}, c1, rs2); w.z = pkbf(o.x, o.y); }
;                 { const f32x2 o = swiglu_pk((f32x2){gb[2], gb[3]}, (f32x2){ub[2], ub[3]}, c1, rs2); w.w = pkbf(o.x, o.y); }
;                 *(u32x4*)rowp = w; }
	s_nop 1
	v_add_u32_e32 v68, 0x80, v142
	v_mad_i64_i32 v[68:69], s[2:3], v68, s16, v[144:145]
	v_lshl_add_u64 v[68:69], v[68:69], 0, v[124:125]
	s_nop 0
	s_nop 1
	s_nop 1
	v_mul_f32_e32 v70, 0xbfb8aa3b, v71
	v_pk_mul_f32 v[56:57], v[56:57], v[70:71] op_sel_hi:[1,0]
	v_pk_mul_f32 v[58:59], v[58:59], v[70:71] op_sel_hi:[1,0]
	v_pk_mul_f32 v[52:53], v[52:53], v[70:71] op_sel_hi:[1,0]
	v_pk_mul_f32 v[54:55], v[54:55], v[70:71] op_sel_hi:[1,0]
	v_exp_f32_e32 v56, v56
	v_exp_f32_e32 v57, v57
	v_exp_f32_e32 v58, v58
	v_exp_f32_e32 v59, v59
	v_exp_f32_e32 v52, v52
	v_exp_f32_e32 v53, v53
	v_exp_f32_e32 v54, v54
	v_exp_f32_e32 v55, v55
	v_pk_add_f32 v[56:57], v[56:57], 1.0 op_sel_hi:[1,0]
	v_pk_add_f32 v[58:59], v[58:59], 1.0 op_sel_hi:[1,0]
	v_pk_add_f32 v[52:53], v[52:53], 1.0 op_sel_hi:[1,0]
	v_pk_add_f32 v[54:55], v[54:55], 1.0 op_sel_hi:[1,0]
	v_rcp_f32_e32 v56, v56
	v_rcp_f32_e32 v57, v57
	v_rcp_f32_e32 v58, v58
	v_rcp_f32_e32 v59, v59
	v_rcp_f32_e32 v52, v52
	v_rcp_f32_e32 v53, v53
	v_rcp_f32_e32 v54, v54
	v_rcp_f32_e32 v55, v55
	v_mul_f32_e32 v72, v71, v71
	v_pk_mul_f32 v[56:57], v[72:73], v[56:57] op_sel_hi:[0,1]
	v_pk_mul_f32 v[58:59], v[72:73], v[58:59] op_sel_hi:[0,1]
	v_pk_mul_f32 v[52:53], v[72:73], v[52:53] op_sel_hi:[0,1]
	v_pk_mul_f32 v[54:55], v[72:73], v[54:55] op_sel_hi:[0,1]
	v_pk_mul_f32 v[56:57], v[64:65], v[56:57]
	v_pk_mul_f32 v[58:59], v[66:67], v[58:59]
	v_pk_mul_f32 v[60:61], v[60:61], v[52:53]
	v_pk_mul_f32 v[62:63], v[62:63], v[54:55]
	v_cvt_pk_bf16_f32 v52, v56, v57
	v_cvt_pk_bf16_f32 v53, v58, v59
	v_cvt_pk_bf16_f32 v54, v60, v61
	v_cvt_pk_bf16_f32 v55, v62, v63
	global_store_dwordx4 v[68:69], v[52:55], off
	s_nop 1
	v_mov_b32_e32 v52, v180
	v_mov_b32_e32 v53, v181
	s_nop 0
	v_mov_b32_e32 v55, v2
	v_mov_b32_e32 v54, v53
	v_lshlrev_b64 v[54:55], s13, v[54:55]
	v_min_u32_e32 v53, 1, v54
	v_or_b32_e32 v53, v55, v53
	v_cvt_f32_u32_e32 v53, v53
	v_cvt_f32_u32_e32 v52, v52
	v_ldexp_f32 v53, v53, s36
	v_fmac_f32_e32 v53, 0x2f800000, v52
	v_fmamk_f32 v52, v53, 0x3a000000, v205
	v_rsq_f32_e32 v55, v52
	s_nop 0
	s_nop 1
	v_add_u32_e32 v52, 0x90, v142
	v_mad_i64_i32 v[52:53], s[2:3], v52, s16, v[144:145]
	v_lshl_add_u64 v[52:53], v[52:53], 0, v[124:125]
	s_nop 0
	s_nop 1
	s_nop 1
	v_mul_f32_e32 v54, 0xbfb8aa3b, v55
	v_pk_mul_f32 v[40:41], v[40:41], v[54:55] op_sel_hi:[1,0]
	v_pk_mul_f32 v[42:43], v[42:43], v[54:55] op_sel_hi:[1,0]
	v_pk_mul_f32 v[36:37], v[36:37], v[54:55] op_sel_hi:[1,0]
	v_pk_mul_f32 v[38:39], v[38:39], v[54:55] op_sel_hi:[1,0]
	v_exp_f32_e32 v40, v40
	v_exp_f32_e32 v41, v41
	v_exp_f32_e32 v42, v42
	v_exp_f32_e32 v43, v43
	v_exp_f32_e32 v36, v36
	v_exp_f32_e32 v37, v37
	v_exp_f32_e32 v38, v38
	v_exp_f32_e32 v39, v39
	v_pk_add_f32 v[40:41], v[40:41], 1.0 op_sel_hi:[1,0]
	v_pk_add_f32 v[42:43], v[42:43], 1.0 op_sel_hi:[1,0]
	v_pk_add_f32 v[36:37], v[36:37], 1.0 op_sel_hi:[1,0]
	v_pk_add_f32 v[38:39], v[38:39], 1.0 op_sel_hi:[1,0]
	v_rcp_f32_e32 v40, v40
	v_rcp_f32_e32 v41, v41
	v_rcp_f32_e32 v42, v42
	v_rcp_f32_e32 v43, v43
	v_rcp_f32_e32 v36, v36
	v_rcp_f32_e32 v37, v37
	v_rcp_f32_e32 v38, v38
	v_rcp_f32_e32 v39, v39
	v_mul_f32_e32 v56, v55, v55
	v_pk_mul_f32 v[40:41], v[56:57], v[40:41] op_sel_hi:[0,1]
	v_pk_mul_f32 v[42:43], v[56:57], v[42:43] op_sel_hi:[0,1]
	v_pk_mul_f32 v[36:37], v[56:57], v[36:37] op_sel_hi:[0,1]
	v_pk_mul_f32 v[38:39], v[56:57], v[38:39] op_sel_hi:[0,1]
	v_pk_mul_f32 v[40:41], v[48:49], v[40:41]
	v_pk_mul_f32 v[42:43], v[50:51], v[42:43]
	v_pk_mul_f32 v[44:45], v[44:45], v[36:37]
	v_pk_mul_f32 v[46:47], v[46:47], v[38:39]
	v_cvt_pk_bf16_f32 v36, v40, v41
	v_cvt_pk_bf16_f32 v37, v42, v43
	v_cvt_pk_bf16_f32 v38, v44, v45
	v_cvt_pk_bf16_f32 v39, v46, v47
	global_store_dwordx4 v[52:53], v[36:39], off
	s_nop 1
	v_mov_b32_e32 v36, v182
	v_mov_b32_e32 v37, v183
	s_nop 0
	v_mov_b32_e32 v39, v2
	v_mov_b32_e32 v38, v37
	v_lshlrev_b64 v[38:39], s13, v[38:39]
	v_min_u32_e32 v37, 1, v38
	v_or_b32_e32 v37, v39, v37
	v_cvt_f32_u32_e32 v37, v37
; __device__ __forceinline__ float ss_get(const ss_t* p) { const ss_t v = *p; return (float)(unsigned)(v >> 32) + (float)(unsigned)v * 2.3283064365386963e-10f; }
; __device__ __forceinline__ unsigned pkbf(float lo, float hi) { typedef float f2_t __attribute__((ext_vector_type(2))); typedef __bf16 b2_t __attribute__((ext_vector_type(2))); f2_t v = {lo, hi}; b2_t b = __builtin_convertvector(v, b2_t); return __builtin_bit_cast(unsigned, b); }
; #define PG8_BAR __builtin_amdgcn_s_barrier()
;     __device__ __forceinline__ void operator()(const f32x4 (&acc)[2][2][4][2], const Unit& u, int wr, int wc, int fr, int fq) const {
;     ...
;             for (int m = 0; m < 4; ++m) { const int row = row0 + ai * HALF + m * 16; bf16_t* rowp = O + (size_t)row * ldc + col0;
;                 const float rs = 1.0f / sqrtf(ss_get(ssq + row) * (1.0f / 2048.f) + 1e-6f);
;                 const float c1 = -1.4426950408889634f * rs, rs2 = rs * rs;
;                 const f32x4 ga = acc[ai][0][m][0], gb = acc[ai][0][m][1], ua = acc[ai][1][m][0], ub = acc[ai][1][m][1];
;                 u32x4 w;
;                 { const f32x2 o = swiglu_pk((f32x2){ga[0], ga[1]}, (f32x2){ua[0], ua[1]}, c1, rs2); w.x = pkbf(o.x, o.y); }
;                 { const f32x2 o = swiglu_pk((f32x2){ga[2], ga[3]}, (f32x2){ua[2], ua[3]}, c1, rs2); w.y = pkbf(o.x, o.y); }
;                 { const f32x2 o = swiglu_pk((f32x2){gb[0], gb[1]}, (f32x2){ub[0], ub[1]}, c1, rs2); w.z = pkbf(o.x, o.y); }
;                 { const f32x2 o = swiglu_pk((f32x2){gb[2], gb[3]}, (f32x2){ub[2], ub[3]}, c1, rs2); w.w = pkbf(o.x, o.y); }
;                 *(u32x4*)rowp = w; }
; template <class Epi, class Sched, bool ALIGN_EPI = false, bool SP2 = false>
; __device__ __forceinline__ void gemm_phase(PG8_LAS unsigned char* lds, const Gemm g, const Sched& S, const Epi& E) {
;     ...
;         if (!has_next) break;
; #pragma unroll
;         for (int a = 0; a < 2; ++a)
; #pragma unroll
;             for (int b = 0; b < 2; ++b)
; #pragma unroll
;                 for (int m = 0; m < 4; ++m)
; #pragma unroll
;                     for (int n = 0; n < 2; ++n) acc[a][b][m][n] = (f32x4){0.f, 0.f, 0.f, 0.f};
;         cur = nxt; cA = nA; cB = nB; ++ui;
;         if constexpr (ALIGN_EPI) { if (wr == 1) PG8_BAR; }
	v_cvt_f32_u32_e32 v36, v36
	v_ldexp_f32 v37, v37, s36
	v_fmac_f32_e32 v37, 0x2f800000, v36
	v_fmamk_f32 v36, v37, 0x3a000000, v205
	v_rsq_f32_e32 v39, v36
	s_nop 0
	s_nop 1
	v_add_u32_e32 v36, 0xa0, v142
	v_mad_i64_i32 v[36:37], s[2:3], v36, s16, v[144:145]
	v_lshl_add_u64 v[36:37], v[36:37], 0, v[124:125]
	s_nop 0
	s_nop 1
	s_nop 1
	v_mul_f32_e32 v38, 0xbfb8aa3b, v39
	v_pk_mul_f32 v[24:25], v[24:25], v[38:39] op_sel_hi:[1,0]
	v_pk_mul_f32 v[26:27], v[26:27], v[38:39] op_sel_hi:[1,0]
	v_pk_mul_f32 v[20:21], v[20:21], v[38:39] op_sel_hi:[1,0]
	v_pk_mul_f32 v[22:23], v[22:23], v[38:39] op_sel_hi:[1,0]
	v_exp_f32_e32 v24, v24
	v_exp_f32_e32 v25, v25
	v_exp_f32_e32 v26, v26
	v_exp_f32_e32 v27, v27
	v_exp_f32_e32 v20, v20
	v_exp_f32_e32 v21, v21
	v_exp_f32_e32 v22, v22
	v_exp_f32_e32 v23, v23
	v_pk_add_f32 v[24:25], v[24:25], 1.0 op_sel_hi:[1,0]
	v_pk_add_f32 v[26:27], v[26:27], 1.0 op_sel_hi:[1,0]
	v_pk_add_f32 v[20:21], v[20:21], 1.0 op_sel_hi:[1,0]
	v_pk_add_f32 v[22:23], v[22:23], 1.0 op_sel_hi:[1,0]
	v_rcp_f32_e32 v24, v24
	v_rcp_f32_e32 v25, v25
	v_rcp_f32_e32 v26, v26
	v_rcp_f32_e32 v27, v27
	v_rcp_f32_e32 v20, v20
	v_rcp_f32_e32 v21, v21
	v_rcp_f32_e32 v22, v22
	v_rcp_f32_e32 v23, v23
	v_mul_f32_e32 v40, v39, v39
	v_pk_mul_f32 v[24:25], v[40:41], v[24:25] op_sel_hi:[0,1]
	v_pk_mul_f32 v[26:27], v[40:41], v[26:27] op_sel_hi:[0,1]
	v_pk_mul_f32 v[20:21], v[40:41], v[20:21] op_sel_hi:[0,1]
	v_pk_mul_f32 v[22:23], v[40:41], v[22:23] op_sel_hi:[0,1]
	v_pk_mul_f32 v[24:25], v[32:33], v[24:25]
	v_pk_mul_f32 v[26:27], v[34:35], v[26:27]
	v_pk_mul_f32 v[28:29], v[28:29], v[20:21]
	v_pk_mul_f32 v[30:31], v[30:31], v[22:23]
	v_cvt_pk_bf16_f32 v20, v24, v25
	v_cvt_pk_bf16_f32 v21, v26, v27
	v_cvt_pk_bf16_f32 v22, v28, v29
	v_cvt_pk_bf16_f32 v23, v30, v31
	global_store_dwordx4 v[36:37], v[20:23], off
	s_nop 1
	v_mov_b32_e32 v20, v184
	v_mov_b32_e32 v21, v185
	s_nop 0
	v_mov_b32_e32 v23, v2
	v_mov_b32_e32 v22, v21
	v_lshlrev_b64 v[22:23], s13, v[22:23]
	v_min_u32_e32 v21, 1, v22
	v_or_b32_e32 v21, v23, v21
	v_cvt_f32_u32_e32 v21, v21
	v_cvt_f32_u32_e32 v20, v20
	v_ldexp_f32 v21, v21, s36
	v_fmac_f32_e32 v21, 0x2f800000, v20
	v_fmamk_f32 v20, v21, 0x3a000000, v205
	v_rsq_f32_e32 v23, v20
	s_nop 0
	s_nop 1
	v_add_u32_e32 v20, 0xb0, v142
	v_mad_i64_i32 v[20:21], s[2:3], v20, s16, v[144:145]
	v_lshl_add_u64 v[20:21], v[20:21], 0, v[124:125]
	s_nop 0
	s_nop 1
	s_nop 1
	s_mov_b64 s[2:3], -1
	v_mul_f32_e32 v22, 0xbfb8aa3b, v23
	v_pk_mul_f32 v[8:9], v[8:9], v[22:23] op_sel_hi:[1,0]
	v_pk_mul_f32 v[10:11], v[10:11], v[22:23] op_sel_hi:[1,0]
	v_pk_mul_f32 v[4:5], v[4:5], v[22:23] op_sel_hi:[1,0]
	v_pk_mul_f32 v[6:7], v[6:7], v[22:23] op_sel_hi:[1,0]
	v_exp_f32_e32 v8, v8
	v_exp_f32_e32 v9, v9
	v_exp_f32_e32 v10, v10
	v_exp_f32_e32 v11, v11
	v_exp_f32_e32 v4, v4
	v_exp_f32_e32 v5, v5
	v_exp_f32_e32 v6, v6
	v_exp_f32_e32 v7, v7
	v_pk_add_f32 v[8:9], v[8:9], 1.0 op_sel_hi:[1,0]
	v_pk_add_f32 v[10:11], v[10:11], 1.0 op_sel_hi:[1,0]
	v_pk_add_f32 v[4:5], v[4:5], 1.0 op_sel_hi:[1,0]
	v_pk_add_f32 v[6:7], v[6:7], 1.0 op_sel_hi:[1,0]
	v_rcp_f32_e32 v8, v8
	v_rcp_f32_e32 v9, v9
	v_rcp_f32_e32 v10, v10
	v_rcp_f32_e32 v11, v11
	v_rcp_f32_e32 v4, v4
	v_rcp_f32_e32 v5, v5
	v_rcp_f32_e32 v6, v6
	v_rcp_f32_e32 v7, v7
	v_mul_f32_e32 v24, v23, v23
	v_pk_mul_f32 v[8:9], v[24:25], v[8:9] op_sel_hi:[0,1]
	v_pk_mul_f32 v[10:11], v[24:25], v[10:11] op_sel_hi:[0,1]
	v_pk_mul_f32 v[4:5], v[24:25], v[4:5] op_sel_hi:[0,1]
	v_pk_mul_f32 v[6:7], v[24:25], v[6:7] op_sel_hi:[0,1]
	v_pk_mul_f32 v[8:9], v[16:17], v[8:9]
	v_pk_mul_f32 v[10:11], v[18:19], v[10:11]
	v_pk_mul_f32 v[12:13], v[12:13], v[4:5]
	v_pk_mul_f32 v[14:15], v[14:15], v[6:7]
	s_andn2_b64 vcc, exec, s[14:15]
	v_cvt_pk_bf16_f32 v4, v8, v9
	v_cvt_pk_bf16_f32 v5, v10, v11
	v_cvt_pk_bf16_f32 v6, v12, v13
	v_cvt_pk_bf16_f32 v7, v14, v15
	global_store_dwordx4 v[20:21], v[4:7], off
	s_cbranch_vccnz .LBB0_1049
	s_andn2_b64 vcc, exec, s[8:9]
	s_cbranch_vccnz .LBB0_1048
	s_barrier
	s_branch .LBB0_1048
